# 8-phase GEMM main loops: barrier hoisted above the last MFMA of each cluster, trailing MFMA at priority 2, and the scalar/address updates that sat before the barrier moved behind it (earlier barrier a
# speedup vs baseline: 1.0070x; 1.0070x over previous
.LBB0_114:
	ds_read_b128 v[152:155], v148
	ds_read_b128 v[156:159], v148 offset:1024
	ds_read_b128 v[160:163], v148 offset:2048
	ds_read_b128 v[164:167], v148 offset:3072
	s_add_u32 s38, s36, 0xfff80080
	s_addc_u32 s39, s37, -1
	s_cmp_eq_u32 s63, 28
	s_cselect_b32 s41, s4, s39
	s_cselect_b32 s40, s5, s38
	s_cselect_b32 s39, s23, s29
	s_cselect_b32 s38, s26, s27
	v_lshl_add_u64 v[188:189], s[36:37], 0, v[138:139]
	s_add_i32 m0, s19, 0xc000
	ds_read_b128 v[168:171], v149
	ds_read_b128 v[172:175], v149 offset:1024
	ds_read_b128 v[176:179], v149 offset:2048
	ds_read_b128 v[180:183], v149 offset:3072
	ds_read_b128 v[184:187], v149 offset:4096
	ds_read_b128 v[192:195], v149 offset:5120
	ds_read_b128 v[196:199], v149 offset:6144
	ds_read_b128 v[200:203], v149 offset:7168
	global_load_lds_dwordx4 v[188:189], off
	v_lshl_add_u64 v[188:189], s[36:37], 0, v[140:141]
	s_add_i32 m0, s19, 0xe000
	s_nop 0
	global_load_lds_dwordx4 v[188:189], off
	s_waitcnt lgkmcnt(8)
	s_barrier
	s_waitcnt lgkmcnt(0)
	s_setprio 1
	s_waitcnt lgkmcnt(0)
	v_mfma_f32_16x16x32_bf16 v[126:129], v[152:155], v[168:171], v[126:129]
	v_mfma_f32_16x16x32_bf16 v[122:125], v[160:163], v[168:171], v[122:125]
	v_mfma_f32_16x16x32_bf16 v[118:121], v[152:155], v[176:179], v[118:121]
	v_mfma_f32_16x16x32_bf16 v[114:117], v[160:163], v[176:179], v[114:117]
	v_mfma_f32_16x16x32_bf16 v[102:105], v[152:155], v[184:187], v[102:105]
	v_mfma_f32_16x16x32_bf16 v[98:101], v[160:163], v[184:187], v[98:101]
	v_mfma_f32_16x16x32_bf16 v[86:89], v[152:155], v[196:199], v[86:89]
	v_mfma_f32_16x16x32_bf16 v[82:85], v[160:163], v[196:199], v[82:85]
	v_mfma_f32_16x16x32_bf16 v[126:129], v[156:159], v[172:175], v[126:129]
	v_mfma_f32_16x16x32_bf16 v[122:125], v[164:167], v[172:175], v[122:125]
	v_mfma_f32_16x16x32_bf16 v[118:121], v[156:159], v[180:183], v[118:121]
	v_mfma_f32_16x16x32_bf16 v[114:117], v[164:167], v[180:183], v[114:117]
	v_mfma_f32_16x16x32_bf16 v[102:105], v[156:159], v[192:195], v[102:105]
	v_mfma_f32_16x16x32_bf16 v[98:101], v[164:167], v[192:195], v[98:101]
	v_mfma_f32_16x16x32_bf16 v[86:89], v[156:159], v[200:203], v[86:89]
	s_setprio 2
	s_barrier
	v_mfma_f32_16x16x32_bf16 v[82:85], v[164:167], v[200:203], v[82:85]
	s_setprio 0
	s_add_i32 s64, s57, s47
	v_lshl_add_u64 v[188:189], s[38:39], 0, v[132:133]
	s_mov_b32 m0, s64
	ds_read_b128 v[204:207], v150
	ds_read_b128 v[208:211], v150 offset:1024
	ds_read_b128 v[212:215], v150 offset:2048
	ds_read_b128 v[216:219], v150 offset:3072
	global_load_lds_dwordx4 v[188:189], off
	v_lshl_add_u64 v[220:221], s[38:39], 0, v[136:137]
	s_add_i32 m0, s64, 0x2000
	s_nop 0
	global_load_lds_dwordx4 v[220:221], off
	s_barrier
	s_waitcnt lgkmcnt(0)
	s_setprio 1
	s_waitcnt lgkmcnt(0)
	v_mfma_f32_16x16x32_bf16 v[110:113], v[204:207], v[168:171], v[110:113]
	v_mfma_f32_16x16x32_bf16 v[106:109], v[212:215], v[168:171], v[106:109]
	v_mfma_f32_16x16x32_bf16 v[94:97], v[204:207], v[176:179], v[94:97]
	v_mfma_f32_16x16x32_bf16 v[90:93], v[212:215], v[176:179], v[90:93]
	v_mfma_f32_16x16x32_bf16 v[78:81], v[204:207], v[184:187], v[78:81]
	v_mfma_f32_16x16x32_bf16 v[74:77], v[212:215], v[184:187], v[74:77]
	v_mfma_f32_16x16x32_bf16 v[70:73], v[204:207], v[196:199], v[70:73]
	v_mfma_f32_16x16x32_bf16 v[66:69], v[212:215], v[196:199], v[66:69]
	v_mfma_f32_16x16x32_bf16 v[110:113], v[208:211], v[172:175], v[110:113]
	v_mfma_f32_16x16x32_bf16 v[106:109], v[216:219], v[172:175], v[106:109]
	v_mfma_f32_16x16x32_bf16 v[94:97], v[208:211], v[180:183], v[94:97]
	v_mfma_f32_16x16x32_bf16 v[90:93], v[216:219], v[180:183], v[90:93]
	v_mfma_f32_16x16x32_bf16 v[78:81], v[208:211], v[192:195], v[78:81]
	v_mfma_f32_16x16x32_bf16 v[74:77], v[216:219], v[192:195], v[74:77]
	v_mfma_f32_16x16x32_bf16 v[70:73], v[208:211], v[200:203], v[70:73]
	s_setprio 2
	s_barrier
	v_mfma_f32_16x16x32_bf16 v[66:69], v[216:219], v[200:203], v[66:69]
	s_setprio 0
	s_mov_b32 m0, s19
	v_lshl_add_u64 v[222:223], s[40:41], 0, v[130:131]
	ds_read_b128 v[168:171], v149 offset:16384
	ds_read_b128 v[172:175], v149 offset:17408
	ds_read_b128 v[176:179], v149 offset:18432
	ds_read_b128 v[180:183], v149 offset:19456
	ds_read_b128 v[184:187], v149 offset:20480
	ds_read_b128 v[192:195], v149 offset:21504
	ds_read_b128 v[196:199], v149 offset:22528
	ds_read_b128 v[200:203], v149 offset:23552
	global_load_lds_dwordx4 v[222:223], off
	v_lshl_add_u64 v[224:225], s[40:41], 0, v[134:135]
	s_mov_b32 m0, s21
	s_nop 0
	global_load_lds_dwordx4 v[224:225], off
	s_barrier
	s_waitcnt lgkmcnt(0)
	s_setprio 1
	s_waitcnt lgkmcnt(0)
	v_mfma_f32_16x16x32_bf16 v[62:65], v[152:155], v[168:171], v[62:65]
	v_mfma_f32_16x16x32_bf16 v[58:61], v[160:163], v[168:171], v[58:61]
	v_mfma_f32_16x16x32_bf16 v[54:57], v[152:155], v[176:179], v[54:57]
	v_mfma_f32_16x16x32_bf16 v[50:53], v[160:163], v[176:179], v[50:53]
	v_mfma_f32_16x16x32_bf16 v[38:41], v[152:155], v[184:187], v[38:41]
	v_mfma_f32_16x16x32_bf16 v[34:37], v[160:163], v[184:187], v[34:37]
	v_mfma_f32_16x16x32_bf16 v[22:25], v[152:155], v[196:199], v[22:25]
	v_mfma_f32_16x16x32_bf16 v[18:21], v[160:163], v[196:199], v[18:21]
	v_mfma_f32_16x16x32_bf16 v[62:65], v[156:159], v[172:175], v[62:65]
	v_mfma_f32_16x16x32_bf16 v[58:61], v[164:167], v[172:175], v[58:61]
	v_mfma_f32_16x16x32_bf16 v[54:57], v[156:159], v[180:183], v[54:57]
	v_mfma_f32_16x16x32_bf16 v[50:53], v[164:167], v[180:183], v[50:53]
	v_mfma_f32_16x16x32_bf16 v[38:41], v[156:159], v[192:195], v[38:41]
	v_mfma_f32_16x16x32_bf16 v[34:37], v[164:167], v[192:195], v[34:37]
	v_mfma_f32_16x16x32_bf16 v[22:25], v[156:159], v[200:203], v[22:25]
	s_setprio 2
	s_barrier
	v_mfma_f32_16x16x32_bf16 v[18:21], v[164:167], v[200:203], v[18:21]
	s_setprio 0
	s_add_u32 s64, s38, 0x80000
	s_addc_u32 s65, s39, 0
	s_add_i32 s66, s58, s47
	v_lshl_add_u64 v[152:153], s[64:65], 0, v[132:133]
	s_mov_b32 m0, s66
	s_nop 0
	global_load_lds_dwordx4 v[152:153], off
	v_lshl_add_u64 v[152:153], s[64:65], 0, v[136:137]
	s_add_i32 m0, s66, 0x2000
	s_nop 0
	global_load_lds_dwordx4 v[152:153], off
	s_waitcnt vmcnt(6)
	s_barrier
	s_setprio 1
	v_mfma_f32_16x16x32_bf16 v[46:49], v[204:207], v[168:171], v[46:49]
	v_mfma_f32_16x16x32_bf16 v[42:45], v[212:215], v[168:171], v[42:45]
	v_mfma_f32_16x16x32_bf16 v[30:33], v[204:207], v[176:179], v[30:33]
	v_mfma_f32_16x16x32_bf16 v[26:29], v[212:215], v[176:179], v[26:29]
	v_mfma_f32_16x16x32_bf16 v[14:17], v[204:207], v[184:187], v[14:17]
	v_mfma_f32_16x16x32_bf16 v[10:13], v[212:215], v[184:187], v[10:13]
	v_mfma_f32_16x16x32_bf16 v[6:9], v[204:207], v[196:199], v[6:9]
	v_mfma_f32_16x16x32_bf16 v[2:5], v[212:215], v[196:199], v[2:5]
	v_mfma_f32_16x16x32_bf16 v[46:49], v[208:211], v[172:175], v[46:49]
	v_mfma_f32_16x16x32_bf16 v[42:45], v[216:219], v[172:175], v[42:45]
	v_mfma_f32_16x16x32_bf16 v[30:33], v[208:211], v[180:183], v[30:33]
	v_mfma_f32_16x16x32_bf16 v[26:29], v[216:219], v[180:183], v[26:29]
	v_mfma_f32_16x16x32_bf16 v[14:17], v[208:211], v[192:195], v[14:17]
	v_mfma_f32_16x16x32_bf16 v[10:13], v[216:219], v[192:195], v[10:13]
	v_mfma_f32_16x16x32_bf16 v[6:9], v[208:211], v[200:203], v[6:9]
	s_setprio 2
	s_barrier
	v_mfma_f32_16x16x32_bf16 v[2:5], v[216:219], v[200:203], v[2:5]
	s_setprio 0
	s_add_i32 s64, 0, 0x18000
	v_add_u32_e32 v151, s64, v146
	ds_read_b128 v[152:155], v151
	ds_read_b128 v[156:159], v151 offset:1024
	ds_read_b128 v[160:163], v151 offset:2048
	ds_read_b128 v[164:167], v151 offset:3072
	s_add_u32 s40, s40, 0x80000
	s_addc_u32 s41, s41, 0
	s_mov_b32 m0, s48
	v_lshl_add_u64 v[204:205], s[40:41], 0, v[130:131]
	ds_read_b128 v[168:171], v149 offset:32768
	ds_read_b128 v[172:175], v149 offset:33792
	ds_read_b128 v[176:179], v149 offset:34816
	ds_read_b128 v[180:183], v149 offset:35840
	ds_read_b128 v[184:187], v149 offset:36864
	ds_read_b128 v[192:195], v149 offset:37888
	ds_read_b128 v[196:199], v149 offset:38912
	ds_read_b128 v[200:203], v149 offset:39936
	global_load_lds_dwordx4 v[204:205], off
	v_lshl_add_u64 v[204:205], s[40:41], 0, v[134:135]
	s_mov_b32 m0, s49
	s_nop 0
	global_load_lds_dwordx4 v[204:205], off
	s_waitcnt lgkmcnt(8)
	s_barrier
	s_waitcnt lgkmcnt(0)
	s_setprio 1
	s_waitcnt lgkmcnt(0)
	v_mfma_f32_16x16x32_bf16 v[126:129], v[152:155], v[168:171], v[126:129]
	v_mfma_f32_16x16x32_bf16 v[122:125], v[160:163], v[168:171], v[122:125]
	v_mfma_f32_16x16x32_bf16 v[118:121], v[152:155], v[176:179], v[118:121]
	v_mfma_f32_16x16x32_bf16 v[114:117], v[160:163], v[176:179], v[114:117]
	v_mfma_f32_16x16x32_bf16 v[102:105], v[152:155], v[184:187], v[102:105]
	v_mfma_f32_16x16x32_bf16 v[98:101], v[160:163], v[184:187], v[98:101]
	v_mfma_f32_16x16x32_bf16 v[86:89], v[152:155], v[196:199], v[86:89]
	v_mfma_f32_16x16x32_bf16 v[82:85], v[160:163], v[196:199], v[82:85]
	v_mfma_f32_16x16x32_bf16 v[126:129], v[156:159], v[172:175], v[126:129]
	v_mfma_f32_16x16x32_bf16 v[122:125], v[164:167], v[172:175], v[122:125]
	v_mfma_f32_16x16x32_bf16 v[118:121], v[156:159], v[180:183], v[118:121]
	v_mfma_f32_16x16x32_bf16 v[114:117], v[164:167], v[180:183], v[114:117]
	v_mfma_f32_16x16x32_bf16 v[102:105], v[156:159], v[192:195], v[102:105]
	v_mfma_f32_16x16x32_bf16 v[98:101], v[164:167], v[192:195], v[98:101]
	v_mfma_f32_16x16x32_bf16 v[86:89], v[156:159], v[200:203], v[86:89]
	s_setprio 2
	s_barrier
	v_mfma_f32_16x16x32_bf16 v[82:85], v[164:167], v[200:203], v[82:85]
	s_setprio 0
	s_add_i32 s40, 0, 0x1c000
	s_add_i32 s41, s64, s47
	v_add_u32_e32 v151, s40, v146
	v_lshl_add_u64 v[188:189], v[188:189], 0, s[10:11]
	s_mov_b32 m0, s41
	ds_read_b128 v[204:207], v151
	ds_read_b128 v[208:211], v151 offset:1024
	ds_read_b128 v[212:215], v151 offset:2048
	ds_read_b128 v[216:219], v151 offset:3072
	global_load_lds_dwordx4 v[188:189], off
	v_lshl_add_u64 v[188:189], v[220:221], 0, s[10:11]
	s_add_i32 m0, s41, 0x2000
	s_nop 0
	global_load_lds_dwordx4 v[188:189], off
	s_barrier
	s_waitcnt lgkmcnt(0)
	s_setprio 1
	s_waitcnt lgkmcnt(0)
	v_mfma_f32_16x16x32_bf16 v[110:113], v[204:207], v[168:171], v[110:113]
	v_mfma_f32_16x16x32_bf16 v[106:109], v[212:215], v[168:171], v[106:109]
	v_mfma_f32_16x16x32_bf16 v[94:97], v[204:207], v[176:179], v[94:97]
	v_mfma_f32_16x16x32_bf16 v[90:93], v[212:215], v[176:179], v[90:93]
	v_mfma_f32_16x16x32_bf16 v[78:81], v[204:207], v[184:187], v[78:81]
	v_mfma_f32_16x16x32_bf16 v[74:77], v[212:215], v[184:187], v[74:77]
	v_mfma_f32_16x16x32_bf16 v[70:73], v[204:207], v[196:199], v[70:73]
	v_mfma_f32_16x16x32_bf16 v[66:69], v[212:215], v[196:199], v[66:69]
	v_mfma_f32_16x16x32_bf16 v[110:113], v[208:211], v[172:175], v[110:113]
	v_mfma_f32_16x16x32_bf16 v[106:109], v[216:219], v[172:175], v[106:109]
	v_mfma_f32_16x16x32_bf16 v[94:97], v[208:211], v[180:183], v[94:97]
	v_mfma_f32_16x16x32_bf16 v[90:93], v[216:219], v[180:183], v[90:93]
	v_mfma_f32_16x16x32_bf16 v[78:81], v[208:211], v[192:195], v[78:81]
	v_mfma_f32_16x16x32_bf16 v[74:77], v[216:219], v[192:195], v[74:77]
	v_mfma_f32_16x16x32_bf16 v[70:73], v[208:211], v[200:203], v[70:73]
	s_setprio 2
	s_barrier
	v_mfma_f32_16x16x32_bf16 v[66:69], v[216:219], v[200:203], v[66:69]
	s_setprio 0
	s_mov_b32 m0, s53
	v_lshl_add_u64 v[188:189], v[222:223], 0, s[10:11]
	ds_read_b128 v[168:171], v149 offset:49152
	ds_read_b128 v[172:175], v149 offset:50176
	ds_read_b128 v[176:179], v149 offset:51200
	ds_read_b128 v[180:183], v149 offset:52224
	ds_read_b128 v[184:187], v149 offset:53248
	ds_read_b128 v[192:195], v149 offset:54272
	ds_read_b128 v[196:199], v149 offset:55296
	ds_read_b128 v[200:203], v149 offset:56320
	global_load_lds_dwordx4 v[188:189], off
	v_lshl_add_u64 v[188:189], v[224:225], 0, s[10:11]
	s_mov_b32 m0, s54
	s_nop 0
	global_load_lds_dwordx4 v[188:189], off
	s_barrier
	s_waitcnt lgkmcnt(0)
	s_setprio 1
	s_waitcnt lgkmcnt(0)
	v_mfma_f32_16x16x32_bf16 v[62:65], v[152:155], v[168:171], v[62:65]
	v_mfma_f32_16x16x32_bf16 v[58:61], v[160:163], v[168:171], v[58:61]
	v_mfma_f32_16x16x32_bf16 v[54:57], v[152:155], v[176:179], v[54:57]
	v_mfma_f32_16x16x32_bf16 v[50:53], v[160:163], v[176:179], v[50:53]
	v_mfma_f32_16x16x32_bf16 v[38:41], v[152:155], v[184:187], v[38:41]
	v_mfma_f32_16x16x32_bf16 v[34:37], v[160:163], v[184:187], v[34:37]
	v_mfma_f32_16x16x32_bf16 v[22:25], v[152:155], v[196:199], v[22:25]
	v_mfma_f32_16x16x32_bf16 v[18:21], v[160:163], v[196:199], v[18:21]
	v_mfma_f32_16x16x32_bf16 v[62:65], v[156:159], v[172:175], v[62:65]
	v_mfma_f32_16x16x32_bf16 v[58:61], v[164:167], v[172:175], v[58:61]
	v_mfma_f32_16x16x32_bf16 v[54:57], v[156:159], v[180:183], v[54:57]
	v_mfma_f32_16x16x32_bf16 v[50:53], v[164:167], v[180:183], v[50:53]
	v_mfma_f32_16x16x32_bf16 v[38:41], v[156:159], v[192:195], v[38:41]
	v_mfma_f32_16x16x32_bf16 v[34:37], v[164:167], v[192:195], v[34:37]
	v_mfma_f32_16x16x32_bf16 v[22:25], v[156:159], v[200:203], v[22:25]
	s_setprio 2
	s_barrier
	v_mfma_f32_16x16x32_bf16 v[18:21], v[164:167], v[200:203], v[18:21]
	s_setprio 0
	s_add_u32 s38, s38, 0x80080
	s_addc_u32 s39, s39, 0
	s_add_i32 s40, s40, s47
	v_lshl_add_u64 v[152:153], s[38:39], 0, v[132:133]
	s_mov_b32 m0, s40
	s_nop 0
	global_load_lds_dwordx4 v[152:153], off
	v_lshl_add_u64 v[152:153], s[38:39], 0, v[136:137]
	s_add_i32 m0, s40, 0x2000
	s_nop 0
	global_load_lds_dwordx4 v[152:153], off
	s_waitcnt vmcnt(6)
	s_barrier
	s_setprio 1
	v_mfma_f32_16x16x32_bf16 v[46:49], v[204:207], v[168:171], v[46:49]
	v_mfma_f32_16x16x32_bf16 v[42:45], v[212:215], v[168:171], v[42:45]
	v_mfma_f32_16x16x32_bf16 v[30:33], v[204:207], v[176:179], v[30:33]
	v_mfma_f32_16x16x32_bf16 v[26:29], v[212:215], v[176:179], v[26:29]
	v_mfma_f32_16x16x32_bf16 v[14:17], v[204:207], v[184:187], v[14:17]
	v_mfma_f32_16x16x32_bf16 v[10:13], v[212:215], v[184:187], v[10:13]
	v_mfma_f32_16x16x32_bf16 v[6:9], v[204:207], v[196:199], v[6:9]
	v_mfma_f32_16x16x32_bf16 v[2:5], v[212:215], v[196:199], v[2:5]
	v_mfma_f32_16x16x32_bf16 v[46:49], v[208:211], v[172:175], v[46:49]
	v_mfma_f32_16x16x32_bf16 v[42:45], v[216:219], v[172:175], v[42:45]
	v_mfma_f32_16x16x32_bf16 v[30:33], v[208:211], v[180:183], v[30:33]
	v_mfma_f32_16x16x32_bf16 v[26:29], v[216:219], v[180:183], v[26:29]
	v_mfma_f32_16x16x32_bf16 v[14:17], v[208:211], v[192:195], v[14:17]
	v_mfma_f32_16x16x32_bf16 v[10:13], v[216:219], v[192:195], v[10:13]
	v_mfma_f32_16x16x32_bf16 v[6:9], v[208:211], v[200:203], v[6:9]
	s_setprio 2
	s_barrier
	v_mfma_f32_16x16x32_bf16 v[2:5], v[216:219], v[200:203], v[2:5]
	s_setprio 0
	s_add_i32 s63, s63, 2
	s_add_u32 s36, s36, 0x100
	s_addc_u32 s37, s37, 0
	s_add_u32 s27, s27, 0x100
	s_addc_u32 s29, s29, 0
	s_cmp_gt_u32 s63, 29
	s_cbranch_scc0 .LBB0_114
	s_ashr_i32 s4, s18, 31
	s_lshr_b32 s4, s4, 29
	s_add_i32 s4, s18, s4
	s_lshl_b32 s5, s20, 8
	s_ashr_i32 s4, s4, 3
	s_and_b32 s5, s5, 0x3f00
	v_add_u32_e32 v152, s5, v1
	s_lshl_b32 s5, s4, 11
	s_lshl_b32 s18, s18, 8
	s_sub_i32 s5, s18, s5
	v_or_b32_e32 v154, s5, v147
	s_ashr_i32 s5, s4, 31
	s_lshl_b64 s[4:5], s[4:5], 26
	s_add_u32 s4, s51, s4
	s_addc_u32 s5, s52, s5
	v_ashrrev_i32_e32 v155, 31, v154
	v_ashrrev_i32_e32 v153, 31, v152
	v_lshl_add_u64 v[154:155], v[154:155], 1, s[4:5]
	v_lshlrev_b64 v[156:157], 12, v[152:153]
	v_lshl_add_u64 v[156:157], v[154:155], 0, v[156:157]
	v_cvt_pk_bf16_f32 v62, v62, v63
	v_cvt_pk_bf16_f32 v63, v64, v65
	v_cvt_pk_bf16_f32 v64, v58, v59
	v_add_co_u32_e32 v58, vcc, s59, v156
	v_cvt_pk_bf16_f32 v70, v70, v71
	v_cvt_pk_bf16_f32 v71, v72, v73
	v_cvt_pk_bf16_f32 v72, v66, v67
	v_lshl_add_u64 v[66:67], v[156:157], 0, s[8:9]
	v_addc_co_u32_e32 v59, vcc, 0, v157, vcc
	v_cvt_pk_bf16_f32 v46, v46, v47
	v_cvt_pk_bf16_f32 v47, v48, v49
	v_cvt_pk_bf16_f32 v48, v42, v43
	v_cvt_pk_bf16_f32 v49, v44, v45
	global_store_dwordx4 v[66:67], v[46:49], off offset:256
	v_cvt_pk_bf16_f32 v110, v110, v111
	v_cvt_pk_bf16_f32 v111, v112, v113
	v_add_co_u32_e32 v48, vcc, s60, v156
	v_cvt_pk_bf16_f32 v112, v106, v107
	v_or_b32_e32 v106, 16, v152
	v_lshl_add_u64 v[46:47], v[156:157], 0, s[12:13]
	v_addc_co_u32_e32 v49, vcc, 0, v157, vcc
	v_cvt_pk_bf16_f32 v30, v30, v31
	v_cvt_pk_bf16_f32 v31, v32, v33
	v_cvt_pk_bf16_f32 v32, v26, v27
	v_cvt_pk_bf16_f32 v33, v28, v29
	v_ashrrev_i32_e32 v107, 31, v106
	v_cvt_pk_bf16_f32 v94, v94, v95
	v_cvt_pk_bf16_f32 v95, v96, v97
	v_cvt_pk_bf16_f32 v96, v90, v91
	v_or_b32_e32 v90, 32, v152
	global_store_dwordx4 v[46:47], v[30:33], off offset:256
	v_cvt_pk_bf16_f32 v113, v108, v109
	v_lshlrev_b64 v[106:107], 12, v[106:107]
	v_add_co_u32_e32 v32, vcc, s61, v156
	v_ashrrev_i32_e32 v91, 31, v90
	v_cvt_pk_bf16_f32 v78, v78, v79
	v_cvt_pk_bf16_f32 v79, v80, v81
	v_cvt_pk_bf16_f32 v80, v74, v75
	v_or_b32_e32 v74, 48, v152
	v_lshl_add_u64 v[30:31], v[156:157], 0, s[14:15]
	v_addc_co_u32_e32 v33, vcc, 0, v157, vcc
	v_cvt_pk_bf16_f32 v14, v14, v15
	v_cvt_pk_bf16_f32 v15, v16, v17
	v_cvt_pk_bf16_f32 v16, v10, v11
	v_cvt_pk_bf16_f32 v17, v12, v13
	global_store_dwordx4 v[156:157], v[110:113], off offset:256
	v_cvt_pk_bf16_f32 v97, v92, v93
	v_lshlrev_b64 v[90:91], 12, v[90:91]
	v_lshl_add_u64 v[110:111], v[154:155], 0, v[106:107]
	v_ashrrev_i32_e32 v75, 31, v74
	global_store_dwordx4 v[30:31], v[14:17], off offset:256
	global_store_dwordx4 v[110:111], v[94:97], off offset:256
	v_cvt_pk_bf16_f32 v81, v76, v77
	v_add_co_u32_e32 v16, vcc, s62, v156
	v_lshl_add_u64 v[94:95], v[154:155], 0, v[90:91]
	v_lshlrev_b64 v[74:75], 12, v[74:75]
	v_addc_co_u32_e32 v17, vcc, 0, v157, vcc
	v_cvt_pk_bf16_f32 v126, v126, v127
	v_cvt_pk_bf16_f32 v127, v128, v129
	v_cvt_pk_bf16_f32 v128, v122, v123
	v_cvt_pk_bf16_f32 v129, v124, v125
	v_cvt_pk_bf16_f32 v106, v118, v119
	v_cvt_pk_bf16_f32 v107, v120, v121
	v_cvt_pk_bf16_f32 v108, v114, v115
	v_cvt_pk_bf16_f32 v109, v116, v117
	v_cvt_pk_bf16_f32 v90, v102, v103
	v_cvt_pk_bf16_f32 v91, v104, v105
	v_cvt_pk_bf16_f32 v92, v98, v99
	v_cvt_pk_bf16_f32 v93, v100, v101
	global_store_dwordx4 v[94:95], v[78:81], off offset:256
	v_cvt_pk_bf16_f32 v76, v82, v83
	v_cvt_pk_bf16_f32 v77, v84, v85
	v_lshl_add_u64 v[78:79], v[154:155], 0, v[74:75]
	v_cvt_pk_bf16_f32 v74, v86, v87
	v_cvt_pk_bf16_f32 v75, v88, v89
	v_cvt_pk_bf16_f32 v73, v68, v69
	v_cvt_pk_bf16_f32 v65, v60, v61
	v_cvt_pk_bf16_f32 v42, v54, v55
	v_cvt_pk_bf16_f32 v43, v56, v57
	v_cvt_pk_bf16_f32 v44, v50, v51
	v_cvt_pk_bf16_f32 v45, v52, v53
	v_cvt_pk_bf16_f32 v26, v38, v39
	v_cvt_pk_bf16_f32 v27, v40, v41
	v_cvt_pk_bf16_f32 v28, v34, v35
	v_cvt_pk_bf16_f32 v29, v36, v37
	v_lshl_add_u64 v[14:15], v[156:157], 0, s[16:17]
	v_cvt_pk_bf16_f32 v10, v22, v23
	v_cvt_pk_bf16_f32 v11, v24, v25
	v_cvt_pk_bf16_f32 v12, v18, v19
	v_cvt_pk_bf16_f32 v13, v20, v21
	v_cvt_pk_bf16_f32 v6, v6, v7
	v_cvt_pk_bf16_f32 v7, v8, v9
	v_cvt_pk_bf16_f32 v8, v2, v3
	v_cvt_pk_bf16_f32 v9, v4, v5
	s_and_b64 vcc, exec, s[6:7]
	s_mov_b32 s18, s28
	s_mov_b32 s20, s22
	s_mov_b64 s[38:39], s[34:35]
	s_mov_b64 s[36:37], s[30:31]
	global_store_dwordx4 v[156:157], v[126:129], off
	global_store_dwordx4 v[110:111], v[106:109], off
	global_store_dwordx4 v[94:95], v[90:93], off
	global_store_dwordx4 v[78:79], v[74:77], off
	global_store_dwordx4 v[78:79], v[70:73], off offset:256
	global_store_dwordx4 v[58:59], v[62:65], off
	global_store_dwordx4 v[48:49], v[42:45], off
	global_store_dwordx4 v[32:33], v[26:29], off
	global_store_dwordx4 v[16:17], v[10:13], off
	global_store_dwordx4 v[14:15], v[6:9], off offset:256
	s_cbranch_vccz .LBB0_107
	s_waitcnt vmcnt(0)
	s_cmpk_gt_u32 s3, 0xff
	s_cbranch_scc1 .LBB0_118
	s_barrier

.LBB0_320:
	ds_read_b128 v[152:155], v149
	ds_read_b128 v[156:159], v149 offset:1024
	ds_read_b128 v[160:163], v149 offset:2048
	ds_read_b128 v[164:167], v149 offset:3072
	s_add_u32 s38, s36, 0xfff80080
	s_addc_u32 s39, s37, -1
	s_cmp_eq_u32 s27, 28
	s_cselect_b32 s41, s4, s39
	s_cselect_b32 s40, s5, s38
	s_cselect_b32 s39, s9, s26
	s_cselect_b32 s38, s21, s23
	v_lshl_add_u64 v[188:189], s[36:37], 0, v[140:141]
	s_add_i32 m0, s35, 0xc000
	ds_read_b128 v[168:171], v150
	ds_read_b128 v[172:175], v150 offset:1024
	ds_read_b128 v[176:179], v150 offset:2048
	ds_read_b128 v[180:183], v150 offset:3072
	ds_read_b128 v[184:187], v150 offset:4096
	ds_read_b128 v[192:195], v150 offset:5120
	ds_read_b128 v[196:199], v150 offset:6144
	ds_read_b128 v[200:203], v150 offset:7168
	global_load_lds_dwordx4 v[188:189], off
	v_lshl_add_u64 v[188:189], s[36:37], 0, v[142:143]
	s_add_i32 m0, s35, 0xe000
	s_nop 0
	global_load_lds_dwordx4 v[188:189], off
	s_waitcnt lgkmcnt(8)
	s_barrier
	s_waitcnt lgkmcnt(0)
	s_setprio 1
	s_waitcnt lgkmcnt(0)
	v_mfma_f32_16x16x32_bf16 v[126:129], v[152:155], v[168:171], v[126:129]
	v_mfma_f32_16x16x32_bf16 v[122:125], v[160:163], v[168:171], v[122:125]
	v_mfma_f32_16x16x32_bf16 v[110:113], v[152:155], v[176:179], v[110:113]
	v_mfma_f32_16x16x32_bf16 v[106:109], v[160:163], v[176:179], v[106:109]
	v_mfma_f32_16x16x32_bf16 v[94:97], v[152:155], v[184:187], v[94:97]
	v_mfma_f32_16x16x32_bf16 v[90:93], v[160:163], v[184:187], v[90:93]
	v_mfma_f32_16x16x32_bf16 v[78:81], v[152:155], v[196:199], v[78:81]
	v_mfma_f32_16x16x32_bf16 v[74:77], v[160:163], v[196:199], v[74:77]
	v_mfma_f32_16x16x32_bf16 v[126:129], v[156:159], v[172:175], v[126:129]
	v_mfma_f32_16x16x32_bf16 v[122:125], v[164:167], v[172:175], v[122:125]
	v_mfma_f32_16x16x32_bf16 v[110:113], v[156:159], v[180:183], v[110:113]
	v_mfma_f32_16x16x32_bf16 v[106:109], v[164:167], v[180:183], v[106:109]
	v_mfma_f32_16x16x32_bf16 v[94:97], v[156:159], v[192:195], v[94:97]
	v_mfma_f32_16x16x32_bf16 v[90:93], v[164:167], v[192:195], v[90:93]
	v_mfma_f32_16x16x32_bf16 v[78:81], v[156:159], v[200:203], v[78:81]
	s_setprio 2
	s_barrier
	v_mfma_f32_16x16x32_bf16 v[74:77], v[164:167], v[200:203], v[74:77]
	s_setprio 0
	s_add_i32 s58, s56, s46
	v_lshl_add_u64 v[188:189], s[38:39], 0, v[132:133]
	s_mov_b32 m0, s58
	ds_read_b128 v[204:207], v151
	ds_read_b128 v[208:211], v151 offset:1024
	ds_read_b128 v[212:215], v151 offset:2048
	ds_read_b128 v[216:219], v151 offset:3072
	global_load_lds_dwordx4 v[188:189], off
	v_lshl_add_u64 v[220:221], s[38:39], 0, v[136:137]
	s_add_i32 m0, s58, 0x2000
	s_nop 0
	global_load_lds_dwordx4 v[220:221], off
	s_barrier
	s_waitcnt lgkmcnt(0)
	s_setprio 1
	s_waitcnt lgkmcnt(0)
	v_mfma_f32_16x16x32_bf16 v[118:121], v[204:207], v[168:171], v[118:121]
	v_mfma_f32_16x16x32_bf16 v[114:117], v[212:215], v[168:171], v[114:117]
	v_mfma_f32_16x16x32_bf16 v[102:105], v[204:207], v[176:179], v[102:105]
	v_mfma_f32_16x16x32_bf16 v[98:101], v[212:215], v[176:179], v[98:101]
	v_mfma_f32_16x16x32_bf16 v[86:89], v[204:207], v[184:187], v[86:89]
	v_mfma_f32_16x16x32_bf16 v[82:85], v[212:215], v[184:187], v[82:85]
	v_mfma_f32_16x16x32_bf16 v[70:73], v[204:207], v[196:199], v[70:73]
	v_mfma_f32_16x16x32_bf16 v[66:69], v[212:215], v[196:199], v[66:69]
	v_mfma_f32_16x16x32_bf16 v[118:121], v[208:211], v[172:175], v[118:121]
	v_mfma_f32_16x16x32_bf16 v[114:117], v[216:219], v[172:175], v[114:117]
	v_mfma_f32_16x16x32_bf16 v[102:105], v[208:211], v[180:183], v[102:105]
	v_mfma_f32_16x16x32_bf16 v[98:101], v[216:219], v[180:183], v[98:101]
	v_mfma_f32_16x16x32_bf16 v[86:89], v[208:211], v[192:195], v[86:89]
	v_mfma_f32_16x16x32_bf16 v[82:85], v[216:219], v[192:195], v[82:85]
	v_mfma_f32_16x16x32_bf16 v[70:73], v[208:211], v[200:203], v[70:73]
	s_setprio 2
	s_barrier
	v_mfma_f32_16x16x32_bf16 v[66:69], v[216:219], v[200:203], v[66:69]
	s_setprio 0
	s_mov_b32 m0, s35
	v_lshl_add_u64 v[222:223], s[40:41], 0, v[130:131]
	ds_read_b128 v[168:171], v150 offset:16384
	ds_read_b128 v[172:175], v150 offset:17408
	ds_read_b128 v[176:179], v150 offset:18432
	ds_read_b128 v[180:183], v150 offset:19456
	ds_read_b128 v[184:187], v150 offset:20480
	ds_read_b128 v[192:195], v150 offset:21504
	ds_read_b128 v[196:199], v150 offset:22528
	ds_read_b128 v[200:203], v150 offset:23552
	global_load_lds_dwordx4 v[222:223], off
	v_lshl_add_u64 v[224:225], s[40:41], 0, v[134:135]
	s_mov_b32 m0, s47
	s_nop 0
	global_load_lds_dwordx4 v[224:225], off
	s_barrier
	s_waitcnt lgkmcnt(0)
	s_setprio 1
	s_waitcnt lgkmcnt(0)
	v_mfma_f32_16x16x32_bf16 v[62:65], v[152:155], v[168:171], v[62:65]
	v_mfma_f32_16x16x32_bf16 v[58:61], v[160:163], v[168:171], v[58:61]
	v_mfma_f32_16x16x32_bf16 v[46:49], v[152:155], v[176:179], v[46:49]
	v_mfma_f32_16x16x32_bf16 v[42:45], v[160:163], v[176:179], v[42:45]
	v_mfma_f32_16x16x32_bf16 v[30:33], v[152:155], v[184:187], v[30:33]
	v_mfma_f32_16x16x32_bf16 v[26:29], v[160:163], v[184:187], v[26:29]
	v_mfma_f32_16x16x32_bf16 v[14:17], v[152:155], v[196:199], v[14:17]
	v_mfma_f32_16x16x32_bf16 v[10:13], v[160:163], v[196:199], v[10:13]
	v_mfma_f32_16x16x32_bf16 v[62:65], v[156:159], v[172:175], v[62:65]
	v_mfma_f32_16x16x32_bf16 v[58:61], v[164:167], v[172:175], v[58:61]
	v_mfma_f32_16x16x32_bf16 v[46:49], v[156:159], v[180:183], v[46:49]
	v_mfma_f32_16x16x32_bf16 v[42:45], v[164:167], v[180:183], v[42:45]
	v_mfma_f32_16x16x32_bf16 v[30:33], v[156:159], v[192:195], v[30:33]
	v_mfma_f32_16x16x32_bf16 v[26:29], v[164:167], v[192:195], v[26:29]
	v_mfma_f32_16x16x32_bf16 v[14:17], v[156:159], v[200:203], v[14:17]
	s_setprio 2
	s_barrier
	v_mfma_f32_16x16x32_bf16 v[10:13], v[164:167], v[200:203], v[10:13]
	s_setprio 0
	s_add_u32 s58, s38, 0x80000
	s_addc_u32 s59, s39, 0
	s_add_i32 s60, s57, s46
	v_lshl_add_u64 v[152:153], s[58:59], 0, v[132:133]
	s_mov_b32 m0, s60
	s_nop 0
	global_load_lds_dwordx4 v[152:153], off
	v_lshl_add_u64 v[152:153], s[58:59], 0, v[136:137]
	s_add_i32 m0, s60, 0x2000
	s_nop 0
	global_load_lds_dwordx4 v[152:153], off
	s_waitcnt vmcnt(6)
	s_barrier
	s_setprio 1
	v_mfma_f32_16x16x32_bf16 v[54:57], v[204:207], v[168:171], v[54:57]
	v_mfma_f32_16x16x32_bf16 v[50:53], v[212:215], v[168:171], v[50:53]
	v_mfma_f32_16x16x32_bf16 v[38:41], v[204:207], v[176:179], v[38:41]
	v_mfma_f32_16x16x32_bf16 v[34:37], v[212:215], v[176:179], v[34:37]
	v_mfma_f32_16x16x32_bf16 v[22:25], v[204:207], v[184:187], v[22:25]
	v_mfma_f32_16x16x32_bf16 v[18:21], v[212:215], v[184:187], v[18:21]
	v_mfma_f32_16x16x32_bf16 v[6:9], v[204:207], v[196:199], v[6:9]
	v_mfma_f32_16x16x32_bf16 v[2:5], v[212:215], v[196:199], v[2:5]
	v_mfma_f32_16x16x32_bf16 v[54:57], v[208:211], v[172:175], v[54:57]
	v_mfma_f32_16x16x32_bf16 v[50:53], v[216:219], v[172:175], v[50:53]
	v_mfma_f32_16x16x32_bf16 v[38:41], v[208:211], v[180:183], v[38:41]
	v_mfma_f32_16x16x32_bf16 v[34:37], v[216:219], v[180:183], v[34:37]
	v_mfma_f32_16x16x32_bf16 v[22:25], v[208:211], v[192:195], v[22:25]
	v_mfma_f32_16x16x32_bf16 v[18:21], v[216:219], v[192:195], v[18:21]
	v_mfma_f32_16x16x32_bf16 v[6:9], v[208:211], v[200:203], v[6:9]
	s_setprio 2
	s_barrier
	v_mfma_f32_16x16x32_bf16 v[2:5], v[216:219], v[200:203], v[2:5]
	s_setprio 0
	s_add_i32 s58, 0, 0x18000
	v_add_u32_e32 v164, s58, v148
	ds_read_b128 v[152:155], v164
	ds_read_b128 v[156:159], v164 offset:1024
	ds_read_b128 v[160:163], v164 offset:2048
	ds_read_b128 v[164:167], v164 offset:3072
	s_add_u32 s40, s40, 0x80000
	s_addc_u32 s41, s41, 0
	s_mov_b32 m0, s48
	v_lshl_add_u64 v[204:205], s[40:41], 0, v[130:131]
	ds_read_b128 v[168:171], v150 offset:32768
	ds_read_b128 v[172:175], v150 offset:33792
	ds_read_b128 v[176:179], v150 offset:34816
	ds_read_b128 v[180:183], v150 offset:35840
	ds_read_b128 v[184:187], v150 offset:36864
	ds_read_b128 v[192:195], v150 offset:37888
	ds_read_b128 v[196:199], v150 offset:38912
	ds_read_b128 v[200:203], v150 offset:39936
	global_load_lds_dwordx4 v[204:205], off
	v_lshl_add_u64 v[204:205], s[40:41], 0, v[134:135]
	s_mov_b32 m0, s49
	s_nop 0
	global_load_lds_dwordx4 v[204:205], off
	s_waitcnt lgkmcnt(8)
	s_barrier
	s_waitcnt lgkmcnt(0)
	s_setprio 1
	s_waitcnt lgkmcnt(0)
	v_mfma_f32_16x16x32_bf16 v[126:129], v[152:155], v[168:171], v[126:129]
	v_mfma_f32_16x16x32_bf16 v[122:125], v[160:163], v[168:171], v[122:125]
	v_mfma_f32_16x16x32_bf16 v[110:113], v[152:155], v[176:179], v[110:113]
	v_mfma_f32_16x16x32_bf16 v[106:109], v[160:163], v[176:179], v[106:109]
	v_mfma_f32_16x16x32_bf16 v[94:97], v[152:155], v[184:187], v[94:97]
	v_mfma_f32_16x16x32_bf16 v[90:93], v[160:163], v[184:187], v[90:93]
	v_mfma_f32_16x16x32_bf16 v[78:81], v[152:155], v[196:199], v[78:81]
	v_mfma_f32_16x16x32_bf16 v[74:77], v[160:163], v[196:199], v[74:77]
	v_mfma_f32_16x16x32_bf16 v[126:129], v[156:159], v[172:175], v[126:129]
	v_mfma_f32_16x16x32_bf16 v[122:125], v[164:167], v[172:175], v[122:125]
	v_mfma_f32_16x16x32_bf16 v[110:113], v[156:159], v[180:183], v[110:113]
	v_mfma_f32_16x16x32_bf16 v[106:109], v[164:167], v[180:183], v[106:109]
	v_mfma_f32_16x16x32_bf16 v[94:97], v[156:159], v[192:195], v[94:97]
	v_mfma_f32_16x16x32_bf16 v[90:93], v[164:167], v[192:195], v[90:93]
	v_mfma_f32_16x16x32_bf16 v[78:81], v[156:159], v[200:203], v[78:81]
	s_setprio 2
	s_barrier
	v_mfma_f32_16x16x32_bf16 v[74:77], v[164:167], v[200:203], v[74:77]
	s_setprio 0
	s_add_i32 s40, 0, 0x1c000
	s_add_i32 s41, s58, s46
	v_add_u32_e32 v191, s40, v148
	v_lshl_add_u64 v[188:189], v[188:189], 0, s[10:11]
	s_mov_b32 m0, s41
	ds_read_b128 v[204:207], v191
	ds_read_b128 v[208:211], v191 offset:1024
	ds_read_b128 v[212:215], v191 offset:2048
	ds_read_b128 v[216:219], v191 offset:3072
	global_load_lds_dwordx4 v[188:189], off
	v_lshl_add_u64 v[188:189], v[220:221], 0, s[10:11]
	s_add_i32 m0, s41, 0x2000
	s_nop 0
	global_load_lds_dwordx4 v[188:189], off
	s_barrier
	s_waitcnt lgkmcnt(0)
	s_setprio 1
	s_waitcnt lgkmcnt(0)
	v_mfma_f32_16x16x32_bf16 v[118:121], v[204:207], v[168:171], v[118:121]
	v_mfma_f32_16x16x32_bf16 v[114:117], v[212:215], v[168:171], v[114:117]
	v_mfma_f32_16x16x32_bf16 v[102:105], v[204:207], v[176:179], v[102:105]
	v_mfma_f32_16x16x32_bf16 v[98:101], v[212:215], v[176:179], v[98:101]
	v_mfma_f32_16x16x32_bf16 v[86:89], v[204:207], v[184:187], v[86:89]
	v_mfma_f32_16x16x32_bf16 v[82:85], v[212:215], v[184:187], v[82:85]
	v_mfma_f32_16x16x32_bf16 v[70:73], v[204:207], v[196:199], v[70:73]
	v_mfma_f32_16x16x32_bf16 v[66:69], v[212:215], v[196:199], v[66:69]
	v_mfma_f32_16x16x32_bf16 v[118:121], v[208:211], v[172:175], v[118:121]
	v_mfma_f32_16x16x32_bf16 v[114:117], v[216:219], v[172:175], v[114:117]
	v_mfma_f32_16x16x32_bf16 v[102:105], v[208:211], v[180:183], v[102:105]
	v_mfma_f32_16x16x32_bf16 v[98:101], v[216:219], v[180:183], v[98:101]
	v_mfma_f32_16x16x32_bf16 v[86:89], v[208:211], v[192:195], v[86:89]
	v_mfma_f32_16x16x32_bf16 v[82:85], v[216:219], v[192:195], v[82:85]
	v_mfma_f32_16x16x32_bf16 v[70:73], v[208:211], v[200:203], v[70:73]
	s_setprio 2
	s_barrier
	v_mfma_f32_16x16x32_bf16 v[66:69], v[216:219], v[200:203], v[66:69]
	s_setprio 0
	s_mov_b32 m0, s52
	v_lshl_add_u64 v[188:189], v[222:223], 0, s[10:11]
	ds_read_b128 v[168:171], v150 offset:49152
	ds_read_b128 v[172:175], v150 offset:50176
	ds_read_b128 v[176:179], v150 offset:51200
	ds_read_b128 v[180:183], v150 offset:52224
	ds_read_b128 v[184:187], v150 offset:53248
	ds_read_b128 v[192:195], v150 offset:54272
	ds_read_b128 v[196:199], v150 offset:55296
	ds_read_b128 v[200:203], v150 offset:56320
	global_load_lds_dwordx4 v[188:189], off
	v_lshl_add_u64 v[188:189], v[224:225], 0, s[10:11]
	s_mov_b32 m0, s53
	s_nop 0
	global_load_lds_dwordx4 v[188:189], off
	s_barrier
	s_waitcnt lgkmcnt(0)
	s_setprio 1
	s_waitcnt lgkmcnt(0)
	v_mfma_f32_16x16x32_bf16 v[62:65], v[152:155], v[168:171], v[62:65]
	v_mfma_f32_16x16x32_bf16 v[58:61], v[160:163], v[168:171], v[58:61]
	v_mfma_f32_16x16x32_bf16 v[46:49], v[152:155], v[176:179], v[46:49]
	v_mfma_f32_16x16x32_bf16 v[42:45], v[160:163], v[176:179], v[42:45]
	v_mfma_f32_16x16x32_bf16 v[30:33], v[152:155], v[184:187], v[30:33]
	v_mfma_f32_16x16x32_bf16 v[26:29], v[160:163], v[184:187], v[26:29]
	v_mfma_f32_16x16x32_bf16 v[14:17], v[152:155], v[196:199], v[14:17]
	v_mfma_f32_16x16x32_bf16 v[10:13], v[160:163], v[196:199], v[10:13]
	v_mfma_f32_16x16x32_bf16 v[62:65], v[156:159], v[172:175], v[62:65]
	v_mfma_f32_16x16x32_bf16 v[58:61], v[164:167], v[172:175], v[58:61]
	v_mfma_f32_16x16x32_bf16 v[46:49], v[156:159], v[180:183], v[46:49]
	v_mfma_f32_16x16x32_bf16 v[42:45], v[164:167], v[180:183], v[42:45]
	v_mfma_f32_16x16x32_bf16 v[30:33], v[156:159], v[192:195], v[30:33]
	v_mfma_f32_16x16x32_bf16 v[26:29], v[164:167], v[192:195], v[26:29]
	v_mfma_f32_16x16x32_bf16 v[14:17], v[156:159], v[200:203], v[14:17]
	s_setprio 2
	s_barrier
	v_mfma_f32_16x16x32_bf16 v[10:13], v[164:167], v[200:203], v[10:13]
	s_setprio 0
	s_add_u32 s38, s38, 0x80080
	s_addc_u32 s39, s39, 0
	s_add_i32 s40, s40, s46
	v_lshl_add_u64 v[152:153], s[38:39], 0, v[132:133]
	s_mov_b32 m0, s40
	s_nop 0
	global_load_lds_dwordx4 v[152:153], off
	v_lshl_add_u64 v[152:153], s[38:39], 0, v[136:137]
	s_add_i32 m0, s40, 0x2000
	s_nop 0
	global_load_lds_dwordx4 v[152:153], off
	s_waitcnt vmcnt(6)
	s_barrier
	s_setprio 1
	v_mfma_f32_16x16x32_bf16 v[54:57], v[204:207], v[168:171], v[54:57]
	v_mfma_f32_16x16x32_bf16 v[50:53], v[212:215], v[168:171], v[50:53]
	v_mfma_f32_16x16x32_bf16 v[38:41], v[204:207], v[176:179], v[38:41]
	v_mfma_f32_16x16x32_bf16 v[34:37], v[212:215], v[176:179], v[34:37]
	v_mfma_f32_16x16x32_bf16 v[22:25], v[204:207], v[184:187], v[22:25]
	v_mfma_f32_16x16x32_bf16 v[18:21], v[212:215], v[184:187], v[18:21]
	v_mfma_f32_16x16x32_bf16 v[6:9], v[204:207], v[196:199], v[6:9]
	v_mfma_f32_16x16x32_bf16 v[2:5], v[212:215], v[196:199], v[2:5]
	v_mfma_f32_16x16x32_bf16 v[54:57], v[208:211], v[172:175], v[54:57]
	v_mfma_f32_16x16x32_bf16 v[50:53], v[216:219], v[172:175], v[50:53]
	v_mfma_f32_16x16x32_bf16 v[38:41], v[208:211], v[180:183], v[38:41]
	v_mfma_f32_16x16x32_bf16 v[34:37], v[216:219], v[180:183], v[34:37]
	v_mfma_f32_16x16x32_bf16 v[22:25], v[208:211], v[192:195], v[22:25]
	v_mfma_f32_16x16x32_bf16 v[18:21], v[216:219], v[192:195], v[18:21]
	v_mfma_f32_16x16x32_bf16 v[6:9], v[208:211], v[200:203], v[6:9]
	s_setprio 2
	s_barrier
	v_mfma_f32_16x16x32_bf16 v[2:5], v[216:219], v[200:203], v[2:5]
	s_setprio 0
	s_add_i32 s27, s27, 2
	s_add_u32 s36, s36, 0x100
	s_addc_u32 s37, s37, 0
	s_add_u32 s23, s23, 0x100
	s_addc_u32 s26, s26, 0
	s_cmp_gt_u32 s27, 29
	s_cbranch_scc0 .LBB0_320
	s_cmp_lt_i32 s8, 2
	s_mov_b64 s[4:5], -1
	s_cbranch_scc1 .LBB0_325
	s_cmp_eq_u32 s8, 2
	v_mov_b32_e32 v158, v125
	v_mov_b32_e32 v157, v124
	v_mov_b32_e32 v155, v123
	v_mov_b32_e32 v153, v122
	v_mov_b32_e32 v159, v129
	v_mov_b32_e32 v156, v128
	v_mov_b32_e32 v154, v127
	v_mov_b32_e32 v152, v126
	s_cbranch_scc0 .LBB0_324
	v_mul_f32_e32 v158, 0xbfb8aa3b, v129
	v_mul_f32_e32 v152, 0xbfb8aa3b, v126
	v_mul_f32_e32 v153, 0xbfb8aa3b, v122
	v_mul_f32_e32 v154, 0xbfb8aa3b, v127
	v_mul_f32_e32 v155, 0xbfb8aa3b, v123
	v_mul_f32_e32 v156, 0xbfb8aa3b, v128
	v_mul_f32_e32 v157, 0xbfb8aa3b, v124
	v_exp_f32_e32 v158, v158
	v_mul_f32_e32 v159, 0xbfb8aa3b, v125
	v_exp_f32_e32 v152, v152
	v_exp_f32_e32 v153, v153
	v_exp_f32_e32 v154, v154
	v_exp_f32_e32 v155, v155
	v_exp_f32_e32 v156, v156
	v_exp_f32_e32 v157, v157
	v_exp_f32_e32 v160, v159
	v_add_f32_e32 v158, 1.0, v158
	v_add_f32_e32 v152, 1.0, v152
	v_add_f32_e32 v153, 1.0, v153
	v_add_f32_e32 v154, 1.0, v154
	v_add_f32_e32 v155, 1.0, v155
	v_add_f32_e32 v156, 1.0, v156
	v_add_f32_e32 v157, 1.0, v157
	v_rcp_f32_e32 v159, v158
	v_add_f32_e32 v158, 1.0, v160
	v_rcp_f32_e32 v152, v152
	v_rcp_f32_e32 v153, v153
	v_rcp_f32_e32 v154, v154
	v_rcp_f32_e32 v155, v155
	v_rcp_f32_e32 v156, v156
	v_rcp_f32_e32 v157, v157
	v_rcp_f32_e32 v158, v158

.LBB0_850:
	ds_read_b128 v[154:157], v150
	ds_read_b128 v[158:161], v150 offset:1024
	ds_read_b128 v[162:165], v150 offset:2048
	ds_read_b128 v[166:169], v150 offset:3072
	s_add_u32 s44, s42, 0xfff80080
	s_addc_u32 s45, s43, -1
	s_cmp_eq_u32 s62, 28
	s_cselect_b32 s47, s4, s45
	s_cselect_b32 s46, s5, s44
	s_cselect_b32 s45, s26, s31
	s_cselect_b32 s44, s27, s29
	v_lshl_add_u64 v[146:147], s[42:43], 0, v[138:139]
	s_add_i32 m0, s39, 0xc000
	ds_read_b128 v[170:173], v151
	ds_read_b128 v[174:177], v151 offset:1024
	ds_read_b128 v[178:181], v151 offset:2048
	ds_read_b128 v[182:185], v151 offset:3072
	ds_read_b128 v[186:189], v151 offset:4096
	ds_read_b128 v[192:195], v151 offset:5120
	ds_read_b128 v[196:199], v151 offset:6144
	ds_read_b128 v[200:203], v151 offset:7168
	global_load_lds_dwordx4 v[146:147], off
	v_lshl_add_u64 v[146:147], s[42:43], 0, v[140:141]
	s_add_i32 m0, s39, 0xe000
	s_nop 0
	global_load_lds_dwordx4 v[146:147], off
	s_waitcnt lgkmcnt(8)
	s_barrier
	s_waitcnt lgkmcnt(0)
	s_setprio 1
	s_waitcnt lgkmcnt(0)
	v_mfma_f32_16x16x32_bf16 v[126:129], v[154:157], v[170:173], v[126:129]
	v_mfma_f32_16x16x32_bf16 v[122:125], v[162:165], v[170:173], v[122:125]
	v_mfma_f32_16x16x32_bf16 v[110:113], v[154:157], v[178:181], v[110:113]
	v_mfma_f32_16x16x32_bf16 v[106:109], v[162:165], v[178:181], v[106:109]
	v_mfma_f32_16x16x32_bf16 v[94:97], v[154:157], v[186:189], v[94:97]
	v_mfma_f32_16x16x32_bf16 v[90:93], v[162:165], v[186:189], v[90:93]
	v_mfma_f32_16x16x32_bf16 v[78:81], v[154:157], v[196:199], v[78:81]
	v_mfma_f32_16x16x32_bf16 v[74:77], v[162:165], v[196:199], v[74:77]
	v_mfma_f32_16x16x32_bf16 v[126:129], v[158:161], v[174:177], v[126:129]
	v_mfma_f32_16x16x32_bf16 v[122:125], v[166:169], v[174:177], v[122:125]
	v_mfma_f32_16x16x32_bf16 v[110:113], v[158:161], v[182:185], v[110:113]
	v_mfma_f32_16x16x32_bf16 v[106:109], v[166:169], v[182:185], v[106:109]
	v_mfma_f32_16x16x32_bf16 v[94:97], v[158:161], v[192:195], v[94:97]
	v_mfma_f32_16x16x32_bf16 v[90:93], v[166:169], v[192:195], v[90:93]
	v_mfma_f32_16x16x32_bf16 v[78:81], v[158:161], v[200:203], v[78:81]
	s_setprio 2
	s_barrier
	v_mfma_f32_16x16x32_bf16 v[74:77], v[166:169], v[200:203], v[74:77]
	s_setprio 0
	s_add_i32 s63, s60, s52
	v_lshl_add_u64 v[146:147], s[44:45], 0, v[132:133]
	s_mov_b32 m0, s63
	ds_read_b128 v[204:207], v152
	ds_read_b128 v[208:211], v152 offset:1024
	ds_read_b128 v[212:215], v152 offset:2048
	ds_read_b128 v[216:219], v152 offset:3072
	global_load_lds_dwordx4 v[146:147], off
	v_lshl_add_u64 v[220:221], s[44:45], 0, v[136:137]
	s_add_i32 m0, s63, 0x2000
	s_nop 0
	global_load_lds_dwordx4 v[220:221], off
	s_barrier
	s_waitcnt lgkmcnt(0)
	s_setprio 1
	s_waitcnt lgkmcnt(0)
	v_mfma_f32_16x16x32_bf16 v[118:121], v[204:207], v[170:173], v[118:121]
	v_mfma_f32_16x16x32_bf16 v[114:117], v[212:215], v[170:173], v[114:117]
	v_mfma_f32_16x16x32_bf16 v[102:105], v[204:207], v[178:181], v[102:105]
	v_mfma_f32_16x16x32_bf16 v[98:101], v[212:215], v[178:181], v[98:101]
	v_mfma_f32_16x16x32_bf16 v[86:89], v[204:207], v[186:189], v[86:89]
	v_mfma_f32_16x16x32_bf16 v[82:85], v[212:215], v[186:189], v[82:85]
	v_mfma_f32_16x16x32_bf16 v[70:73], v[204:207], v[196:199], v[70:73]
	v_mfma_f32_16x16x32_bf16 v[66:69], v[212:215], v[196:199], v[66:69]
	v_mfma_f32_16x16x32_bf16 v[118:121], v[208:211], v[174:177], v[118:121]
	v_mfma_f32_16x16x32_bf16 v[114:117], v[216:219], v[174:177], v[114:117]
	v_mfma_f32_16x16x32_bf16 v[102:105], v[208:211], v[182:185], v[102:105]
	v_mfma_f32_16x16x32_bf16 v[98:101], v[216:219], v[182:185], v[98:101]
	v_mfma_f32_16x16x32_bf16 v[86:89], v[208:211], v[192:195], v[86:89]
	v_mfma_f32_16x16x32_bf16 v[82:85], v[216:219], v[192:195], v[82:85]
	v_mfma_f32_16x16x32_bf16 v[70:73], v[208:211], v[200:203], v[70:73]
	s_setprio 2
	s_barrier
	v_mfma_f32_16x16x32_bf16 v[66:69], v[216:219], v[200:203], v[66:69]
	s_setprio 0
	s_mov_b32 m0, s39
	v_lshl_add_u64 v[222:223], s[46:47], 0, v[130:131]
	ds_read_b128 v[170:173], v151 offset:16384
	ds_read_b128 v[174:177], v151 offset:17408
	ds_read_b128 v[178:181], v151 offset:18432
	ds_read_b128 v[182:185], v151 offset:19456
	ds_read_b128 v[186:189], v151 offset:20480
	ds_read_b128 v[192:195], v151 offset:21504
	ds_read_b128 v[196:199], v151 offset:22528
	ds_read_b128 v[200:203], v151 offset:23552
	global_load_lds_dwordx4 v[222:223], off
	v_lshl_add_u64 v[224:225], s[46:47], 0, v[134:135]
	s_mov_b32 m0, s41
	s_nop 0
	global_load_lds_dwordx4 v[224:225], off
	s_barrier
	s_waitcnt lgkmcnt(0)
	s_setprio 1
	s_waitcnt lgkmcnt(0)
	v_mfma_f32_16x16x32_bf16 v[62:65], v[154:157], v[170:173], v[62:65]
	v_mfma_f32_16x16x32_bf16 v[58:61], v[162:165], v[170:173], v[58:61]
	v_mfma_f32_16x16x32_bf16 v[46:49], v[154:157], v[178:181], v[46:49]
	v_mfma_f32_16x16x32_bf16 v[42:45], v[162:165], v[178:181], v[42:45]
	v_mfma_f32_16x16x32_bf16 v[30:33], v[154:157], v[186:189], v[30:33]
	v_mfma_f32_16x16x32_bf16 v[26:29], v[162:165], v[186:189], v[26:29]
	v_mfma_f32_16x16x32_bf16 v[14:17], v[154:157], v[196:199], v[14:17]
	v_mfma_f32_16x16x32_bf16 v[10:13], v[162:165], v[196:199], v[10:13]
	v_mfma_f32_16x16x32_bf16 v[62:65], v[158:161], v[174:177], v[62:65]
	v_mfma_f32_16x16x32_bf16 v[58:61], v[166:169], v[174:177], v[58:61]
	v_mfma_f32_16x16x32_bf16 v[46:49], v[158:161], v[182:185], v[46:49]
	v_mfma_f32_16x16x32_bf16 v[42:45], v[166:169], v[182:185], v[42:45]
	v_mfma_f32_16x16x32_bf16 v[30:33], v[158:161], v[192:195], v[30:33]
	v_mfma_f32_16x16x32_bf16 v[26:29], v[166:169], v[192:195], v[26:29]
	v_mfma_f32_16x16x32_bf16 v[14:17], v[158:161], v[200:203], v[14:17]
	s_setprio 2
	s_barrier
	v_mfma_f32_16x16x32_bf16 v[10:13], v[166:169], v[200:203], v[10:13]
	s_setprio 0
	s_add_u32 s64, s44, 0x80000
	s_addc_u32 s65, s45, 0
	s_add_i32 s63, s61, s52
	v_lshl_add_u64 v[154:155], s[64:65], 0, v[132:133]
	s_mov_b32 m0, s63
	s_nop 0
	global_load_lds_dwordx4 v[154:155], off
	v_lshl_add_u64 v[154:155], s[64:65], 0, v[136:137]
	s_add_i32 m0, s63, 0x2000
	s_nop 0
	global_load_lds_dwordx4 v[154:155], off
	s_waitcnt vmcnt(6)
	s_barrier
	s_setprio 1
	v_mfma_f32_16x16x32_bf16 v[54:57], v[204:207], v[170:173], v[54:57]
	v_mfma_f32_16x16x32_bf16 v[50:53], v[212:215], v[170:173], v[50:53]
	v_mfma_f32_16x16x32_bf16 v[38:41], v[204:207], v[178:181], v[38:41]
	v_mfma_f32_16x16x32_bf16 v[34:37], v[212:215], v[178:181], v[34:37]
	v_mfma_f32_16x16x32_bf16 v[22:25], v[204:207], v[186:189], v[22:25]
	v_mfma_f32_16x16x32_bf16 v[18:21], v[212:215], v[186:189], v[18:21]
	v_mfma_f32_16x16x32_bf16 v[6:9], v[204:207], v[196:199], v[6:9]
	v_mfma_f32_16x16x32_bf16 v[2:5], v[212:215], v[196:199], v[2:5]
	v_mfma_f32_16x16x32_bf16 v[54:57], v[208:211], v[174:177], v[54:57]
	v_mfma_f32_16x16x32_bf16 v[50:53], v[216:219], v[174:177], v[50:53]
	v_mfma_f32_16x16x32_bf16 v[38:41], v[208:211], v[182:185], v[38:41]
	v_mfma_f32_16x16x32_bf16 v[34:37], v[216:219], v[182:185], v[34:37]
	v_mfma_f32_16x16x32_bf16 v[22:25], v[208:211], v[192:195], v[22:25]
	v_mfma_f32_16x16x32_bf16 v[18:21], v[216:219], v[192:195], v[18:21]
	v_mfma_f32_16x16x32_bf16 v[6:9], v[208:211], v[200:203], v[6:9]
	s_setprio 2
	s_barrier
	v_mfma_f32_16x16x32_bf16 v[2:5], v[216:219], v[200:203], v[2:5]
	s_setprio 0
	s_add_i32 s63, 0, 0x18000
	v_add_u32_e32 v153, s63, v148
	ds_read_b128 v[154:157], v153
	ds_read_b128 v[158:161], v153 offset:1024
	ds_read_b128 v[162:165], v153 offset:2048
	ds_read_b128 v[166:169], v153 offset:3072
	s_add_u32 s46, s46, 0x80000
	s_addc_u32 s47, s47, 0
	s_mov_b32 m0, s53
	v_lshl_add_u64 v[204:205], s[46:47], 0, v[130:131]
	ds_read_b128 v[170:173], v151 offset:32768
	ds_read_b128 v[174:177], v151 offset:33792
	ds_read_b128 v[178:181], v151 offset:34816
	ds_read_b128 v[182:185], v151 offset:35840
	ds_read_b128 v[186:189], v151 offset:36864
	ds_read_b128 v[192:195], v151 offset:37888
	ds_read_b128 v[196:199], v151 offset:38912
	ds_read_b128 v[200:203], v151 offset:39936
	global_load_lds_dwordx4 v[204:205], off
	v_lshl_add_u64 v[204:205], s[46:47], 0, v[134:135]
	s_mov_b32 m0, s54
	s_nop 0
	global_load_lds_dwordx4 v[204:205], off
	s_waitcnt lgkmcnt(8)
	s_barrier
	s_waitcnt lgkmcnt(0)
	s_setprio 1
	s_waitcnt lgkmcnt(0)
	v_mfma_f32_16x16x32_bf16 v[126:129], v[154:157], v[170:173], v[126:129]
	v_mfma_f32_16x16x32_bf16 v[122:125], v[162:165], v[170:173], v[122:125]
	v_mfma_f32_16x16x32_bf16 v[110:113], v[154:157], v[178:181], v[110:113]
	v_mfma_f32_16x16x32_bf16 v[106:109], v[162:165], v[178:181], v[106:109]
	v_mfma_f32_16x16x32_bf16 v[94:97], v[154:157], v[186:189], v[94:97]
	v_mfma_f32_16x16x32_bf16 v[90:93], v[162:165], v[186:189], v[90:93]
	v_mfma_f32_16x16x32_bf16 v[78:81], v[154:157], v[196:199], v[78:81]
	v_mfma_f32_16x16x32_bf16 v[74:77], v[162:165], v[196:199], v[74:77]
	v_mfma_f32_16x16x32_bf16 v[126:129], v[158:161], v[174:177], v[126:129]
	v_mfma_f32_16x16x32_bf16 v[122:125], v[166:169], v[174:177], v[122:125]
	v_mfma_f32_16x16x32_bf16 v[110:113], v[158:161], v[182:185], v[110:113]
	v_mfma_f32_16x16x32_bf16 v[106:109], v[166:169], v[182:185], v[106:109]
	v_mfma_f32_16x16x32_bf16 v[94:97], v[158:161], v[192:195], v[94:97]
	v_mfma_f32_16x16x32_bf16 v[90:93], v[166:169], v[192:195], v[90:93]
	v_mfma_f32_16x16x32_bf16 v[78:81], v[158:161], v[200:203], v[78:81]
	s_setprio 2
	s_barrier
	v_mfma_f32_16x16x32_bf16 v[74:77], v[166:169], v[200:203], v[74:77]
	s_setprio 0
	s_add_i32 s46, 0, 0x1c000
	s_add_i32 s47, s63, s52
	v_add_u32_e32 v153, s46, v148
	v_lshl_add_u64 v[146:147], v[146:147], 0, s[12:13]
	s_mov_b32 m0, s47
	ds_read_b128 v[204:207], v153
	ds_read_b128 v[208:211], v153 offset:1024
	ds_read_b128 v[212:215], v153 offset:2048
	ds_read_b128 v[216:219], v153 offset:3072
	global_load_lds_dwordx4 v[146:147], off
	v_lshl_add_u64 v[146:147], v[220:221], 0, s[12:13]
	s_add_i32 m0, s47, 0x2000
	s_nop 0
	global_load_lds_dwordx4 v[146:147], off
	s_barrier
	s_waitcnt lgkmcnt(0)
	s_setprio 1
	s_waitcnt lgkmcnt(0)
	v_mfma_f32_16x16x32_bf16 v[118:121], v[204:207], v[170:173], v[118:121]
	v_mfma_f32_16x16x32_bf16 v[114:117], v[212:215], v[170:173], v[114:117]
	v_mfma_f32_16x16x32_bf16 v[102:105], v[204:207], v[178:181], v[102:105]
	v_mfma_f32_16x16x32_bf16 v[98:101], v[212:215], v[178:181], v[98:101]
	v_mfma_f32_16x16x32_bf16 v[86:89], v[204:207], v[186:189], v[86:89]
	v_mfma_f32_16x16x32_bf16 v[82:85], v[212:215], v[186:189], v[82:85]
	v_mfma_f32_16x16x32_bf16 v[70:73], v[204:207], v[196:199], v[70:73]
	v_mfma_f32_16x16x32_bf16 v[66:69], v[212:215], v[196:199], v[66:69]
	v_mfma_f32_16x16x32_bf16 v[118:121], v[208:211], v[174:177], v[118:121]
	v_mfma_f32_16x16x32_bf16 v[114:117], v[216:219], v[174:177], v[114:117]
	v_mfma_f32_16x16x32_bf16 v[102:105], v[208:211], v[182:185], v[102:105]
	v_mfma_f32_16x16x32_bf16 v[98:101], v[216:219], v[182:185], v[98:101]
	v_mfma_f32_16x16x32_bf16 v[86:89], v[208:211], v[192:195], v[86:89]
	v_mfma_f32_16x16x32_bf16 v[82:85], v[216:219], v[192:195], v[82:85]
	v_mfma_f32_16x16x32_bf16 v[70:73], v[208:211], v[200:203], v[70:73]
	s_setprio 2
	s_barrier
	v_mfma_f32_16x16x32_bf16 v[66:69], v[216:219], v[200:203], v[66:69]
	s_setprio 0
	s_mov_b32 m0, s56
	v_lshl_add_u64 v[146:147], v[222:223], 0, s[12:13]
	ds_read_b128 v[170:173], v151 offset:49152
	ds_read_b128 v[174:177], v151 offset:50176
	ds_read_b128 v[178:181], v151 offset:51200
	ds_read_b128 v[182:185], v151 offset:52224
	ds_read_b128 v[186:189], v151 offset:53248
	ds_read_b128 v[192:195], v151 offset:54272
	ds_read_b128 v[196:199], v151 offset:55296
	ds_read_b128 v[200:203], v151 offset:56320
	global_load_lds_dwordx4 v[146:147], off
	v_lshl_add_u64 v[146:147], v[224:225], 0, s[12:13]
	s_mov_b32 m0, s57
	s_nop 0
	global_load_lds_dwordx4 v[146:147], off
	s_barrier
	s_waitcnt lgkmcnt(0)
	s_setprio 1
	s_waitcnt lgkmcnt(0)
	v_mfma_f32_16x16x32_bf16 v[62:65], v[154:157], v[170:173], v[62:65]
	v_mfma_f32_16x16x32_bf16 v[58:61], v[162:165], v[170:173], v[58:61]
	v_mfma_f32_16x16x32_bf16 v[46:49], v[154:157], v[178:181], v[46:49]
	v_mfma_f32_16x16x32_bf16 v[42:45], v[162:165], v[178:181], v[42:45]
	v_mfma_f32_16x16x32_bf16 v[30:33], v[154:157], v[186:189], v[30:33]
	v_mfma_f32_16x16x32_bf16 v[26:29], v[162:165], v[186:189], v[26:29]
	v_mfma_f32_16x16x32_bf16 v[14:17], v[154:157], v[196:199], v[14:17]
	v_mfma_f32_16x16x32_bf16 v[10:13], v[162:165], v[196:199], v[10:13]
	v_mfma_f32_16x16x32_bf16 v[62:65], v[158:161], v[174:177], v[62:65]
	v_mfma_f32_16x16x32_bf16 v[58:61], v[166:169], v[174:177], v[58:61]
	v_mfma_f32_16x16x32_bf16 v[46:49], v[158:161], v[182:185], v[46:49]
	v_mfma_f32_16x16x32_bf16 v[42:45], v[166:169], v[182:185], v[42:45]
	v_mfma_f32_16x16x32_bf16 v[30:33], v[158:161], v[192:195], v[30:33]
	v_mfma_f32_16x16x32_bf16 v[26:29], v[166:169], v[192:195], v[26:29]
	v_mfma_f32_16x16x32_bf16 v[14:17], v[158:161], v[200:203], v[14:17]
	s_setprio 2
	s_barrier
	v_mfma_f32_16x16x32_bf16 v[10:13], v[166:169], v[200:203], v[10:13]
	s_setprio 0
	s_add_u32 s44, s44, 0x80080
	s_addc_u32 s45, s45, 0
	s_add_i32 s46, s46, s52
	v_lshl_add_u64 v[146:147], s[44:45], 0, v[132:133]
	s_mov_b32 m0, s46
	s_nop 0
	global_load_lds_dwordx4 v[146:147], off
	v_lshl_add_u64 v[146:147], s[44:45], 0, v[136:137]
	s_add_i32 m0, s46, 0x2000
	s_nop 0
	global_load_lds_dwordx4 v[146:147], off
	s_waitcnt vmcnt(6)
	s_barrier
	s_setprio 1
	v_mfma_f32_16x16x32_bf16 v[54:57], v[204:207], v[170:173], v[54:57]
	v_mfma_f32_16x16x32_bf16 v[50:53], v[212:215], v[170:173], v[50:53]
	v_mfma_f32_16x16x32_bf16 v[38:41], v[204:207], v[178:181], v[38:41]
	v_mfma_f32_16x16x32_bf16 v[34:37], v[212:215], v[178:181], v[34:37]
	v_mfma_f32_16x16x32_bf16 v[22:25], v[204:207], v[186:189], v[22:25]
	v_mfma_f32_16x16x32_bf16 v[18:21], v[212:215], v[186:189], v[18:21]
	v_mfma_f32_16x16x32_bf16 v[6:9], v[204:207], v[196:199], v[6:9]
	v_mfma_f32_16x16x32_bf16 v[2:5], v[212:215], v[196:199], v[2:5]
	v_mfma_f32_16x16x32_bf16 v[54:57], v[208:211], v[174:177], v[54:57]
	v_mfma_f32_16x16x32_bf16 v[50:53], v[216:219], v[174:177], v[50:53]
	v_mfma_f32_16x16x32_bf16 v[38:41], v[208:211], v[182:185], v[38:41]
	v_mfma_f32_16x16x32_bf16 v[34:37], v[216:219], v[182:185], v[34:37]
	v_mfma_f32_16x16x32_bf16 v[22:25], v[208:211], v[192:195], v[22:25]
	v_mfma_f32_16x16x32_bf16 v[18:21], v[216:219], v[192:195], v[18:21]
	v_mfma_f32_16x16x32_bf16 v[6:9], v[208:211], v[200:203], v[6:9]
	s_setprio 2
	s_barrier
	v_mfma_f32_16x16x32_bf16 v[2:5], v[216:219], v[200:203], v[2:5]
	s_setprio 0
	s_add_i32 s62, s62, 2
	s_add_u32 s42, s42, 0x100
	s_addc_u32 s43, s43, 0
	s_add_u32 s29, s29, 0x100
	s_addc_u32 s31, s31, 0
	s_cmp_gt_u32 s62, 29
	s_cbranch_scc0 .LBB0_850
	s_lshl_b32 s4, s40, 8
	s_and_b32 s4, s4, 0x3f00
	v_add_u32_e32 v162, s4, v1
	s_ashr_i32 s4, s38, 31
	s_lshr_b32 s4, s4, 29
	s_add_i32 s4, s38, s4
	s_and_b32 s4, s4, 0xfffff8
	s_sub_i32 s4, s38, s4
	v_lshl_or_b32 v164, s4, 8, v149
	v_ashrrev_i32_e32 v163, 31, v162
	v_ashrrev_i32_e32 v165, 31, v164
	v_lshlrev_b32_e32 v146, 13, v162
	v_lshl_add_u32 v146, v164, 2, v146
	v_lshlrev_b32_e32 v147, 12, v162
	v_lshl_add_u32 v147, v164, 1, v147
	s_add_u32 s64, s8, 0x0
	s_addc_u32 s65, s9, 0
	global_load_dwordx4 v[176:179], v146, s[64:65]
	global_load_dwordx4 v[180:183], v146, s[64:65] offset:16
	s_add_u32 s64, s8, 0x200
	s_addc_u32 s65, s9, 0
	global_load_dwordx4 v[184:187], v146, s[64:65]
	global_load_dwordx4 v[192:195], v146, s[64:65] offset:16
	s_add_u32 s64, s8, 0x20000
	s_addc_u32 s65, s9, 0
	global_load_dwordx4 v[196:199], v146, s[64:65]
	global_load_dwordx4 v[200:203], v146, s[64:65] offset:16
	s_add_u32 s64, s8, 0x20200
	s_addc_u32 s65, s9, 0
	global_load_dwordx4 v[204:207], v146, s[64:65]
	global_load_dwordx4 v[208:211], v146, s[64:65] offset:16
	s_add_u32 s64, s8, 0x40000
	s_addc_u32 s65, s9, 0
	global_load_dwordx4 v[212:215], v146, s[64:65]
	global_load_dwordx4 v[216:219], v146, s[64:65] offset:16
	s_add_u32 s64, s8, 0x40200
	s_addc_u32 s65, s9, 0
	global_load_dwordx4 v[220:223], v146, s[64:65]
	global_load_dwordx4 v[224:227], v146, s[64:65] offset:16
	s_add_u32 s64, s8, 0x60000
	s_addc_u32 s65, s9, 0
	global_load_dwordx4 v[228:231], v146, s[64:65]
	global_load_dwordx4 v[232:235], v146, s[64:65] offset:16
	s_add_u32 s64, s8, 0x60200
	s_addc_u32 s65, s9, 0
	global_load_dwordx4 v[236:239], v146, s[64:65]
	global_load_dwordx4 v[240:243], v146, s[64:65] offset:16
	s_waitcnt vmcnt(14)
	v_pk_fma_f32 v[176:177], v[176:177], s[14:15], v[126:127] op_sel_hi:[1,0,1]
	v_pk_fma_f32 v[178:179], v[178:179], s[14:15], v[128:129] op_sel_hi:[1,0,1]
	v_pk_fma_f32 v[180:181], v[180:181], s[14:15], v[122:123] op_sel_hi:[1,0,1]
	v_pk_fma_f32 v[182:183], v[182:183], s[14:15], v[124:125] op_sel_hi:[1,0,1]
	v_cvt_pk_bf16_f32 v176, v176, v177
	v_cvt_pk_bf16_f32 v177, v178, v179
	v_cvt_pk_bf16_f32 v178, v180, v181
	v_cvt_pk_bf16_f32 v179, v182, v183
	s_add_u32 s66, s10, 0x0
	s_addc_u32 s67, s11, 0
	global_store_dwordx4 v147, v[176:179], s[66:67]
	s_waitcnt vmcnt(13)
	v_pk_fma_f32 v[184:185], v[184:185], s[14:15], v[118:119] op_sel_hi:[1,0,1]
	v_pk_fma_f32 v[186:187], v[186:187], s[14:15], v[120:121] op_sel_hi:[1,0,1]
	v_pk_fma_f32 v[192:193], v[192:193], s[14:15], v[114:115] op_sel_hi:[1,0,1]
	v_pk_fma_f32 v[194:195], v[194:195], s[14:15], v[116:117] op_sel_hi:[1,0,1]
	v_cvt_pk_bf16_f32 v184, v184, v185
	v_cvt_pk_bf16_f32 v185, v186, v187
	v_cvt_pk_bf16_f32 v186, v192, v193
	v_cvt_pk_bf16_f32 v187, v194, v195
	s_add_u32 s66, s10, 0x100
	s_addc_u32 s67, s11, 0
	global_store_dwordx4 v147, v[184:187], s[66:67]
	s_waitcnt vmcnt(12)
	v_pk_fma_f32 v[196:197], v[196:197], s[14:15], v[110:111] op_sel_hi:[1,0,1]
	v_pk_fma_f32 v[198:199], v[198:199], s[14:15], v[112:113] op_sel_hi:[1,0,1]
	v_pk_fma_f32 v[200:201], v[200:201], s[14:15], v[106:107] op_sel_hi:[1,0,1]
	v_pk_fma_f32 v[202:203], v[202:203], s[14:15], v[108:109] op_sel_hi:[1,0,1]
	v_cvt_pk_bf16_f32 v196, v196, v197
	v_cvt_pk_bf16_f32 v197, v198, v199
	v_cvt_pk_bf16_f32 v198, v200, v201
	v_cvt_pk_bf16_f32 v199, v202, v203
	s_add_u32 s66, s10, 0x10000
	s_addc_u32 s67, s11, 0
	global_store_dwordx4 v147, v[196:199], s[66:67]
	s_waitcnt vmcnt(11)
	v_pk_fma_f32 v[204:205], v[204:205], s[14:15], v[102:103] op_sel_hi:[1,0,1]
	v_pk_fma_f32 v[206:207], v[206:207], s[14:15], v[104:105] op_sel_hi:[1,0,1]
	v_pk_fma_f32 v[208:209], v[208:209], s[14:15], v[98:99] op_sel_hi:[1,0,1]
	v_pk_fma_f32 v[210:211], v[210:211], s[14:15], v[100:101] op_sel_hi:[1,0,1]
	v_cvt_pk_bf16_f32 v204, v204, v205
	v_cvt_pk_bf16_f32 v205, v206, v207
	v_cvt_pk_bf16_f32 v206, v208, v209
	v_cvt_pk_bf16_f32 v207, v210, v211
	s_add_u32 s66, s10, 0x10100
	s_addc_u32 s67, s11, 0
	global_store_dwordx4 v147, v[204:207], s[66:67]
	s_waitcnt vmcnt(10)
	v_pk_fma_f32 v[212:213], v[212:213], s[14:15], v[94:95] op_sel_hi:[1,0,1]
	v_pk_fma_f32 v[214:215], v[214:215], s[14:15], v[96:97] op_sel_hi:[1,0,1]
	v_pk_fma_f32 v[216:217], v[216:217], s[14:15], v[90:91] op_sel_hi:[1,0,1]
	v_pk_fma_f32 v[218:219], v[218:219], s[14:15], v[92:93] op_sel_hi:[1,0,1]
	v_cvt_pk_bf16_f32 v212, v212, v213
	v_cvt_pk_bf16_f32 v213, v214, v215
	v_cvt_pk_bf16_f32 v214, v216, v217
	v_cvt_pk_bf16_f32 v215, v218, v219
	s_add_u32 s66, s10, 0x20000
	s_addc_u32 s67, s11, 0
	global_store_dwordx4 v147, v[212:215], s[66:67]
	s_waitcnt vmcnt(9)
	v_pk_fma_f32 v[220:221], v[220:221], s[14:15], v[86:87] op_sel_hi:[1,0,1]
	v_pk_fma_f32 v[222:223], v[222:223], s[14:15], v[88:89] op_sel_hi:[1,0,1]
	v_pk_fma_f32 v[224:225], v[224:225], s[14:15], v[82:83] op_sel_hi:[1,0,1]
	v_pk_fma_f32 v[226:227], v[226:227], s[14:15], v[84:85] op_sel_hi:[1,0,1]
	v_cvt_pk_bf16_f32 v220, v220, v221
	v_cvt_pk_bf16_f32 v221, v222, v223
	v_cvt_pk_bf16_f32 v222, v224, v225
	v_cvt_pk_bf16_f32 v223, v226, v227
	s_add_u32 s66, s10, 0x20100
	s_addc_u32 s67, s11, 0
	global_store_dwordx4 v147, v[220:223], s[66:67]
	s_waitcnt vmcnt(8)
	v_pk_fma_f32 v[228:229], v[228:229], s[14:15], v[78:79] op_sel_hi:[1,0,1]
	v_pk_fma_f32 v[230:231], v[230:231], s[14:15], v[80:81] op_sel_hi:[1,0,1]
	v_pk_fma_f32 v[232:233], v[232:233], s[14:15], v[74:75] op_sel_hi:[1,0,1]
	v_pk_fma_f32 v[234:235], v[234:235], s[14:15], v[76:77] op_sel_hi:[1,0,1]
	v_cvt_pk_bf16_f32 v228, v228, v229
	v_cvt_pk_bf16_f32 v229, v230, v231
	v_cvt_pk_bf16_f32 v230, v232, v233
	v_cvt_pk_bf16_f32 v231, v234, v235
	s_add_u32 s66, s10, 0x30000
	s_addc_u32 s67, s11, 0
	global_store_dwordx4 v147, v[228:231], s[66:67]
	s_waitcnt vmcnt(7)
	v_pk_fma_f32 v[236:237], v[236:237], s[14:15], v[70:71] op_sel_hi:[1,0,1]
	v_pk_fma_f32 v[238:239], v[238:239], s[14:15], v[72:73] op_sel_hi:[1,0,1]
	v_pk_fma_f32 v[240:241], v[240:241], s[14:15], v[66:67] op_sel_hi:[1,0,1]
	v_pk_fma_f32 v[242:243], v[242:243], s[14:15], v[68:69] op_sel_hi:[1,0,1]
	v_cvt_pk_bf16_f32 v236, v236, v237
	v_cvt_pk_bf16_f32 v237, v238, v239
	v_cvt_pk_bf16_f32 v238, v240, v241
	v_cvt_pk_bf16_f32 v239, v242, v243
	s_add_u32 s66, s10, 0x30100
	s_addc_u32 s67, s11, 0
	global_store_dwordx4 v147, v[236:239], s[66:67]
	s_add_u32 s64, s8, 0x100000
	s_addc_u32 s65, s9, 0
	global_load_dwordx4 v[176:179], v146, s[64:65]
	global_load_dwordx4 v[180:183], v146, s[64:65] offset:16
	s_add_u32 s64, s8, 0x100200
	s_addc_u32 s65, s9, 0
	global_load_dwordx4 v[184:187], v146, s[64:65]
	global_load_dwordx4 v[192:195], v146, s[64:65] offset:16
	s_add_u32 s64, s8, 0x120000
	s_addc_u32 s65, s9, 0
	global_load_dwordx4 v[196:199], v146, s[64:65]
	global_load_dwordx4 v[200:203], v146, s[64:65] offset:16
	s_add_u32 s64, s8, 0x120200
	s_addc_u32 s65, s9, 0
	global_load_dwordx4 v[204:207], v146, s[64:65]
	global_load_dwordx4 v[208:211], v146, s[64:65] offset:16
	s_add_u32 s64, s8, 0x140000
	s_addc_u32 s65, s9, 0
	global_load_dwordx4 v[212:215], v146, s[64:65]
	global_load_dwordx4 v[216:219], v146, s[64:65] offset:16
	s_add_u32 s64, s8, 0x140200
	s_addc_u32 s65, s9, 0
	global_load_dwordx4 v[220:223], v146, s[64:65]
	global_load_dwordx4 v[224:227], v146, s[64:65] offset:16
	s_add_u32 s64, s8, 0x160000
	s_addc_u32 s65, s9, 0
	global_load_dwordx4 v[228:231], v146, s[64:65]
	global_load_dwordx4 v[232:235], v146, s[64:65] offset:16
	s_add_u32 s64, s8, 0x160200
	s_addc_u32 s65, s9, 0
	global_load_dwordx4 v[236:239], v146, s[64:65]
	global_load_dwordx4 v[240:243], v146, s[64:65] offset:16
	s_waitcnt vmcnt(14)
	v_pk_fma_f32 v[176:177], v[176:177], s[14:15], v[62:63] op_sel_hi:[1,0,1]
	v_pk_fma_f32 v[178:179], v[178:179], s[14:15], v[64:65] op_sel_hi:[1,0,1]
	v_pk_fma_f32 v[180:181], v[180:181], s[14:15], v[58:59] op_sel_hi:[1,0,1]
	v_pk_fma_f32 v[182:183], v[182:183], s[14:15], v[60:61] op_sel_hi:[1,0,1]
	v_cvt_pk_bf16_f32 v176, v176, v177
	v_cvt_pk_bf16_f32 v177, v178, v179
	v_cvt_pk_bf16_f32 v178, v180, v181
	v_cvt_pk_bf16_f32 v179, v182, v183
	s_add_u32 s66, s10, 0x80000
	s_addc_u32 s67, s11, 0
	global_store_dwordx4 v147, v[176:179], s[66:67]
	s_waitcnt vmcnt(13)
	v_pk_fma_f32 v[184:185], v[184:185], s[14:15], v[54:55] op_sel_hi:[1,0,1]
	v_pk_fma_f32 v[186:187], v[186:187], s[14:15], v[56:57] op_sel_hi:[1,0,1]
	v_pk_fma_f32 v[192:193], v[192:193], s[14:15], v[50:51] op_sel_hi:[1,0,1]
	v_pk_fma_f32 v[194:195], v[194:195], s[14:15], v[52:53] op_sel_hi:[1,0,1]
	v_cvt_pk_bf16_f32 v184, v184, v185
	v_cvt_pk_bf16_f32 v185, v186, v187
	v_cvt_pk_bf16_f32 v186, v192, v193
	v_cvt_pk_bf16_f32 v187, v194, v195
	s_add_u32 s66, s10, 0x80100
	s_addc_u32 s67, s11, 0
	global_store_dwordx4 v147, v[184:187], s[66:67]
	s_waitcnt vmcnt(12)
	v_pk_fma_f32 v[196:197], v[196:197], s[14:15], v[46:47] op_sel_hi:[1,0,1]
	v_pk_fma_f32 v[198:199], v[198:199], s[14:15], v[48:49] op_sel_hi:[1,0,1]
	v_pk_fma_f32 v[200:201], v[200:201], s[14:15], v[42:43] op_sel_hi:[1,0,1]
	v_pk_fma_f32 v[202:203], v[202:203], s[14:15], v[44:45] op_sel_hi:[1,0,1]
	v_cvt_pk_bf16_f32 v196, v196, v197
	v_cvt_pk_bf16_f32 v197, v198, v199
	v_cvt_pk_bf16_f32 v198, v200, v201
	v_cvt_pk_bf16_f32 v199, v202, v203
	s_add_u32 s66, s10, 0x90000
	s_addc_u32 s67, s11, 0
	global_store_dwordx4 v147, v[196:199], s[66:67]
	s_waitcnt vmcnt(11)
	v_pk_fma_f32 v[204:205], v[204:205], s[14:15], v[38:39] op_sel_hi:[1,0,1]
	v_pk_fma_f32 v[206:207], v[206:207], s[14:15], v[40:41] op_sel_hi:[1,0,1]
	v_pk_fma_f32 v[208:209], v[208:209], s[14:15], v[34:35] op_sel_hi:[1,0,1]
	v_pk_fma_f32 v[210:211], v[210:211], s[14:15], v[36:37] op_sel_hi:[1,0,1]
	v_cvt_pk_bf16_f32 v204, v204, v205
	v_cvt_pk_bf16_f32 v205, v206, v207
	v_cvt_pk_bf16_f32 v206, v208, v209
	v_cvt_pk_bf16_f32 v207, v210, v211
	s_add_u32 s66, s10, 0x90100
	s_addc_u32 s67, s11, 0
	global_store_dwordx4 v147, v[204:207], s[66:67]
	s_waitcnt vmcnt(10)
	v_pk_fma_f32 v[212:213], v[212:213], s[14:15], v[30:31] op_sel_hi:[1,0,1]
	v_pk_fma_f32 v[214:215], v[214:215], s[14:15], v[32:33] op_sel_hi:[1,0,1]
	v_pk_fma_f32 v[216:217], v[216:217], s[14:15], v[26:27] op_sel_hi:[1,0,1]
	v_pk_fma_f32 v[218:219], v[218:219], s[14:15], v[28:29] op_sel_hi:[1,0,1]
	v_cvt_pk_bf16_f32 v212, v212, v213
	v_cvt_pk_bf16_f32 v213, v214, v215
	v_cvt_pk_bf16_f32 v214, v216, v217
	v_cvt_pk_bf16_f32 v215, v218, v219
	s_add_u32 s66, s10, 0xa0000
	s_addc_u32 s67, s11, 0
	global_store_dwordx4 v147, v[212:215], s[66:67]
	s_waitcnt vmcnt(9)
	v_pk_fma_f32 v[220:221], v[220:221], s[14:15], v[22:23] op_sel_hi:[1,0,1]
	v_pk_fma_f32 v[222:223], v[222:223], s[14:15], v[24:25] op_sel_hi:[1,0,1]
	v_pk_fma_f32 v[224:225], v[224:225], s[14:15], v[18:19] op_sel_hi:[1,0,1]
	v_pk_fma_f32 v[226:227], v[226:227], s[14:15], v[20:21] op_sel_hi:[1,0,1]
	v_cvt_pk_bf16_f32 v220, v220, v221
	v_cvt_pk_bf16_f32 v221, v222, v223
	v_cvt_pk_bf16_f32 v222, v224, v225
	v_cvt_pk_bf16_f32 v223, v226, v227
	s_add_u32 s66, s10, 0xa0100
	s_addc_u32 s67, s11, 0
	global_store_dwordx4 v147, v[220:223], s[66:67]
	s_waitcnt vmcnt(8)
	v_pk_fma_f32 v[228:229], v[228:229], s[14:15], v[14:15] op_sel_hi:[1,0,1]
	v_pk_fma_f32 v[230:231], v[230:231], s[14:15], v[16:17] op_sel_hi:[1,0,1]
	v_pk_fma_f32 v[232:233], v[232:233], s[14:15], v[10:11] op_sel_hi:[1,0,1]
	v_pk_fma_f32 v[234:235], v[234:235], s[14:15], v[12:13] op_sel_hi:[1,0,1]
	v_cvt_pk_bf16_f32 v228, v228, v229
	v_cvt_pk_bf16_f32 v229, v230, v231
	v_cvt_pk_bf16_f32 v230, v232, v233
	v_cvt_pk_bf16_f32 v231, v234, v235
	s_add_u32 s66, s10, 0xb0000
	s_addc_u32 s67, s11, 0
	global_store_dwordx4 v147, v[228:231], s[66:67]
	s_waitcnt vmcnt(7)
	v_pk_fma_f32 v[236:237], v[236:237], s[14:15], v[6:7] op_sel_hi:[1,0,1]
	v_pk_fma_f32 v[238:239], v[238:239], s[14:15], v[8:9] op_sel_hi:[1,0,1]
	v_pk_fma_f32 v[240:241], v[240:241], s[14:15], v[2:3] op_sel_hi:[1,0,1]
	v_pk_fma_f32 v[242:243], v[242:243], s[14:15], v[4:5] op_sel_hi:[1,0,1]
	v_cvt_pk_bf16_f32 v236, v236, v237
	v_cvt_pk_bf16_f32 v237, v238, v239
	v_cvt_pk_bf16_f32 v238, v240, v241
	v_cvt_pk_bf16_f32 v239, v242, v243
	s_add_u32 s66, s10, 0xb0100
	s_addc_u32 s67, s11, 0
	global_store_dwordx4 v147, v[236:239], s[66:67]
	s_and_b64 vcc, exec, s[6:7]
	s_mov_b32 s40, s28
	s_mov_b32 s38, s30
	s_mov_b64 s[44:45], s[36:37]
	s_mov_b64 s[42:43], s[34:35]
	s_cbranch_vccz .LBB0_843
	s_waitcnt vmcnt(0)
	s_cmpk_gt_u32 s3, 0xff
	s_cbranch_scc1 .LBB0_854
	s_barrier

.LBB0_1019:
	s_add_u32 s44, s68, 0xfff80080
	s_addc_u32 s45, s69, -1
	s_add_i32 s48, 0, 0x10000
	v_add_u32_e32 v144, s48, v141
	ds_read_b128 v[158:161], v144
	ds_read_b128 v[162:165], v144 offset:1024
	ds_read_b128 v[166:169], v144 offset:2048
	ds_read_b128 v[170:173], v144 offset:3072
	s_cmp_eq_u32 s47, 28
	s_cselect_b32 s95, s11, s45
	s_cselect_b32 s94, s43, s44
	s_cselect_b32 s45, s13, s7
	s_cselect_b32 s44, s46, s6
	v_lshl_add_u64 v[144:145], s[68:69], 0, v[136:137]
	s_add_i32 m0, s23, 0xc000
	ds_read_b128 v[174:177], v143
	ds_read_b128 v[178:181], v143 offset:1024
	ds_read_b128 v[182:185], v143 offset:2048
	ds_read_b128 v[186:189], v143 offset:3072
	ds_read_b128 v[206:209], v143 offset:4096
	ds_read_b128 v[210:213], v143 offset:5120
	ds_read_b128 v[214:217], v143 offset:6144
	ds_read_b128 v[218:221], v143 offset:7168
	global_load_lds_dwordx4 v[144:145], off
	v_lshl_add_u64 v[144:145], s[68:69], 0, v[138:139]
	s_add_i32 m0, s23, 0xe000
	s_nop 0
	global_load_lds_dwordx4 v[144:145], off
	s_waitcnt lgkmcnt(8)
	s_barrier
	s_waitcnt lgkmcnt(0)
	s_setprio 1
	s_waitcnt lgkmcnt(0)
	v_mfma_f32_16x16x32_bf16 v[126:129], v[158:161], v[174:177], v[126:129]
	v_mfma_f32_16x16x32_bf16 v[122:125], v[166:169], v[174:177], v[122:125]
	v_mfma_f32_16x16x32_bf16 v[118:121], v[158:161], v[182:185], v[118:121]
	v_mfma_f32_16x16x32_bf16 v[114:117], v[166:169], v[182:185], v[114:117]
	v_mfma_f32_16x16x32_bf16 v[102:105], v[158:161], v[206:209], v[102:105]
	v_mfma_f32_16x16x32_bf16 v[98:101], v[166:169], v[206:209], v[98:101]
	v_mfma_f32_16x16x32_bf16 v[86:89], v[158:161], v[214:217], v[86:89]
	v_mfma_f32_16x16x32_bf16 v[82:85], v[166:169], v[214:217], v[82:85]
	v_mfma_f32_16x16x32_bf16 v[126:129], v[162:165], v[178:181], v[126:129]
	v_mfma_f32_16x16x32_bf16 v[122:125], v[170:173], v[178:181], v[122:125]
	v_mfma_f32_16x16x32_bf16 v[118:121], v[162:165], v[186:189], v[118:121]
	v_mfma_f32_16x16x32_bf16 v[114:117], v[170:173], v[186:189], v[114:117]
	v_mfma_f32_16x16x32_bf16 v[102:105], v[162:165], v[210:213], v[102:105]
	v_mfma_f32_16x16x32_bf16 v[98:101], v[170:173], v[210:213], v[98:101]
	v_mfma_f32_16x16x32_bf16 v[86:89], v[162:165], v[218:221], v[86:89]
	s_setprio 2
	s_barrier
	v_mfma_f32_16x16x32_bf16 v[82:85], v[170:173], v[218:221], v[82:85]
	s_setprio 0
	s_add_i32 s50, 0, 0x14000
	v_add_u32_e32 v144, s50, v141
	s_add_i32 s48, s48, s22
	ds_read_b128 v[222:225], v144
	ds_read_b128 v[226:229], v144 offset:1024
	ds_read_b128 v[230:233], v144 offset:2048
	ds_read_b128 v[234:237], v144 offset:3072
	v_lshl_add_u64 v[144:145], s[44:45], 0, v[0:1]
	s_mov_b32 m0, s48
	v_lshl_add_u64 v[238:239], s[44:45], 0, v[130:131]
	global_load_lds_dwordx4 v[144:145], off
	s_add_i32 m0, s48, 0x2000
	s_nop 0
	global_load_lds_dwordx4 v[238:239], off
	s_barrier
	s_waitcnt lgkmcnt(0)
	s_setprio 1
	s_waitcnt lgkmcnt(0)
	v_mfma_f32_16x16x32_bf16 v[110:113], v[222:225], v[174:177], v[110:113]
	v_mfma_f32_16x16x32_bf16 v[106:109], v[230:233], v[174:177], v[106:109]
	v_mfma_f32_16x16x32_bf16 v[94:97], v[222:225], v[182:185], v[94:97]
	v_mfma_f32_16x16x32_bf16 v[90:93], v[230:233], v[182:185], v[90:93]
	v_mfma_f32_16x16x32_bf16 v[78:81], v[222:225], v[206:209], v[78:81]
	v_mfma_f32_16x16x32_bf16 v[74:77], v[230:233], v[206:209], v[74:77]
	v_mfma_f32_16x16x32_bf16 v[70:73], v[222:225], v[214:217], v[70:73]
	v_mfma_f32_16x16x32_bf16 v[66:69], v[230:233], v[214:217], v[66:69]
	v_mfma_f32_16x16x32_bf16 v[110:113], v[226:229], v[178:181], v[110:113]
	v_mfma_f32_16x16x32_bf16 v[106:109], v[234:237], v[178:181], v[106:109]
	v_mfma_f32_16x16x32_bf16 v[94:97], v[226:229], v[186:189], v[94:97]
	v_mfma_f32_16x16x32_bf16 v[90:93], v[234:237], v[186:189], v[90:93]
	v_mfma_f32_16x16x32_bf16 v[78:81], v[226:229], v[210:213], v[78:81]
	v_mfma_f32_16x16x32_bf16 v[74:77], v[234:237], v[210:213], v[74:77]
	v_mfma_f32_16x16x32_bf16 v[70:73], v[226:229], v[218:221], v[70:73]
	s_setprio 2
	s_barrier
	v_mfma_f32_16x16x32_bf16 v[66:69], v[234:237], v[218:221], v[66:69]
	s_setprio 0
	s_mov_b32 m0, s23
	v_lshl_add_u64 v[240:241], s[94:95], 0, v[134:135]
	ds_read_b128 v[174:177], v143 offset:16384
	ds_read_b128 v[178:181], v143 offset:17408
	ds_read_b128 v[182:185], v143 offset:18432
	ds_read_b128 v[186:189], v143 offset:19456
	ds_read_b128 v[206:209], v143 offset:20480
	ds_read_b128 v[210:213], v143 offset:21504
	ds_read_b128 v[214:217], v143 offset:22528
	ds_read_b128 v[218:221], v143 offset:23552
	global_load_lds_dwordx4 v[240:241], off
	v_lshl_add_u64 v[242:243], s[94:95], 0, v[132:133]
	s_mov_b32 m0, s26
	s_nop 0
	global_load_lds_dwordx4 v[242:243], off
	s_barrier
	s_waitcnt lgkmcnt(0)
	s_setprio 1
	s_waitcnt lgkmcnt(0)
	v_mfma_f32_16x16x32_bf16 v[62:65], v[158:161], v[174:177], v[62:65]
	v_mfma_f32_16x16x32_bf16 v[58:61], v[166:169], v[174:177], v[58:61]
	v_mfma_f32_16x16x32_bf16 v[54:57], v[158:161], v[182:185], v[54:57]
	v_mfma_f32_16x16x32_bf16 v[50:53], v[166:169], v[182:185], v[50:53]
	v_mfma_f32_16x16x32_bf16 v[38:41], v[158:161], v[206:209], v[38:41]
	v_mfma_f32_16x16x32_bf16 v[34:37], v[166:169], v[206:209], v[34:37]
	v_mfma_f32_16x16x32_bf16 v[22:25], v[158:161], v[214:217], v[22:25]
	v_mfma_f32_16x16x32_bf16 v[18:21], v[166:169], v[214:217], v[18:21]
	v_mfma_f32_16x16x32_bf16 v[62:65], v[162:165], v[178:181], v[62:65]
	v_mfma_f32_16x16x32_bf16 v[58:61], v[170:173], v[178:181], v[58:61]
	v_mfma_f32_16x16x32_bf16 v[54:57], v[162:165], v[186:189], v[54:57]
	v_mfma_f32_16x16x32_bf16 v[50:53], v[170:173], v[186:189], v[50:53]
	v_mfma_f32_16x16x32_bf16 v[38:41], v[162:165], v[210:213], v[38:41]
	v_mfma_f32_16x16x32_bf16 v[34:37], v[170:173], v[210:213], v[34:37]
	v_mfma_f32_16x16x32_bf16 v[22:25], v[162:165], v[218:221], v[22:25]
	s_setprio 2
	s_barrier
	v_mfma_f32_16x16x32_bf16 v[18:21], v[170:173], v[218:221], v[18:21]
	s_setprio 0
	s_add_u32 s48, s44, 0x80000
	s_addc_u32 s49, s45, 0
	s_add_i32 s50, s50, s22
	v_lshl_add_u64 v[158:159], s[48:49], 0, v[0:1]
	s_mov_b32 m0, s50
	s_nop 0
	global_load_lds_dwordx4 v[158:159], off
	v_lshl_add_u64 v[158:159], s[48:49], 0, v[130:131]
	s_add_i32 m0, s50, 0x2000
	s_nop 0
	global_load_lds_dwordx4 v[158:159], off
	s_waitcnt vmcnt(6)
	s_barrier
	s_setprio 1
	v_mfma_f32_16x16x32_bf16 v[46:49], v[222:225], v[174:177], v[46:49]
	v_mfma_f32_16x16x32_bf16 v[42:45], v[230:233], v[174:177], v[42:45]
	v_mfma_f32_16x16x32_bf16 v[30:33], v[222:225], v[182:185], v[30:33]
	v_mfma_f32_16x16x32_bf16 v[26:29], v[230:233], v[182:185], v[26:29]
	v_mfma_f32_16x16x32_bf16 v[14:17], v[222:225], v[206:209], v[14:17]
	v_mfma_f32_16x16x32_bf16 v[10:13], v[230:233], v[206:209], v[10:13]
	v_mfma_f32_16x16x32_bf16 v[6:9], v[222:225], v[214:217], v[6:9]
	v_mfma_f32_16x16x32_bf16 v[2:5], v[230:233], v[214:217], v[2:5]
	v_mfma_f32_16x16x32_bf16 v[46:49], v[226:229], v[178:181], v[46:49]
	v_mfma_f32_16x16x32_bf16 v[42:45], v[234:237], v[178:181], v[42:45]
	v_mfma_f32_16x16x32_bf16 v[30:33], v[226:229], v[186:189], v[30:33]
	v_mfma_f32_16x16x32_bf16 v[26:29], v[234:237], v[186:189], v[26:29]
	v_mfma_f32_16x16x32_bf16 v[14:17], v[226:229], v[210:213], v[14:17]
	v_mfma_f32_16x16x32_bf16 v[10:13], v[234:237], v[210:213], v[10:13]
	v_mfma_f32_16x16x32_bf16 v[6:9], v[226:229], v[218:221], v[6:9]
	s_setprio 2
	s_barrier
	v_mfma_f32_16x16x32_bf16 v[2:5], v[234:237], v[218:221], v[2:5]
	s_setprio 0
	s_add_i32 s50, 0, 0x18000
	v_add_u32_e32 v170, s50, v141
	ds_read_b128 v[158:161], v170
	ds_read_b128 v[162:165], v170 offset:1024
	ds_read_b128 v[166:169], v170 offset:2048
	ds_read_b128 v[170:173], v170 offset:3072
	s_add_u32 s48, s94, 0x80000
	s_addc_u32 s49, s95, 0
	s_mov_b32 m0, s27
	v_lshl_add_u64 v[222:223], s[48:49], 0, v[134:135]
	ds_read_b128 v[174:177], v143 offset:32768
	ds_read_b128 v[178:181], v143 offset:33792
	ds_read_b128 v[182:185], v143 offset:34816
	ds_read_b128 v[186:189], v143 offset:35840
	ds_read_b128 v[206:209], v143 offset:36864
	ds_read_b128 v[210:213], v143 offset:37888
	ds_read_b128 v[214:217], v143 offset:38912
	ds_read_b128 v[218:221], v143 offset:39936
	global_load_lds_dwordx4 v[222:223], off
	v_lshl_add_u64 v[222:223], s[48:49], 0, v[132:133]
	s_mov_b32 m0, s28
	s_nop 0
	global_load_lds_dwordx4 v[222:223], off
	s_waitcnt lgkmcnt(8)
	s_barrier
	s_waitcnt lgkmcnt(0)
	s_setprio 1
	s_waitcnt lgkmcnt(0)
	v_mfma_f32_16x16x32_bf16 v[126:129], v[158:161], v[174:177], v[126:129]
	v_mfma_f32_16x16x32_bf16 v[122:125], v[166:169], v[174:177], v[122:125]
	v_mfma_f32_16x16x32_bf16 v[118:121], v[158:161], v[182:185], v[118:121]
	v_mfma_f32_16x16x32_bf16 v[114:117], v[166:169], v[182:185], v[114:117]
	v_mfma_f32_16x16x32_bf16 v[102:105], v[158:161], v[206:209], v[102:105]
	v_mfma_f32_16x16x32_bf16 v[98:101], v[166:169], v[206:209], v[98:101]
	v_mfma_f32_16x16x32_bf16 v[86:89], v[158:161], v[214:217], v[86:89]
	v_mfma_f32_16x16x32_bf16 v[82:85], v[166:169], v[214:217], v[82:85]
	v_mfma_f32_16x16x32_bf16 v[126:129], v[162:165], v[178:181], v[126:129]
	v_mfma_f32_16x16x32_bf16 v[122:125], v[170:173], v[178:181], v[122:125]
	v_mfma_f32_16x16x32_bf16 v[118:121], v[162:165], v[186:189], v[118:121]
	v_mfma_f32_16x16x32_bf16 v[114:117], v[170:173], v[186:189], v[114:117]
	v_mfma_f32_16x16x32_bf16 v[102:105], v[162:165], v[210:213], v[102:105]
	v_mfma_f32_16x16x32_bf16 v[98:101], v[170:173], v[210:213], v[98:101]
	v_mfma_f32_16x16x32_bf16 v[86:89], v[162:165], v[218:221], v[86:89]
	s_setprio 2
	s_barrier
	v_mfma_f32_16x16x32_bf16 v[82:85], v[170:173], v[218:221], v[82:85]
	s_setprio 0
	s_add_i32 s48, 0, 0x1c000
	s_add_i32 s49, s50, s22
	v_add_u32_e32 v205, s48, v141
	v_lshl_add_u64 v[144:145], v[144:145], 0, s[62:63]
	s_mov_b32 m0, s49
	ds_read_b128 v[222:225], v205
	ds_read_b128 v[226:229], v205 offset:1024
	ds_read_b128 v[230:233], v205 offset:2048
	ds_read_b128 v[234:237], v205 offset:3072
	global_load_lds_dwordx4 v[144:145], off
	v_lshl_add_u64 v[144:145], v[238:239], 0, s[62:63]
	s_add_i32 m0, s49, 0x2000
	s_nop 0
	global_load_lds_dwordx4 v[144:145], off
	s_barrier
	s_waitcnt lgkmcnt(0)
	s_setprio 1
	s_waitcnt lgkmcnt(0)
	v_mfma_f32_16x16x32_bf16 v[110:113], v[222:225], v[174:177], v[110:113]
	v_mfma_f32_16x16x32_bf16 v[106:109], v[230:233], v[174:177], v[106:109]
	v_mfma_f32_16x16x32_bf16 v[94:97], v[222:225], v[182:185], v[94:97]
	v_mfma_f32_16x16x32_bf16 v[90:93], v[230:233], v[182:185], v[90:93]
	v_mfma_f32_16x16x32_bf16 v[78:81], v[222:225], v[206:209], v[78:81]
	v_mfma_f32_16x16x32_bf16 v[74:77], v[230:233], v[206:209], v[74:77]
	v_mfma_f32_16x16x32_bf16 v[70:73], v[222:225], v[214:217], v[70:73]
	v_mfma_f32_16x16x32_bf16 v[66:69], v[230:233], v[214:217], v[66:69]
	v_mfma_f32_16x16x32_bf16 v[110:113], v[226:229], v[178:181], v[110:113]
	v_mfma_f32_16x16x32_bf16 v[106:109], v[234:237], v[178:181], v[106:109]
	v_mfma_f32_16x16x32_bf16 v[94:97], v[226:229], v[186:189], v[94:97]
	v_mfma_f32_16x16x32_bf16 v[90:93], v[234:237], v[186:189], v[90:93]
	v_mfma_f32_16x16x32_bf16 v[78:81], v[226:229], v[210:213], v[78:81]
	v_mfma_f32_16x16x32_bf16 v[74:77], v[234:237], v[210:213], v[74:77]
	v_mfma_f32_16x16x32_bf16 v[70:73], v[226:229], v[218:221], v[70:73]
	s_setprio 2
	s_barrier
	v_mfma_f32_16x16x32_bf16 v[66:69], v[234:237], v[218:221], v[66:69]
	s_setprio 0
	s_mov_b32 m0, s36
	v_lshl_add_u64 v[144:145], v[240:241], 0, s[62:63]
	ds_read_b128 v[174:177], v143 offset:49152
	ds_read_b128 v[178:181], v143 offset:50176
	ds_read_b128 v[182:185], v143 offset:51200
	ds_read_b128 v[186:189], v143 offset:52224
	ds_read_b128 v[206:209], v143 offset:53248
	ds_read_b128 v[210:213], v143 offset:54272
	ds_read_b128 v[214:217], v143 offset:55296
	ds_read_b128 v[218:221], v143 offset:56320
	global_load_lds_dwordx4 v[144:145], off
	v_lshl_add_u64 v[144:145], v[242:243], 0, s[62:63]
	s_mov_b32 m0, s37
	s_nop 0
	global_load_lds_dwordx4 v[144:145], off
	s_barrier
	s_waitcnt lgkmcnt(0)
	s_setprio 1
	s_waitcnt lgkmcnt(0)
	v_mfma_f32_16x16x32_bf16 v[62:65], v[158:161], v[174:177], v[62:65]
	v_mfma_f32_16x16x32_bf16 v[58:61], v[166:169], v[174:177], v[58:61]
	v_mfma_f32_16x16x32_bf16 v[54:57], v[158:161], v[182:185], v[54:57]
	v_mfma_f32_16x16x32_bf16 v[50:53], v[166:169], v[182:185], v[50:53]
	v_mfma_f32_16x16x32_bf16 v[38:41], v[158:161], v[206:209], v[38:41]
	v_mfma_f32_16x16x32_bf16 v[34:37], v[166:169], v[206:209], v[34:37]
	v_mfma_f32_16x16x32_bf16 v[22:25], v[158:161], v[214:217], v[22:25]
	v_mfma_f32_16x16x32_bf16 v[18:21], v[166:169], v[214:217], v[18:21]
	v_mfma_f32_16x16x32_bf16 v[62:65], v[162:165], v[178:181], v[62:65]
	v_mfma_f32_16x16x32_bf16 v[58:61], v[170:173], v[178:181], v[58:61]
	v_mfma_f32_16x16x32_bf16 v[54:57], v[162:165], v[186:189], v[54:57]
	v_mfma_f32_16x16x32_bf16 v[50:53], v[170:173], v[186:189], v[50:53]
	v_mfma_f32_16x16x32_bf16 v[38:41], v[162:165], v[210:213], v[38:41]
	v_mfma_f32_16x16x32_bf16 v[34:37], v[170:173], v[210:213], v[34:37]
	v_mfma_f32_16x16x32_bf16 v[22:25], v[162:165], v[218:221], v[22:25]
	s_setprio 2
	s_barrier
	v_mfma_f32_16x16x32_bf16 v[18:21], v[170:173], v[218:221], v[18:21]
	s_setprio 0
	s_add_u32 s44, s44, 0x80080
	s_addc_u32 s45, s45, 0
	s_add_i32 s48, s48, s22
	v_lshl_add_u64 v[144:145], s[44:45], 0, v[0:1]
	s_mov_b32 m0, s48
	s_nop 0
	global_load_lds_dwordx4 v[144:145], off
	v_lshl_add_u64 v[144:145], s[44:45], 0, v[130:131]
	s_add_i32 m0, s48, 0x2000
	s_nop 0
	global_load_lds_dwordx4 v[144:145], off
	s_waitcnt vmcnt(6)
	s_barrier
	s_setprio 1
	v_mfma_f32_16x16x32_bf16 v[46:49], v[222:225], v[174:177], v[46:49]
	v_mfma_f32_16x16x32_bf16 v[42:45], v[230:233], v[174:177], v[42:45]
	v_mfma_f32_16x16x32_bf16 v[30:33], v[222:225], v[182:185], v[30:33]
	v_mfma_f32_16x16x32_bf16 v[26:29], v[230:233], v[182:185], v[26:29]
	v_mfma_f32_16x16x32_bf16 v[14:17], v[222:225], v[206:209], v[14:17]
	v_mfma_f32_16x16x32_bf16 v[10:13], v[230:233], v[206:209], v[10:13]
	v_mfma_f32_16x16x32_bf16 v[6:9], v[222:225], v[214:217], v[6:9]
	v_mfma_f32_16x16x32_bf16 v[2:5], v[230:233], v[214:217], v[2:5]
	v_mfma_f32_16x16x32_bf16 v[46:49], v[226:229], v[178:181], v[46:49]
	v_mfma_f32_16x16x32_bf16 v[42:45], v[234:237], v[178:181], v[42:45]
	v_mfma_f32_16x16x32_bf16 v[30:33], v[226:229], v[186:189], v[30:33]
	v_mfma_f32_16x16x32_bf16 v[26:29], v[234:237], v[186:189], v[26:29]
	v_mfma_f32_16x16x32_bf16 v[14:17], v[226:229], v[210:213], v[14:17]
	v_mfma_f32_16x16x32_bf16 v[10:13], v[234:237], v[210:213], v[10:13]
	v_mfma_f32_16x16x32_bf16 v[6:9], v[226:229], v[218:221], v[6:9]
	s_setprio 2
	s_barrier
	v_mfma_f32_16x16x32_bf16 v[2:5], v[234:237], v[218:221], v[2:5]
	s_setprio 0
	s_add_i32 s47, s47, 2
	s_add_u32 s68, s68, 0x100
	s_addc_u32 s69, s69, 0
	s_add_u32 s6, s6, 0x100
	s_addc_u32 s7, s7, 0
	s_cmp_gt_u32 s47, 29
	s_cbranch_scc0 .LBB0_1019
	s_lshl_b32 s6, s42, 8
	s_and_b32 s6, s6, 0x3f00
	v_add_u32_e32 v160, s6, v140
	s_mul_hi_i32 s6, s41, 0x2aaaaaab
	s_lshr_b32 s7, s6, 31
	s_lshr_b32 s6, s6, 2
	s_add_i32 s6, s6, s7
	s_mul_i32 s6, s6, 24
	s_sub_i32 s6, s41, s6
	v_lshl_or_b32 v144, s6, 8, v142
	v_ashrrev_i32_e32 v145, 31, v144
	v_lshl_add_u64 v[144:145], v[144:145], 1, s[84:85]
	v_cvt_pk_bf16_f32 v70, v70, v71
	v_cvt_pk_bf16_f32 v71, v72, v73
	v_cvt_pk_bf16_f32 v72, v66, v67
	v_add_u32_e32 v66, 0x80, v160
	v_mad_i64_i32 v[158:159], s[6:7], v160, s34, v[144:145]
	v_cvt_pk_bf16_f32 v110, v110, v111
	v_cvt_pk_bf16_f32 v111, v112, v113
	v_cvt_pk_bf16_f32 v112, v106, v107
	v_cvt_pk_bf16_f32 v113, v108, v109
	v_or_b32_e32 v106, 16, v160
	v_mad_i64_i32 v[66:67], s[6:7], v66, s34, v[144:145]
	v_cvt_pk_bf16_f32 v46, v46, v47
	v_cvt_pk_bf16_f32 v47, v48, v49
	v_cvt_pk_bf16_f32 v48, v42, v43
	v_cvt_pk_bf16_f32 v49, v44, v45
	v_add_u32_e32 v42, 0x90, v160
	global_store_dwordx4 v[158:159], v[110:113], off offset:256
	v_cvt_pk_bf16_f32 v94, v94, v95
	v_cvt_pk_bf16_f32 v95, v96, v97
	v_mad_i64_i32 v[110:111], s[6:7], v106, s34, v[144:145]
	v_cvt_pk_bf16_f32 v96, v90, v91
	v_cvt_pk_bf16_f32 v97, v92, v93
	v_or_b32_e32 v90, 32, v160
	global_store_dwordx4 v[66:67], v[46:49], off offset:256
	v_cvt_pk_bf16_f32 v30, v30, v31
	v_cvt_pk_bf16_f32 v31, v32, v33
	v_mad_i64_i32 v[46:47], s[6:7], v42, s34, v[144:145]
	v_cvt_pk_bf16_f32 v32, v26, v27
	v_cvt_pk_bf16_f32 v33, v28, v29
	v_add_u32_e32 v26, 0xa0, v160
	global_store_dwordx4 v[110:111], v[94:97], off offset:256
	v_cvt_pk_bf16_f32 v78, v78, v79
	v_cvt_pk_bf16_f32 v79, v80, v81
	v_mad_i64_i32 v[94:95], s[6:7], v90, s34, v[144:145]
	v_cvt_pk_bf16_f32 v80, v74, v75
	v_cvt_pk_bf16_f32 v81, v76, v77
	v_or_b32_e32 v74, 48, v160
	global_store_dwordx4 v[46:47], v[30:33], off offset:256
	v_cvt_pk_bf16_f32 v14, v14, v15
	v_cvt_pk_bf16_f32 v15, v16, v17
	v_mad_i64_i32 v[30:31], s[6:7], v26, s34, v[144:145]
	v_cvt_pk_bf16_f32 v16, v10, v11
	v_cvt_pk_bf16_f32 v17, v12, v13
	v_add_u32_e32 v10, 0xb0, v160
	global_store_dwordx4 v[94:95], v[78:81], off offset:256
	global_store_dwordx4 v[30:31], v[14:17], off offset:256
	v_cvt_pk_bf16_f32 v126, v126, v127
	v_mad_i64_i32 v[78:79], s[6:7], v74, s34, v[144:145]
	v_mad_i64_i32 v[14:15], s[6:7], v10, s34, v[144:145]
	v_cvt_pk_bf16_f32 v127, v128, v129
	v_cvt_pk_bf16_f32 v128, v122, v123
	v_cvt_pk_bf16_f32 v129, v124, v125
	v_cvt_pk_bf16_f32 v106, v118, v119
	v_cvt_pk_bf16_f32 v107, v120, v121
	v_cvt_pk_bf16_f32 v108, v114, v115
	v_cvt_pk_bf16_f32 v109, v116, v117
	v_cvt_pk_bf16_f32 v90, v102, v103
	v_cvt_pk_bf16_f32 v91, v104, v105
	v_cvt_pk_bf16_f32 v92, v98, v99
	v_cvt_pk_bf16_f32 v93, v100, v101
	v_cvt_pk_bf16_f32 v74, v86, v87
	v_cvt_pk_bf16_f32 v75, v88, v89
	v_cvt_pk_bf16_f32 v76, v82, v83
	v_cvt_pk_bf16_f32 v77, v84, v85
	v_cvt_pk_bf16_f32 v73, v68, v69
	v_cvt_pk_bf16_f32 v62, v62, v63
	v_cvt_pk_bf16_f32 v63, v64, v65
	v_cvt_pk_bf16_f32 v64, v58, v59
	v_cvt_pk_bf16_f32 v65, v60, v61
	v_cvt_pk_bf16_f32 v42, v54, v55
	v_cvt_pk_bf16_f32 v43, v56, v57
	v_cvt_pk_bf16_f32 v44, v50, v51
	v_cvt_pk_bf16_f32 v45, v52, v53
	v_cvt_pk_bf16_f32 v26, v38, v39
	v_cvt_pk_bf16_f32 v27, v40, v41
	v_cvt_pk_bf16_f32 v28, v34, v35
	v_cvt_pk_bf16_f32 v29, v36, v37
	v_cvt_pk_bf16_f32 v10, v22, v23
	v_cvt_pk_bf16_f32 v11, v24, v25
	v_cvt_pk_bf16_f32 v12, v18, v19
	v_cvt_pk_bf16_f32 v13, v20, v21
	v_cvt_pk_bf16_f32 v6, v6, v7
	v_cvt_pk_bf16_f32 v7, v8, v9
	v_cvt_pk_bf16_f32 v8, v2, v3
	v_cvt_pk_bf16_f32 v9, v4, v5
	s_and_b64 vcc, exec, s[8:9]
	s_mov_b32 s41, s12
	s_mov_b32 s42, s10
	s_mov_b64 s[94:95], s[64:65]
	s_mov_b64 s[6:7], s[14:15]
	global_store_dwordx4 v[158:159], v[126:129], off
	global_store_dwordx4 v[110:111], v[106:109], off
	global_store_dwordx4 v[94:95], v[90:93], off
	global_store_dwordx4 v[78:79], v[74:77], off
	global_store_dwordx4 v[78:79], v[70:73], off offset:256
	global_store_dwordx4 v[66:67], v[62:65], off
	global_store_dwordx4 v[46:47], v[42:45], off
	global_store_dwordx4 v[30:31], v[26:29], off
	global_store_dwordx4 v[14:15], v[10:13], off
	global_store_dwordx4 v[14:15], v[6:9], off offset:256
	s_cbranch_vccz .LBB0_1016
	s_waitcnt vmcnt(0)
	s_cmpk_gt_u32 s5, 0xff
	s_cbranch_scc1 .LBB0_1023
	s_barrier

.LBB0_1256:
	s_add_u32 s44, s64, 0xfff80080
	s_addc_u32 s45, s65, -1
	s_add_i32 s48, 0, 0x10000
	v_add_u32_e32 v102, s48, v187
	ds_read_b128 v[90:93], v102
	ds_read_b128 v[94:97], v102 offset:1024
	ds_read_b128 v[98:101], v102 offset:2048
	ds_read_b128 v[102:105], v102 offset:3072
	s_cmp_eq_u32 s47, 28
	s_cselect_b32 s69, s4, s45
	s_cselect_b32 s68, s5, s44
	s_cselect_b32 s45, s6, s19
	s_cselect_b32 s44, s7, s18
	v_lshl_add_u64 v[184:185], s[64:65], 0, v[164:165]
	s_add_i32 m0, s27, 0xc000
	ds_read_b128 v[168:171], v189
	ds_read_b128 v[172:175], v189 offset:1024
	ds_read_b128 v[176:179], v189 offset:2048
	ds_read_b128 v[180:183], v189 offset:3072
	ds_read_b128 v[206:209], v189 offset:4096
	ds_read_b128 v[210:213], v189 offset:5120
	ds_read_b128 v[214:217], v189 offset:6144
	ds_read_b128 v[218:221], v189 offset:7168
	global_load_lds_dwordx4 v[184:185], off
	v_lshl_add_u64 v[184:185], s[64:65], 0, v[166:167]
	s_add_i32 m0, s27, 0xe000
	s_nop 0
	global_load_lds_dwordx4 v[184:185], off
	s_waitcnt lgkmcnt(8)
	s_barrier
	s_waitcnt lgkmcnt(0)
	s_setprio 1
	s_waitcnt lgkmcnt(0)
	v_mfma_f32_16x16x32_bf16 v[142:145], v[90:93], v[168:171], v[142:145]
	v_mfma_f32_16x16x32_bf16 v[138:141], v[98:101], v[168:171], v[138:141]
	v_mfma_f32_16x16x32_bf16 v[134:137], v[90:93], v[176:179], v[134:137]
	v_mfma_f32_16x16x32_bf16 v[130:133], v[98:101], v[176:179], v[130:133]
	v_mfma_f32_16x16x32_bf16 v[126:129], v[90:93], v[206:209], v[126:129]
	v_mfma_f32_16x16x32_bf16 v[122:125], v[98:101], v[206:209], v[122:125]
	v_mfma_f32_16x16x32_bf16 v[118:121], v[90:93], v[214:217], v[118:121]
	v_mfma_f32_16x16x32_bf16 v[114:117], v[98:101], v[214:217], v[114:117]
	v_mfma_f32_16x16x32_bf16 v[142:145], v[94:97], v[172:175], v[142:145]
	v_mfma_f32_16x16x32_bf16 v[138:141], v[102:105], v[172:175], v[138:141]
	v_mfma_f32_16x16x32_bf16 v[134:137], v[94:97], v[180:183], v[134:137]
	v_mfma_f32_16x16x32_bf16 v[130:133], v[102:105], v[180:183], v[130:133]
	v_mfma_f32_16x16x32_bf16 v[126:129], v[94:97], v[210:213], v[126:129]
	v_mfma_f32_16x16x32_bf16 v[122:125], v[102:105], v[210:213], v[122:125]
	v_mfma_f32_16x16x32_bf16 v[118:121], v[94:97], v[218:221], v[118:121]
	s_setprio 2
	s_barrier
	v_mfma_f32_16x16x32_bf16 v[114:117], v[102:105], v[218:221], v[114:117]
	s_setprio 0
	s_add_i32 s50, 0, 0x14000
	v_add_u32_e32 v184, s50, v187
	s_add_i32 s48, s48, s22
	ds_read_b128 v[222:225], v184
	ds_read_b128 v[226:229], v184 offset:1024
	ds_read_b128 v[230:233], v184 offset:2048
	ds_read_b128 v[234:237], v184 offset:3072
	v_lshl_add_u64 v[184:185], s[44:45], 0, v[0:1]
	s_mov_b32 m0, s48
	v_lshl_add_u64 v[238:239], s[44:45], 0, v[158:159]
	global_load_lds_dwordx4 v[184:185], off
	s_add_i32 m0, s48, 0x2000
	s_nop 0
	global_load_lds_dwordx4 v[238:239], off
	s_barrier
	s_waitcnt lgkmcnt(0)
	s_setprio 1
	s_waitcnt lgkmcnt(0)
	v_mfma_f32_16x16x32_bf16 v[62:65], v[222:225], v[168:171], v[62:65]
	v_mfma_f32_16x16x32_bf16 v[58:61], v[230:233], v[168:171], v[58:61]
	v_mfma_f32_16x16x32_bf16 v[54:57], v[222:225], v[176:179], v[54:57]
	v_mfma_f32_16x16x32_bf16 v[50:53], v[230:233], v[176:179], v[50:53]
	v_mfma_f32_16x16x32_bf16 v[46:49], v[222:225], v[206:209], v[46:49]
	v_mfma_f32_16x16x32_bf16 v[42:45], v[230:233], v[206:209], v[42:45]
	v_mfma_f32_16x16x32_bf16 v[38:41], v[222:225], v[214:217], v[38:41]
	v_mfma_f32_16x16x32_bf16 v[34:37], v[230:233], v[214:217], v[34:37]
	v_mfma_f32_16x16x32_bf16 v[62:65], v[226:229], v[172:175], v[62:65]
	v_mfma_f32_16x16x32_bf16 v[58:61], v[234:237], v[172:175], v[58:61]
	v_mfma_f32_16x16x32_bf16 v[54:57], v[226:229], v[180:183], v[54:57]
	v_mfma_f32_16x16x32_bf16 v[50:53], v[234:237], v[180:183], v[50:53]
	v_mfma_f32_16x16x32_bf16 v[46:49], v[226:229], v[210:213], v[46:49]
	v_mfma_f32_16x16x32_bf16 v[42:45], v[234:237], v[210:213], v[42:45]
	v_mfma_f32_16x16x32_bf16 v[38:41], v[226:229], v[218:221], v[38:41]
	s_setprio 2
	s_barrier
	v_mfma_f32_16x16x32_bf16 v[34:37], v[234:237], v[218:221], v[34:37]
	s_setprio 0
	s_mov_b32 m0, s27
	v_lshl_add_u64 v[240:241], s[68:69], 0, v[162:163]
	ds_read_b128 v[168:171], v189 offset:16384
	ds_read_b128 v[172:175], v189 offset:17408
	ds_read_b128 v[176:179], v189 offset:18432
	ds_read_b128 v[180:183], v189 offset:19456
	ds_read_b128 v[206:209], v189 offset:20480
	ds_read_b128 v[210:213], v189 offset:21504
	ds_read_b128 v[214:217], v189 offset:22528
	ds_read_b128 v[218:221], v189 offset:23552
	global_load_lds_dwordx4 v[240:241], off
	v_lshl_add_u64 v[242:243], s[68:69], 0, v[160:161]
	s_mov_b32 m0, s28
	s_nop 0
	global_load_lds_dwordx4 v[242:243], off
	s_barrier
	s_waitcnt lgkmcnt(0)
	s_setprio 1
	s_waitcnt lgkmcnt(0)
	v_mfma_f32_16x16x32_bf16 v[110:113], v[90:93], v[168:171], v[110:113]
	v_mfma_f32_16x16x32_bf16 v[106:109], v[98:101], v[168:171], v[106:109]
	v_mfma_f32_16x16x32_bf16 v[86:89], v[90:93], v[176:179], v[86:89]
	v_mfma_f32_16x16x32_bf16 v[82:85], v[98:101], v[176:179], v[82:85]
	v_mfma_f32_16x16x32_bf16 v[78:81], v[90:93], v[206:209], v[78:81]
	v_mfma_f32_16x16x32_bf16 v[74:77], v[98:101], v[206:209], v[74:77]
	v_mfma_f32_16x16x32_bf16 v[70:73], v[90:93], v[214:217], v[70:73]
	v_mfma_f32_16x16x32_bf16 v[66:69], v[98:101], v[214:217], v[66:69]
	v_mfma_f32_16x16x32_bf16 v[110:113], v[94:97], v[172:175], v[110:113]
	v_mfma_f32_16x16x32_bf16 v[106:109], v[102:105], v[172:175], v[106:109]
	v_mfma_f32_16x16x32_bf16 v[86:89], v[94:97], v[180:183], v[86:89]
	v_mfma_f32_16x16x32_bf16 v[82:85], v[102:105], v[180:183], v[82:85]
	v_mfma_f32_16x16x32_bf16 v[78:81], v[94:97], v[210:213], v[78:81]
	v_mfma_f32_16x16x32_bf16 v[74:77], v[102:105], v[210:213], v[74:77]
	v_mfma_f32_16x16x32_bf16 v[70:73], v[94:97], v[218:221], v[70:73]
	s_setprio 2
	s_barrier
	v_mfma_f32_16x16x32_bf16 v[66:69], v[102:105], v[218:221], v[66:69]
	s_setprio 0
	s_add_u32 s48, s44, 0x80000
	s_addc_u32 s49, s45, 0
	s_add_i32 s50, s50, s22
	v_lshl_add_u64 v[90:91], s[48:49], 0, v[0:1]
	s_mov_b32 m0, s50
	s_nop 0
	global_load_lds_dwordx4 v[90:91], off
	v_lshl_add_u64 v[90:91], s[48:49], 0, v[158:159]
	s_add_i32 m0, s50, 0x2000
	s_nop 0
	global_load_lds_dwordx4 v[90:91], off
	s_waitcnt vmcnt(6)
	s_barrier
	s_setprio 1
	v_mfma_f32_16x16x32_bf16 v[30:33], v[222:225], v[168:171], v[30:33]
	v_mfma_f32_16x16x32_bf16 v[26:29], v[230:233], v[168:171], v[26:29]
	v_mfma_f32_16x16x32_bf16 v[22:25], v[222:225], v[176:179], v[22:25]
	v_mfma_f32_16x16x32_bf16 v[18:21], v[230:233], v[176:179], v[18:21]
	v_mfma_f32_16x16x32_bf16 v[14:17], v[222:225], v[206:209], v[14:17]
	v_mfma_f32_16x16x32_bf16 v[10:13], v[230:233], v[206:209], v[10:13]
	v_mfma_f32_16x16x32_bf16 v[6:9], v[222:225], v[214:217], v[6:9]
	v_mfma_f32_16x16x32_bf16 v[2:5], v[230:233], v[214:217], v[2:5]
	v_mfma_f32_16x16x32_bf16 v[30:33], v[226:229], v[172:175], v[30:33]
	v_mfma_f32_16x16x32_bf16 v[26:29], v[234:237], v[172:175], v[26:29]
	v_mfma_f32_16x16x32_bf16 v[22:25], v[226:229], v[180:183], v[22:25]
	v_mfma_f32_16x16x32_bf16 v[18:21], v[234:237], v[180:183], v[18:21]
	v_mfma_f32_16x16x32_bf16 v[14:17], v[226:229], v[210:213], v[14:17]
	v_mfma_f32_16x16x32_bf16 v[10:13], v[234:237], v[210:213], v[10:13]
	v_mfma_f32_16x16x32_bf16 v[6:9], v[226:229], v[218:221], v[6:9]
	s_setprio 2
	s_barrier
	v_mfma_f32_16x16x32_bf16 v[2:5], v[234:237], v[218:221], v[2:5]
	s_setprio 0
	s_add_i32 s50, 0, 0x18000
	v_add_u32_e32 v102, s50, v187
	ds_read_b128 v[90:93], v102
	ds_read_b128 v[94:97], v102 offset:1024
	ds_read_b128 v[98:101], v102 offset:2048
	ds_read_b128 v[102:105], v102 offset:3072
	s_add_u32 s48, s68, 0x80000
	s_addc_u32 s49, s69, 0
	s_mov_b32 m0, s36
	v_lshl_add_u64 v[222:223], s[48:49], 0, v[162:163]
	ds_read_b128 v[168:171], v189 offset:32768
	ds_read_b128 v[172:175], v189 offset:33792
	ds_read_b128 v[176:179], v189 offset:34816
	ds_read_b128 v[180:183], v189 offset:35840
	ds_read_b128 v[206:209], v189 offset:36864
	ds_read_b128 v[210:213], v189 offset:37888
	ds_read_b128 v[214:217], v189 offset:38912
	ds_read_b128 v[218:221], v189 offset:39936
	global_load_lds_dwordx4 v[222:223], off
	v_lshl_add_u64 v[222:223], s[48:49], 0, v[160:161]
	s_mov_b32 m0, s37
	s_nop 0
	global_load_lds_dwordx4 v[222:223], off
	s_waitcnt lgkmcnt(8)
	s_barrier
	s_waitcnt lgkmcnt(0)
	s_setprio 1
	s_waitcnt lgkmcnt(0)
	v_mfma_f32_16x16x32_bf16 v[142:145], v[90:93], v[168:171], v[142:145]
	v_mfma_f32_16x16x32_bf16 v[138:141], v[98:101], v[168:171], v[138:141]
	v_mfma_f32_16x16x32_bf16 v[134:137], v[90:93], v[176:179], v[134:137]
	v_mfma_f32_16x16x32_bf16 v[130:133], v[98:101], v[176:179], v[130:133]
	v_mfma_f32_16x16x32_bf16 v[126:129], v[90:93], v[206:209], v[126:129]
	v_mfma_f32_16x16x32_bf16 v[122:125], v[98:101], v[206:209], v[122:125]
	v_mfma_f32_16x16x32_bf16 v[118:121], v[90:93], v[214:217], v[118:121]
	v_mfma_f32_16x16x32_bf16 v[114:117], v[98:101], v[214:217], v[114:117]
	v_mfma_f32_16x16x32_bf16 v[142:145], v[94:97], v[172:175], v[142:145]
	v_mfma_f32_16x16x32_bf16 v[138:141], v[102:105], v[172:175], v[138:141]
	v_mfma_f32_16x16x32_bf16 v[134:137], v[94:97], v[180:183], v[134:137]
	v_mfma_f32_16x16x32_bf16 v[130:133], v[102:105], v[180:183], v[130:133]
	v_mfma_f32_16x16x32_bf16 v[126:129], v[94:97], v[210:213], v[126:129]
	v_mfma_f32_16x16x32_bf16 v[122:125], v[102:105], v[210:213], v[122:125]
	v_mfma_f32_16x16x32_bf16 v[118:121], v[94:97], v[218:221], v[118:121]
	s_setprio 2
	s_barrier
	v_mfma_f32_16x16x32_bf16 v[114:117], v[102:105], v[218:221], v[114:117]
	s_setprio 0
	s_add_i32 s48, 0, 0x1c000
	s_add_i32 s49, s50, s22
	v_add_u32_e32 v205, s48, v187
	v_lshl_add_u64 v[184:185], v[184:185], 0, s[62:63]
	s_mov_b32 m0, s49
	ds_read_b128 v[222:225], v205
	ds_read_b128 v[226:229], v205 offset:1024
	ds_read_b128 v[230:233], v205 offset:2048
	ds_read_b128 v[234:237], v205 offset:3072
	global_load_lds_dwordx4 v[184:185], off
	v_lshl_add_u64 v[184:185], v[238:239], 0, s[62:63]
	s_add_i32 m0, s49, 0x2000
	s_nop 0
	global_load_lds_dwordx4 v[184:185], off
	s_barrier
	s_waitcnt lgkmcnt(0)
	s_setprio 1
	s_waitcnt lgkmcnt(0)
	v_mfma_f32_16x16x32_bf16 v[62:65], v[222:225], v[168:171], v[62:65]
	v_mfma_f32_16x16x32_bf16 v[58:61], v[230:233], v[168:171], v[58:61]
	v_mfma_f32_16x16x32_bf16 v[54:57], v[222:225], v[176:179], v[54:57]
	v_mfma_f32_16x16x32_bf16 v[50:53], v[230:233], v[176:179], v[50:53]
	v_mfma_f32_16x16x32_bf16 v[46:49], v[222:225], v[206:209], v[46:49]
	v_mfma_f32_16x16x32_bf16 v[42:45], v[230:233], v[206:209], v[42:45]
	v_mfma_f32_16x16x32_bf16 v[38:41], v[222:225], v[214:217], v[38:41]
	v_mfma_f32_16x16x32_bf16 v[34:37], v[230:233], v[214:217], v[34:37]
	v_mfma_f32_16x16x32_bf16 v[62:65], v[226:229], v[172:175], v[62:65]
	v_mfma_f32_16x16x32_bf16 v[58:61], v[234:237], v[172:175], v[58:61]
	v_mfma_f32_16x16x32_bf16 v[54:57], v[226:229], v[180:183], v[54:57]
	v_mfma_f32_16x16x32_bf16 v[50:53], v[234:237], v[180:183], v[50:53]
	v_mfma_f32_16x16x32_bf16 v[46:49], v[226:229], v[210:213], v[46:49]
	v_mfma_f32_16x16x32_bf16 v[42:45], v[234:237], v[210:213], v[42:45]
	v_mfma_f32_16x16x32_bf16 v[38:41], v[226:229], v[218:221], v[38:41]
	s_setprio 2
	s_barrier
	v_mfma_f32_16x16x32_bf16 v[34:37], v[234:237], v[218:221], v[34:37]
	s_setprio 0
	s_mov_b32 m0, s40
	v_lshl_add_u64 v[184:185], v[240:241], 0, s[62:63]
	ds_read_b128 v[168:171], v189 offset:49152
	ds_read_b128 v[172:175], v189 offset:50176
	ds_read_b128 v[176:179], v189 offset:51200
	ds_read_b128 v[180:183], v189 offset:52224
	ds_read_b128 v[206:209], v189 offset:53248
	ds_read_b128 v[210:213], v189 offset:54272
	ds_read_b128 v[214:217], v189 offset:55296
	ds_read_b128 v[218:221], v189 offset:56320
	global_load_lds_dwordx4 v[184:185], off
	v_lshl_add_u64 v[184:185], v[242:243], 0, s[62:63]
	s_mov_b32 m0, s41
	s_nop 0
	global_load_lds_dwordx4 v[184:185], off
	s_barrier
	s_waitcnt lgkmcnt(0)
	s_setprio 1
	s_waitcnt lgkmcnt(0)
	v_mfma_f32_16x16x32_bf16 v[110:113], v[90:93], v[168:171], v[110:113]
	v_mfma_f32_16x16x32_bf16 v[106:109], v[98:101], v[168:171], v[106:109]
	v_mfma_f32_16x16x32_bf16 v[86:89], v[90:93], v[176:179], v[86:89]
	v_mfma_f32_16x16x32_bf16 v[82:85], v[98:101], v[176:179], v[82:85]
	v_mfma_f32_16x16x32_bf16 v[78:81], v[90:93], v[206:209], v[78:81]
	v_mfma_f32_16x16x32_bf16 v[74:77], v[98:101], v[206:209], v[74:77]
	v_mfma_f32_16x16x32_bf16 v[70:73], v[90:93], v[214:217], v[70:73]
	v_mfma_f32_16x16x32_bf16 v[66:69], v[98:101], v[214:217], v[66:69]
	v_mfma_f32_16x16x32_bf16 v[110:113], v[94:97], v[172:175], v[110:113]
	v_mfma_f32_16x16x32_bf16 v[106:109], v[102:105], v[172:175], v[106:109]
	v_mfma_f32_16x16x32_bf16 v[86:89], v[94:97], v[180:183], v[86:89]
	v_mfma_f32_16x16x32_bf16 v[82:85], v[102:105], v[180:183], v[82:85]
	v_mfma_f32_16x16x32_bf16 v[78:81], v[94:97], v[210:213], v[78:81]
	v_mfma_f32_16x16x32_bf16 v[74:77], v[102:105], v[210:213], v[74:77]
	v_mfma_f32_16x16x32_bf16 v[70:73], v[94:97], v[218:221], v[70:73]
	s_setprio 2
	s_barrier
	v_mfma_f32_16x16x32_bf16 v[66:69], v[102:105], v[218:221], v[66:69]
	s_setprio 0
	s_add_u32 s44, s44, 0x80080
	s_addc_u32 s45, s45, 0
	s_add_i32 s48, s48, s22
	v_lshl_add_u64 v[90:91], s[44:45], 0, v[0:1]
	s_mov_b32 m0, s48
	s_nop 0
	global_load_lds_dwordx4 v[90:91], off
	v_lshl_add_u64 v[90:91], s[44:45], 0, v[158:159]
	s_add_i32 m0, s48, 0x2000
	s_nop 0
	global_load_lds_dwordx4 v[90:91], off
	s_waitcnt vmcnt(6)
	s_barrier
	s_setprio 1
	v_mfma_f32_16x16x32_bf16 v[30:33], v[222:225], v[168:171], v[30:33]
	v_mfma_f32_16x16x32_bf16 v[26:29], v[230:233], v[168:171], v[26:29]
	v_mfma_f32_16x16x32_bf16 v[22:25], v[222:225], v[176:179], v[22:25]
	v_mfma_f32_16x16x32_bf16 v[18:21], v[230:233], v[176:179], v[18:21]
	v_mfma_f32_16x16x32_bf16 v[14:17], v[222:225], v[206:209], v[14:17]
	v_mfma_f32_16x16x32_bf16 v[10:13], v[230:233], v[206:209], v[10:13]
	v_mfma_f32_16x16x32_bf16 v[6:9], v[222:225], v[214:217], v[6:9]
	v_mfma_f32_16x16x32_bf16 v[2:5], v[230:233], v[214:217], v[2:5]
	v_mfma_f32_16x16x32_bf16 v[30:33], v[226:229], v[172:175], v[30:33]
	v_mfma_f32_16x16x32_bf16 v[26:29], v[234:237], v[172:175], v[26:29]
	v_mfma_f32_16x16x32_bf16 v[22:25], v[226:229], v[180:183], v[22:25]
	v_mfma_f32_16x16x32_bf16 v[18:21], v[234:237], v[180:183], v[18:21]
	v_mfma_f32_16x16x32_bf16 v[14:17], v[226:229], v[210:213], v[14:17]
	v_mfma_f32_16x16x32_bf16 v[10:13], v[234:237], v[210:213], v[10:13]
	v_mfma_f32_16x16x32_bf16 v[6:9], v[226:229], v[218:221], v[6:9]
	s_setprio 2
	s_barrier
	v_mfma_f32_16x16x32_bf16 v[2:5], v[234:237], v[218:221], v[2:5]
	s_setprio 0
	s_add_i32 s47, s47, 2
	s_add_u32 s64, s64, 0x100
	s_addc_u32 s65, s65, 0
	s_add_u32 s18, s18, 0x100
	s_addc_u32 s19, s19, 0
	s_cmp_gt_u32 s47, 29
	s_cbranch_scc0 .LBB0_1256
	s_lshl_b32 s4, s46, 8
	s_and_b32 s4, s4, 0x3f00
	v_add_u32_e32 v178, s4, v186
	s_ashr_i32 s4, s43, 31
	s_lshr_b32 s4, s4, 29
	s_add_i32 s4, s43, s4
	s_and_b32 s4, s4, 0xfffff8
	s_sub_i32 s4, s43, s4
	v_lshl_or_b32 v172, s4, 8, v188
	v_ashrrev_i32_e32 v173, 31, v172
	v_ashrrev_i32_e32 v179, 31, v178
	v_lshlrev_b32_e32 v170, 12, v178
	v_lshl_add_u32 v170, v172, 1, v170
	v_lshlrev_b32_e32 v171, 3, v178
	v_lshlrev_b32_e32 v174, 2, v172
	global_load_dwordx4 v[98:101], v174, s[12:13]
	global_load_dwordx4 v[90:93], v174, s[12:13] offset:16
	global_load_dwordx4 v[102:105], v174, s[14:15]
	global_load_dwordx4 v[94:97], v174, s[14:15] offset:16
	s_add_u32 s48, s82, 0x0
	s_addc_u32 s49, s83, 0
	global_load_dwordx4 v[220:223], v170, s[48:49]
	s_add_u32 s50, s10, 0x0
	s_addc_u32 s51, s11, 0
	global_load_dwordx2 v[176:177], v171, s[50:51]
	s_add_u32 s48, s82, 0x10000
	s_addc_u32 s49, s83, 0
	global_load_dwordx4 v[224:227], v170, s[48:49]
	s_add_u32 s50, s10, 0x80
	s_addc_u32 s51, s11, 0
	global_load_dwordx2 v[180:181], v171, s[50:51]
	s_add_u32 s48, s82, 0x20000
	s_addc_u32 s49, s83, 0
	global_load_dwordx4 v[228:231], v170, s[48:49]
	s_add_u32 s50, s10, 0x100
	s_addc_u32 s51, s11, 0
	global_load_dwordx2 v[182:183], v171, s[50:51]
	s_add_u32 s48, s82, 0x30000
	s_addc_u32 s49, s83, 0
	global_load_dwordx4 v[232:235], v170, s[48:49]
	s_add_u32 s50, s10, 0x180
	s_addc_u32 s51, s11, 0
	global_load_dwordx2 v[184:185], v171, s[50:51]
	s_add_u32 s48, s82, 0x80000
	s_addc_u32 s49, s83, 0
	global_load_dwordx4 v[236:239], v170, s[48:49]
	s_add_u32 s50, s10, 0x400
	s_addc_u32 s51, s11, 0
	global_load_dwordx2 v[168:169], v171, s[50:51]
	s_add_u32 s48, s82, 0x90000
	s_addc_u32 s49, s83, 0
	global_load_dwordx4 v[240:243], v170, s[48:49]
	s_add_u32 s50, s10, 0x480
	s_addc_u32 s51, s11, 0
	global_load_dwordx2 v[252:253], v171, s[50:51]
	s_add_u32 s48, s82, 0xa0000
	s_addc_u32 s49, s83, 0
	global_load_dwordx4 v[244:247], v170, s[48:49]
	s_add_u32 s50, s10, 0x500
	s_addc_u32 s51, s11, 0
	global_load_dwordx2 v[214:215], v171, s[50:51]
	s_add_u32 s48, s82, 0xb0000
	s_addc_u32 s49, s83, 0
	global_load_dwordx4 v[248:251], v170, s[48:49]
	s_add_u32 s50, s10, 0x580
	s_addc_u32 s51, s11, 0
	global_load_dwordx2 v[216:217], v171, s[50:51]
	s_waitcnt vmcnt(14)
	v_lshlrev_b32_e32 v206, 16, v220
	v_and_b32_e32 v207, 0xffff0000, v220
	v_lshlrev_b32_e32 v208, 16, v221
	v_and_b32_e32 v209, 0xffff0000, v221
	v_lshlrev_b32_e32 v210, 16, v222
	v_and_b32_e32 v211, 0xffff0000, v222
	v_lshlrev_b32_e32 v212, 16, v223
	v_and_b32_e32 v213, 0xffff0000, v223
	v_sub_f32_e32 v206, v206, v176
	v_sub_f32_e32 v207, v207, v176
	v_sub_f32_e32 v208, v208, v176
	v_sub_f32_e32 v209, v209, v176
	v_sub_f32_e32 v210, v210, v176
	v_sub_f32_e32 v211, v211, v176
	v_sub_f32_e32 v212, v212, v176
	v_sub_f32_e32 v213, v213, v176
	v_pk_mul_f32 v[206:207], v[176:177], v[206:207] op_sel:[1,0]
	v_pk_mul_f32 v[208:209], v[176:177], v[208:209] op_sel:[1,0]
	v_pk_mul_f32 v[210:211], v[176:177], v[210:211] op_sel:[1,0]
	v_pk_mul_f32 v[212:213], v[176:177], v[212:213] op_sel:[1,0]
	v_pk_fma_f32 v[206:207], v[98:99], v[206:207], v[102:103]
	v_pk_fma_f32 v[208:209], v[100:101], v[208:209], v[104:105]
	v_pk_fma_f32 v[210:211], v[90:91], v[210:211], v[94:95]
	v_pk_fma_f32 v[212:213], v[92:93], v[212:213], v[96:97]
	v_pk_fma_f32 v[206:207], v[206:207], s[66:67], v[142:143] op_sel_hi:[1,0,1]
	v_pk_fma_f32 v[208:209], v[208:209], s[66:67], v[144:145] op_sel_hi:[1,0,1]
	v_pk_fma_f32 v[210:211], v[210:211], s[66:67], v[138:139] op_sel_hi:[1,0,1]
	v_pk_fma_f32 v[212:213], v[212:213], s[66:67], v[140:141] op_sel_hi:[1,0,1]
	v_cvt_pk_bf16_f32 v220, v206, v207
	v_cvt_pk_bf16_f32 v221, v208, v209
	v_cvt_pk_bf16_f32 v222, v210, v211
	v_cvt_pk_bf16_f32 v223, v212, v213
	s_add_u32 s48, s82, 0x0
	s_addc_u32 s49, s83, 0
	global_store_dwordx4 v170, v[220:223], s[48:49]
	s_waitcnt vmcnt(13)
	v_lshlrev_b32_e32 v206, 16, v224
	v_and_b32_e32 v207, 0xffff0000, v224
	v_lshlrev_b32_e32 v208, 16, v225
	v_and_b32_e32 v209, 0xffff0000, v225
	v_lshlrev_b32_e32 v210, 16, v226
	v_and_b32_e32 v211, 0xffff0000, v226
	v_lshlrev_b32_e32 v212, 16, v227
	v_and_b32_e32 v213, 0xffff0000, v227
	v_sub_f32_e32 v206, v206, v180
	v_sub_f32_e32 v207, v207, v180
	v_sub_f32_e32 v208, v208, v180
	v_sub_f32_e32 v209, v209, v180
	v_sub_f32_e32 v210, v210, v180
	v_sub_f32_e32 v211, v211, v180
	v_sub_f32_e32 v212, v212, v180
	v_sub_f32_e32 v213, v213, v180
	v_pk_mul_f32 v[206:207], v[180:181], v[206:207] op_sel:[1,0]
	v_pk_mul_f32 v[208:209], v[180:181], v[208:209] op_sel:[1,0]
	v_pk_mul_f32 v[210:211], v[180:181], v[210:211] op_sel:[1,0]
	v_pk_mul_f32 v[212:213], v[180:181], v[212:213] op_sel:[1,0]
	v_pk_fma_f32 v[206:207], v[98:99], v[206:207], v[102:103]
	v_pk_fma_f32 v[208:209], v[100:101], v[208:209], v[104:105]
	v_pk_fma_f32 v[210:211], v[90:91], v[210:211], v[94:95]
	v_pk_fma_f32 v[212:213], v[92:93], v[212:213], v[96:97]
	v_pk_fma_f32 v[206:207], v[206:207], s[66:67], v[134:135] op_sel_hi:[1,0,1]
	v_pk_fma_f32 v[208:209], v[208:209], s[66:67], v[136:137] op_sel_hi:[1,0,1]
	v_pk_fma_f32 v[210:211], v[210:211], s[66:67], v[130:131] op_sel_hi:[1,0,1]
	v_pk_fma_f32 v[212:213], v[212:213], s[66:67], v[132:133] op_sel_hi:[1,0,1]
	v_cvt_pk_bf16_f32 v224, v206, v207
	v_cvt_pk_bf16_f32 v225, v208, v209
	v_cvt_pk_bf16_f32 v226, v210, v211
	v_cvt_pk_bf16_f32 v227, v212, v213
	s_add_u32 s48, s82, 0x10000
	s_addc_u32 s49, s83, 0
	global_store_dwordx4 v170, v[224:227], s[48:49]
	s_waitcnt vmcnt(12)
	v_lshlrev_b32_e32 v206, 16, v228
	v_and_b32_e32 v207, 0xffff0000, v228
	v_lshlrev_b32_e32 v208, 16, v229
	v_and_b32_e32 v209, 0xffff0000, v229
	v_lshlrev_b32_e32 v210, 16, v230
	v_and_b32_e32 v211, 0xffff0000, v230
	v_lshlrev_b32_e32 v212, 16, v231
	v_and_b32_e32 v213, 0xffff0000, v231
	v_sub_f32_e32 v206, v206, v182
	v_sub_f32_e32 v207, v207, v182
	v_sub_f32_e32 v208, v208, v182
	v_sub_f32_e32 v209, v209, v182
	v_sub_f32_e32 v210, v210, v182
	v_sub_f32_e32 v211, v211, v182
	v_sub_f32_e32 v212, v212, v182
	v_sub_f32_e32 v213, v213, v182
	v_pk_mul_f32 v[206:207], v[182:183], v[206:207] op_sel:[1,0]
	v_pk_mul_f32 v[208:209], v[182:183], v[208:209] op_sel:[1,0]
	v_pk_mul_f32 v[210:211], v[182:183], v[210:211] op_sel:[1,0]
	v_pk_mul_f32 v[212:213], v[182:183], v[212:213] op_sel:[1,0]
	v_pk_fma_f32 v[206:207], v[98:99], v[206:207], v[102:103]
	v_pk_fma_f32 v[208:209], v[100:101], v[208:209], v[104:105]
	v_pk_fma_f32 v[210:211], v[90:91], v[210:211], v[94:95]
	v_pk_fma_f32 v[212:213], v[92:93], v[212:213], v[96:97]
	v_pk_fma_f32 v[206:207], v[206:207], s[66:67], v[126:127] op_sel_hi:[1,0,1]
	v_pk_fma_f32 v[208:209], v[208:209], s[66:67], v[128:129] op_sel_hi:[1,0,1]
	v_pk_fma_f32 v[210:211], v[210:211], s[66:67], v[122:123] op_sel_hi:[1,0,1]
	v_pk_fma_f32 v[212:213], v[212:213], s[66:67], v[124:125] op_sel_hi:[1,0,1]
	v_cvt_pk_bf16_f32 v228, v206, v207
	v_cvt_pk_bf16_f32 v229, v208, v209
	v_cvt_pk_bf16_f32 v230, v210, v211
	v_cvt_pk_bf16_f32 v231, v212, v213
	s_add_u32 s48, s82, 0x20000
	s_addc_u32 s49, s83, 0
	global_store_dwordx4 v170, v[228:231], s[48:49]
	s_waitcnt vmcnt(11)
	v_lshlrev_b32_e32 v206, 16, v232
	v_and_b32_e32 v207, 0xffff0000, v232
	v_lshlrev_b32_e32 v208, 16, v233
	v_and_b32_e32 v209, 0xffff0000, v233
	v_lshlrev_b32_e32 v210, 16, v234
	v_and_b32_e32 v211, 0xffff0000, v234
	v_lshlrev_b32_e32 v212, 16, v235
	v_and_b32_e32 v213, 0xffff0000, v235
	v_sub_f32_e32 v206, v206, v184
	v_sub_f32_e32 v207, v207, v184
	v_sub_f32_e32 v208, v208, v184
	v_sub_f32_e32 v209, v209, v184
	v_sub_f32_e32 v210, v210, v184
	v_sub_f32_e32 v211, v211, v184
	v_sub_f32_e32 v212, v212, v184
	v_sub_f32_e32 v213, v213, v184
	v_pk_mul_f32 v[206:207], v[184:185], v[206:207] op_sel:[1,0]
	v_pk_mul_f32 v[208:209], v[184:185], v[208:209] op_sel:[1,0]
	v_pk_mul_f32 v[210:211], v[184:185], v[210:211] op_sel:[1,0]
	v_pk_mul_f32 v[212:213], v[184:185], v[212:213] op_sel:[1,0]
	v_pk_fma_f32 v[206:207], v[98:99], v[206:207], v[102:103]
	v_pk_fma_f32 v[208:209], v[100:101], v[208:209], v[104:105]
	v_pk_fma_f32 v[210:211], v[90:91], v[210:211], v[94:95]
	v_pk_fma_f32 v[212:213], v[92:93], v[212:213], v[96:97]
	v_pk_fma_f32 v[206:207], v[206:207], s[66:67], v[118:119] op_sel_hi:[1,0,1]
	v_pk_fma_f32 v[208:209], v[208:209], s[66:67], v[120:121] op_sel_hi:[1,0,1]
	v_pk_fma_f32 v[210:211], v[210:211], s[66:67], v[114:115] op_sel_hi:[1,0,1]
	v_pk_fma_f32 v[212:213], v[212:213], s[66:67], v[116:117] op_sel_hi:[1,0,1]
	v_cvt_pk_bf16_f32 v232, v206, v207
	v_cvt_pk_bf16_f32 v233, v208, v209
	v_cvt_pk_bf16_f32 v234, v210, v211
	v_cvt_pk_bf16_f32 v235, v212, v213
	s_add_u32 s48, s82, 0x30000
	s_addc_u32 s49, s83, 0
	global_store_dwordx4 v170, v[232:235], s[48:49]
	s_waitcnt vmcnt(10)
	v_lshlrev_b32_e32 v206, 16, v236
	v_and_b32_e32 v207, 0xffff0000, v236
	v_lshlrev_b32_e32 v208, 16, v237
	v_and_b32_e32 v209, 0xffff0000, v237
	v_lshlrev_b32_e32 v210, 16, v238
	v_and_b32_e32 v211, 0xffff0000, v238
	v_lshlrev_b32_e32 v212, 16, v239
	v_and_b32_e32 v213, 0xffff0000, v239
	v_sub_f32_e32 v206, v206, v168
	v_sub_f32_e32 v207, v207, v168
	v_sub_f32_e32 v208, v208, v168
	v_sub_f32_e32 v209, v209, v168
	v_sub_f32_e32 v210, v210, v168
	v_sub_f32_e32 v211, v211, v168
	v_sub_f32_e32 v212, v212, v168
	v_sub_f32_e32 v213, v213, v168
	v_pk_mul_f32 v[206:207], v[168:169], v[206:207] op_sel:[1,0]
	v_pk_mul_f32 v[208:209], v[168:169], v[208:209] op_sel:[1,0]
	v_pk_mul_f32 v[210:211], v[168:169], v[210:211] op_sel:[1,0]
	v_pk_mul_f32 v[212:213], v[168:169], v[212:213] op_sel:[1,0]
	v_pk_fma_f32 v[206:207], v[98:99], v[206:207], v[102:103]
	v_pk_fma_f32 v[208:209], v[100:101], v[208:209], v[104:105]
	v_pk_fma_f32 v[210:211], v[90:91], v[210:211], v[94:95]
	v_pk_fma_f32 v[212:213], v[92:93], v[212:213], v[96:97]
	v_pk_fma_f32 v[206:207], v[206:207], s[66:67], v[110:111] op_sel_hi:[1,0,1]
	v_pk_fma_f32 v[208:209], v[208:209], s[66:67], v[112:113] op_sel_hi:[1,0,1]
	v_pk_fma_f32 v[210:211], v[210:211], s[66:67], v[106:107] op_sel_hi:[1,0,1]
	v_pk_fma_f32 v[212:213], v[212:213], s[66:67], v[108:109] op_sel_hi:[1,0,1]
	v_cvt_pk_bf16_f32 v236, v206, v207
	v_cvt_pk_bf16_f32 v237, v208, v209
	v_cvt_pk_bf16_f32 v238, v210, v211
	v_cvt_pk_bf16_f32 v239, v212, v213
	s_add_u32 s48, s82, 0x80000
	s_addc_u32 s49, s83, 0
	global_store_dwordx4 v170, v[236:239], s[48:49]
	s_waitcnt vmcnt(9)
	v_lshlrev_b32_e32 v206, 16, v240
	v_and_b32_e32 v207, 0xffff0000, v240
	v_lshlrev_b32_e32 v208, 16, v241
	v_and_b32_e32 v209, 0xffff0000, v241
	v_lshlrev_b32_e32 v210, 16, v242
	v_and_b32_e32 v211, 0xffff0000, v242
	v_lshlrev_b32_e32 v212, 16, v243
	v_and_b32_e32 v213, 0xffff0000, v243
	v_sub_f32_e32 v206, v206, v252
	v_sub_f32_e32 v207, v207, v252
	v_sub_f32_e32 v208, v208, v252
	v_sub_f32_e32 v209, v209, v252
	v_sub_f32_e32 v210, v210, v252
	v_sub_f32_e32 v211, v211, v252
	v_sub_f32_e32 v212, v212, v252
	v_sub_f32_e32 v213, v213, v252
	v_pk_mul_f32 v[206:207], v[252:253], v[206:207] op_sel:[1,0]
	v_pk_mul_f32 v[208:209], v[252:253], v[208:209] op_sel:[1,0]
	v_pk_mul_f32 v[210:211], v[252:253], v[210:211] op_sel:[1,0]
	v_pk_mul_f32 v[212:213], v[252:253], v[212:213] op_sel:[1,0]
	v_pk_fma_f32 v[206:207], v[98:99], v[206:207], v[102:103]
	v_pk_fma_f32 v[208:209], v[100:101], v[208:209], v[104:105]
	v_pk_fma_f32 v[210:211], v[90:91], v[210:211], v[94:95]
	v_pk_fma_f32 v[212:213], v[92:93], v[212:213], v[96:97]
	v_pk_fma_f32 v[206:207], v[206:207], s[66:67], v[86:87] op_sel_hi:[1,0,1]
	v_pk_fma_f32 v[208:209], v[208:209], s[66:67], v[88:89] op_sel_hi:[1,0,1]
	v_pk_fma_f32 v[210:211], v[210:211], s[66:67], v[82:83] op_sel_hi:[1,0,1]
	v_pk_fma_f32 v[212:213], v[212:213], s[66:67], v[84:85] op_sel_hi:[1,0,1]
	v_cvt_pk_bf16_f32 v240, v206, v207
	v_cvt_pk_bf16_f32 v241, v208, v209
	v_cvt_pk_bf16_f32 v242, v210, v211
	v_cvt_pk_bf16_f32 v243, v212, v213
	s_add_u32 s48, s82, 0x90000
	s_addc_u32 s49, s83, 0
	global_store_dwordx4 v170, v[240:243], s[48:49]
	s_waitcnt vmcnt(8)
	v_lshlrev_b32_e32 v206, 16, v244
	v_and_b32_e32 v207, 0xffff0000, v244
	v_lshlrev_b32_e32 v208, 16, v245
	v_and_b32_e32 v209, 0xffff0000, v245
	v_lshlrev_b32_e32 v210, 16, v246
	v_and_b32_e32 v211, 0xffff0000, v246
	v_lshlrev_b32_e32 v212, 16, v247
	v_and_b32_e32 v213, 0xffff0000, v247
	v_sub_f32_e32 v206, v206, v214
	v_sub_f32_e32 v207, v207, v214
	v_sub_f32_e32 v208, v208, v214
	v_sub_f32_e32 v209, v209, v214
	v_sub_f32_e32 v210, v210, v214
	v_sub_f32_e32 v211, v211, v214
	v_sub_f32_e32 v212, v212, v214
	v_sub_f32_e32 v213, v213, v214
	v_pk_mul_f32 v[206:207], v[214:215], v[206:207] op_sel:[1,0]
	v_pk_mul_f32 v[208:209], v[214:215], v[208:209] op_sel:[1,0]
	v_pk_mul_f32 v[210:211], v[214:215], v[210:211] op_sel:[1,0]
	v_pk_mul_f32 v[212:213], v[214:215], v[212:213] op_sel:[1,0]
	v_pk_fma_f32 v[206:207], v[98:99], v[206:207], v[102:103]
	v_pk_fma_f32 v[208:209], v[100:101], v[208:209], v[104:105]
	v_pk_fma_f32 v[210:211], v[90:91], v[210:211], v[94:95]
	v_pk_fma_f32 v[212:213], v[92:93], v[212:213], v[96:97]
	v_pk_fma_f32 v[206:207], v[206:207], s[66:67], v[78:79] op_sel_hi:[1,0,1]
	v_pk_fma_f32 v[208:209], v[208:209], s[66:67], v[80:81] op_sel_hi:[1,0,1]
	v_pk_fma_f32 v[210:211], v[210:211], s[66:67], v[74:75] op_sel_hi:[1,0,1]
	v_pk_fma_f32 v[212:213], v[212:213], s[66:67], v[76:77] op_sel_hi:[1,0,1]
	v_cvt_pk_bf16_f32 v244, v206, v207
	v_cvt_pk_bf16_f32 v245, v208, v209
	v_cvt_pk_bf16_f32 v246, v210, v211
	v_cvt_pk_bf16_f32 v247, v212, v213
	s_add_u32 s48, s82, 0xa0000
	s_addc_u32 s49, s83, 0
	global_store_dwordx4 v170, v[244:247], s[48:49]
	s_waitcnt vmcnt(7)
	v_lshlrev_b32_e32 v206, 16, v248
	v_and_b32_e32 v207, 0xffff0000, v248
	v_lshlrev_b32_e32 v208, 16, v249
	v_and_b32_e32 v209, 0xffff0000, v249
	v_lshlrev_b32_e32 v210, 16, v250
	v_and_b32_e32 v211, 0xffff0000, v250
	v_lshlrev_b32_e32 v212, 16, v251
	v_and_b32_e32 v213, 0xffff0000, v251
	v_sub_f32_e32 v206, v206, v216
	v_sub_f32_e32 v207, v207, v216
	v_sub_f32_e32 v208, v208, v216
	v_sub_f32_e32 v209, v209, v216
	v_sub_f32_e32 v210, v210, v216
	v_sub_f32_e32 v211, v211, v216
	v_sub_f32_e32 v212, v212, v216
	v_sub_f32_e32 v213, v213, v216
	v_pk_mul_f32 v[206:207], v[216:217], v[206:207] op_sel:[1,0]
	v_pk_mul_f32 v[208:209], v[216:217], v[208:209] op_sel:[1,0]
	v_pk_mul_f32 v[210:211], v[216:217], v[210:211] op_sel:[1,0]
	v_pk_mul_f32 v[212:213], v[216:217], v[212:213] op_sel:[1,0]
	v_pk_fma_f32 v[206:207], v[98:99], v[206:207], v[102:103]
	v_pk_fma_f32 v[208:209], v[100:101], v[208:209], v[104:105]
	v_pk_fma_f32 v[210:211], v[90:91], v[210:211], v[94:95]
	v_pk_fma_f32 v[212:213], v[92:93], v[212:213], v[96:97]
	v_pk_fma_f32 v[206:207], v[206:207], s[66:67], v[70:71] op_sel_hi:[1,0,1]
	v_pk_fma_f32 v[208:209], v[208:209], s[66:67], v[72:73] op_sel_hi:[1,0,1]
	v_pk_fma_f32 v[210:211], v[210:211], s[66:67], v[66:67] op_sel_hi:[1,0,1]
	v_pk_fma_f32 v[212:213], v[212:213], s[66:67], v[68:69] op_sel_hi:[1,0,1]
	v_cvt_pk_bf16_f32 v248, v206, v207
	v_cvt_pk_bf16_f32 v249, v208, v209
	v_cvt_pk_bf16_f32 v250, v210, v211
	v_cvt_pk_bf16_f32 v251, v212, v213
	s_add_u32 s48, s82, 0xb0000
	s_addc_u32 s49, s83, 0
	global_store_dwordx4 v170, v[248:251], s[48:49]
	global_load_dwordx4 v[98:101], v174, s[12:13] offset:512
	global_load_dwordx4 v[90:93], v174, s[12:13] offset:528
	global_load_dwordx4 v[102:105], v174, s[14:15] offset:512
	global_load_dwordx4 v[94:97], v174, s[14:15] offset:528
	s_add_u32 s48, s82, 0x100
	s_addc_u32 s49, s83, 0
	global_load_dwordx4 v[220:223], v170, s[48:49]
	s_add_u32 s50, s10, 0x0
	s_addc_u32 s51, s11, 0
	global_load_dwordx2 v[176:177], v171, s[50:51]
	s_add_u32 s48, s82, 0x10100
	s_addc_u32 s49, s83, 0
	global_load_dwordx4 v[224:227], v170, s[48:49]
	s_add_u32 s50, s10, 0x80
	s_addc_u32 s51, s11, 0
	global_load_dwordx2 v[180:181], v171, s[50:51]
	s_add_u32 s48, s82, 0x20100
	s_addc_u32 s49, s83, 0
	global_load_dwordx4 v[228:231], v170, s[48:49]
	s_add_u32 s50, s10, 0x100
	s_addc_u32 s51, s11, 0
	global_load_dwordx2 v[182:183], v171, s[50:51]
	s_add_u32 s48, s82, 0x30100
	s_addc_u32 s49, s83, 0
	global_load_dwordx4 v[232:235], v170, s[48:49]
	s_add_u32 s50, s10, 0x180
	s_addc_u32 s51, s11, 0
	global_load_dwordx2 v[184:185], v171, s[50:51]
	s_add_u32 s48, s82, 0x80100
	s_addc_u32 s49, s83, 0
	global_load_dwordx4 v[236:239], v170, s[48:49]
	s_add_u32 s50, s10, 0x400
	s_addc_u32 s51, s11, 0
	global_load_dwordx2 v[168:169], v171, s[50:51]
	s_add_u32 s48, s82, 0x90100
	s_addc_u32 s49, s83, 0
	global_load_dwordx4 v[240:243], v170, s[48:49]
	s_add_u32 s50, s10, 0x480
	s_addc_u32 s51, s11, 0
	global_load_dwordx2 v[252:253], v171, s[50:51]
	s_add_u32 s48, s82, 0xa0100
	s_addc_u32 s49, s83, 0
	global_load_dwordx4 v[244:247], v170, s[48:49]
	s_add_u32 s50, s10, 0x500
	s_addc_u32 s51, s11, 0
	global_load_dwordx2 v[214:215], v171, s[50:51]
	s_add_u32 s48, s82, 0xb0100
	s_addc_u32 s49, s83, 0
	global_load_dwordx4 v[248:251], v170, s[48:49]
	s_add_u32 s50, s10, 0x580
	s_addc_u32 s51, s11, 0
	global_load_dwordx2 v[216:217], v171, s[50:51]
	s_waitcnt vmcnt(14)
	v_lshlrev_b32_e32 v206, 16, v220
	v_and_b32_e32 v207, 0xffff0000, v220
	v_lshlrev_b32_e32 v208, 16, v221
	v_and_b32_e32 v209, 0xffff0000, v221
	v_lshlrev_b32_e32 v210, 16, v222
	v_and_b32_e32 v211, 0xffff0000, v222
	v_lshlrev_b32_e32 v212, 16, v223
	v_and_b32_e32 v213, 0xffff0000, v223
	v_sub_f32_e32 v206, v206, v176
	v_sub_f32_e32 v207, v207, v176
	v_sub_f32_e32 v208, v208, v176
	v_sub_f32_e32 v209, v209, v176
	v_sub_f32_e32 v210, v210, v176
	v_sub_f32_e32 v211, v211, v176
	v_sub_f32_e32 v212, v212, v176
	v_sub_f32_e32 v213, v213, v176
	v_pk_mul_f32 v[206:207], v[176:177], v[206:207] op_sel:[1,0]
	v_pk_mul_f32 v[208:209], v[176:177], v[208:209] op_sel:[1,0]
	v_pk_mul_f32 v[210:211], v[176:177], v[210:211] op_sel:[1,0]
	v_pk_mul_f32 v[212:213], v[176:177], v[212:213] op_sel:[1,0]
	v_pk_fma_f32 v[206:207], v[98:99], v[206:207], v[102:103]
	v_pk_fma_f32 v[208:209], v[100:101], v[208:209], v[104:105]
	v_pk_fma_f32 v[210:211], v[90:91], v[210:211], v[94:95]
	v_pk_fma_f32 v[212:213], v[92:93], v[212:213], v[96:97]
	v_pk_fma_f32 v[206:207], v[206:207], s[66:67], v[62:63] op_sel_hi:[1,0,1]
	v_pk_fma_f32 v[208:209], v[208:209], s[66:67], v[64:65] op_sel_hi:[1,0,1]
	v_pk_fma_f32 v[210:211], v[210:211], s[66:67], v[58:59] op_sel_hi:[1,0,1]
	v_pk_fma_f32 v[212:213], v[212:213], s[66:67], v[60:61] op_sel_hi:[1,0,1]
	v_cvt_pk_bf16_f32 v220, v206, v207
	v_cvt_pk_bf16_f32 v221, v208, v209
	v_cvt_pk_bf16_f32 v222, v210, v211
	v_cvt_pk_bf16_f32 v223, v212, v213
	s_add_u32 s48, s82, 0x100
	s_addc_u32 s49, s83, 0
	global_store_dwordx4 v170, v[220:223], s[48:49]
	s_waitcnt vmcnt(13)
	v_lshlrev_b32_e32 v206, 16, v224
	v_and_b32_e32 v207, 0xffff0000, v224
	v_lshlrev_b32_e32 v208, 16, v225
	v_and_b32_e32 v209, 0xffff0000, v225
	v_lshlrev_b32_e32 v210, 16, v226
	v_and_b32_e32 v211, 0xffff0000, v226
	v_lshlrev_b32_e32 v212, 16, v227
	v_and_b32_e32 v213, 0xffff0000, v227
	v_sub_f32_e32 v206, v206, v180
	v_sub_f32_e32 v207, v207, v180
	v_sub_f32_e32 v208, v208, v180
	v_sub_f32_e32 v209, v209, v180
	v_sub_f32_e32 v210, v210, v180
	v_sub_f32_e32 v211, v211, v180
	v_sub_f32_e32 v212, v212, v180
	v_sub_f32_e32 v213, v213, v180
	v_pk_mul_f32 v[206:207], v[180:181], v[206:207] op_sel:[1,0]
	v_pk_mul_f32 v[208:209], v[180:181], v[208:209] op_sel:[1,0]
	v_pk_mul_f32 v[210:211], v[180:181], v[210:211] op_sel:[1,0]
	v_pk_mul_f32 v[212:213], v[180:181], v[212:213] op_sel:[1,0]
	v_pk_fma_f32 v[206:207], v[98:99], v[206:207], v[102:103]
	v_pk_fma_f32 v[208:209], v[100:101], v[208:209], v[104:105]
	v_pk_fma_f32 v[210:211], v[90:91], v[210:211], v[94:95]
	v_pk_fma_f32 v[212:213], v[92:93], v[212:213], v[96:97]
	v_pk_fma_f32 v[206:207], v[206:207], s[66:67], v[54:55] op_sel_hi:[1,0,1]
	v_pk_fma_f32 v[208:209], v[208:209], s[66:67], v[56:57] op_sel_hi:[1,0,1]
	v_pk_fma_f32 v[210:211], v[210:211], s[66:67], v[50:51] op_sel_hi:[1,0,1]
	v_pk_fma_f32 v[212:213], v[212:213], s[66:67], v[52:53] op_sel_hi:[1,0,1]
	v_cvt_pk_bf16_f32 v224, v206, v207
	v_cvt_pk_bf16_f32 v225, v208, v209
	v_cvt_pk_bf16_f32 v226, v210, v211
	v_cvt_pk_bf16_f32 v227, v212, v213
	s_add_u32 s48, s82, 0x10100
	s_addc_u32 s49, s83, 0
	global_store_dwordx4 v170, v[224:227], s[48:49]
	s_waitcnt vmcnt(12)
	v_lshlrev_b32_e32 v206, 16, v228
	v_and_b32_e32 v207, 0xffff0000, v228
	v_lshlrev_b32_e32 v208, 16, v229
	v_and_b32_e32 v209, 0xffff0000, v229
	v_lshlrev_b32_e32 v210, 16, v230
	v_and_b32_e32 v211, 0xffff0000, v230
	v_lshlrev_b32_e32 v212, 16, v231
	v_and_b32_e32 v213, 0xffff0000, v231
	v_sub_f32_e32 v206, v206, v182
	v_sub_f32_e32 v207, v207, v182
	v_sub_f32_e32 v208, v208, v182
	v_sub_f32_e32 v209, v209, v182
	v_sub_f32_e32 v210, v210, v182
	v_sub_f32_e32 v211, v211, v182
	v_sub_f32_e32 v212, v212, v182
	v_sub_f32_e32 v213, v213, v182
	v_pk_mul_f32 v[206:207], v[182:183], v[206:207] op_sel:[1,0]
	v_pk_mul_f32 v[208:209], v[182:183], v[208:209] op_sel:[1,0]
	v_pk_mul_f32 v[210:211], v[182:183], v[210:211] op_sel:[1,0]
	v_pk_mul_f32 v[212:213], v[182:183], v[212:213] op_sel:[1,0]
	v_pk_fma_f32 v[206:207], v[98:99], v[206:207], v[102:103]
	v_pk_fma_f32 v[208:209], v[100:101], v[208:209], v[104:105]
	v_pk_fma_f32 v[210:211], v[90:91], v[210:211], v[94:95]
	v_pk_fma_f32 v[212:213], v[92:93], v[212:213], v[96:97]
	v_pk_fma_f32 v[206:207], v[206:207], s[66:67], v[46:47] op_sel_hi:[1,0,1]
	v_pk_fma_f32 v[208:209], v[208:209], s[66:67], v[48:49] op_sel_hi:[1,0,1]
	v_pk_fma_f32 v[210:211], v[210:211], s[66:67], v[42:43] op_sel_hi:[1,0,1]
	v_pk_fma_f32 v[212:213], v[212:213], s[66:67], v[44:45] op_sel_hi:[1,0,1]
	v_cvt_pk_bf16_f32 v228, v206, v207
	v_cvt_pk_bf16_f32 v229, v208, v209
	v_cvt_pk_bf16_f32 v230, v210, v211
	v_cvt_pk_bf16_f32 v231, v212, v213
	s_add_u32 s48, s82, 0x20100
	s_addc_u32 s49, s83, 0
	global_store_dwordx4 v170, v[228:231], s[48:49]
	s_waitcnt vmcnt(11)
	v_lshlrev_b32_e32 v206, 16, v232
	v_and_b32_e32 v207, 0xffff0000, v232
	v_lshlrev_b32_e32 v208, 16, v233
	v_and_b32_e32 v209, 0xffff0000, v233
	v_lshlrev_b32_e32 v210, 16, v234
	v_and_b32_e32 v211, 0xffff0000, v234
	v_lshlrev_b32_e32 v212, 16, v235
	v_and_b32_e32 v213, 0xffff0000, v235
	v_sub_f32_e32 v206, v206, v184
	v_sub_f32_e32 v207, v207, v184
	v_sub_f32_e32 v208, v208, v184
	v_sub_f32_e32 v209, v209, v184
	v_sub_f32_e32 v210, v210, v184
	v_sub_f32_e32 v211, v211, v184
	v_sub_f32_e32 v212, v212, v184
	v_sub_f32_e32 v213, v213, v184
	v_pk_mul_f32 v[206:207], v[184:185], v[206:207] op_sel:[1,0]
	v_pk_mul_f32 v[208:209], v[184:185], v[208:209] op_sel:[1,0]
	v_pk_mul_f32 v[210:211], v[184:185], v[210:211] op_sel:[1,0]
	v_pk_mul_f32 v[212:213], v[184:185], v[212:213] op_sel:[1,0]
	v_pk_fma_f32 v[206:207], v[98:99], v[206:207], v[102:103]
	v_pk_fma_f32 v[208:209], v[100:101], v[208:209], v[104:105]
	v_pk_fma_f32 v[210:211], v[90:91], v[210:211], v[94:95]
	v_pk_fma_f32 v[212:213], v[92:93], v[212:213], v[96:97]
	v_pk_fma_f32 v[206:207], v[206:207], s[66:67], v[38:39] op_sel_hi:[1,0,1]
	v_pk_fma_f32 v[208:209], v[208:209], s[66:67], v[40:41] op_sel_hi:[1,0,1]
	v_pk_fma_f32 v[210:211], v[210:211], s[66:67], v[34:35] op_sel_hi:[1,0,1]
	v_pk_fma_f32 v[212:213], v[212:213], s[66:67], v[36:37] op_sel_hi:[1,0,1]
	v_cvt_pk_bf16_f32 v232, v206, v207
	v_cvt_pk_bf16_f32 v233, v208, v209
	v_cvt_pk_bf16_f32 v234, v210, v211
	v_cvt_pk_bf16_f32 v235, v212, v213
	s_add_u32 s48, s82, 0x30100
	s_addc_u32 s49, s83, 0
	global_store_dwordx4 v170, v[232:235], s[48:49]
	s_waitcnt vmcnt(10)
	v_lshlrev_b32_e32 v206, 16, v236
	v_and_b32_e32 v207, 0xffff0000, v236
	v_lshlrev_b32_e32 v208, 16, v237
	v_and_b32_e32 v209, 0xffff0000, v237
	v_lshlrev_b32_e32 v210, 16, v238
	v_and_b32_e32 v211, 0xffff0000, v238
	v_lshlrev_b32_e32 v212, 16, v239
	v_and_b32_e32 v213, 0xffff0000, v239
	v_sub_f32_e32 v206, v206, v168
	v_sub_f32_e32 v207, v207, v168
	v_sub_f32_e32 v208, v208, v168
	v_sub_f32_e32 v209, v209, v168
	v_sub_f32_e32 v210, v210, v168
	v_sub_f32_e32 v211, v211, v168
	v_sub_f32_e32 v212, v212, v168
	v_sub_f32_e32 v213, v213, v168
	v_pk_mul_f32 v[206:207], v[168:169], v[206:207] op_sel:[1,0]
	v_pk_mul_f32 v[208:209], v[168:169], v[208:209] op_sel:[1,0]
	v_pk_mul_f32 v[210:211], v[168:169], v[210:211] op_sel:[1,0]
	v_pk_mul_f32 v[212:213], v[168:169], v[212:213] op_sel:[1,0]
	v_pk_fma_f32 v[206:207], v[98:99], v[206:207], v[102:103]
	v_pk_fma_f32 v[208:209], v[100:101], v[208:209], v[104:105]
	v_pk_fma_f32 v[210:211], v[90:91], v[210:211], v[94:95]
	v_pk_fma_f32 v[212:213], v[92:93], v[212:213], v[96:97]
	v_pk_fma_f32 v[206:207], v[206:207], s[66:67], v[30:31] op_sel_hi:[1,0,1]
	v_pk_fma_f32 v[208:209], v[208:209], s[66:67], v[32:33] op_sel_hi:[1,0,1]
	v_pk_fma_f32 v[210:211], v[210:211], s[66:67], v[26:27] op_sel_hi:[1,0,1]
	v_pk_fma_f32 v[212:213], v[212:213], s[66:67], v[28:29] op_sel_hi:[1,0,1]
	v_cvt_pk_bf16_f32 v236, v206, v207
	v_cvt_pk_bf16_f32 v237, v208, v209
	v_cvt_pk_bf16_f32 v238, v210, v211
	v_cvt_pk_bf16_f32 v239, v212, v213
	s_add_u32 s48, s82, 0x80100
	s_addc_u32 s49, s83, 0
	global_store_dwordx4 v170, v[236:239], s[48:49]
	s_waitcnt vmcnt(9)
	v_lshlrev_b32_e32 v206, 16, v240
	v_and_b32_e32 v207, 0xffff0000, v240
	v_lshlrev_b32_e32 v208, 16, v241
	v_and_b32_e32 v209, 0xffff0000, v241
	v_lshlrev_b32_e32 v210, 16, v242
	v_and_b32_e32 v211, 0xffff0000, v242
	v_lshlrev_b32_e32 v212, 16, v243
	v_and_b32_e32 v213, 0xffff0000, v243
	v_sub_f32_e32 v206, v206, v252
	v_sub_f32_e32 v207, v207, v252
	v_sub_f32_e32 v208, v208, v252
	v_sub_f32_e32 v209, v209, v252
	v_sub_f32_e32 v210, v210, v252
	v_sub_f32_e32 v211, v211, v252
	v_sub_f32_e32 v212, v212, v252
	v_sub_f32_e32 v213, v213, v252
	v_pk_mul_f32 v[206:207], v[252:253], v[206:207] op_sel:[1,0]
	v_pk_mul_f32 v[208:209], v[252:253], v[208:209] op_sel:[1,0]
	v_pk_mul_f32 v[210:211], v[252:253], v[210:211] op_sel:[1,0]
	v_pk_mul_f32 v[212:213], v[252:253], v[212:213] op_sel:[1,0]
	v_pk_fma_f32 v[206:207], v[98:99], v[206:207], v[102:103]
	v_pk_fma_f32 v[208:209], v[100:101], v[208:209], v[104:105]
	v_pk_fma_f32 v[210:211], v[90:91], v[210:211], v[94:95]
	v_pk_fma_f32 v[212:213], v[92:93], v[212:213], v[96:97]
	v_pk_fma_f32 v[206:207], v[206:207], s[66:67], v[22:23] op_sel_hi:[1,0,1]
	v_pk_fma_f32 v[208:209], v[208:209], s[66:67], v[24:25] op_sel_hi:[1,0,1]
	v_pk_fma_f32 v[210:211], v[210:211], s[66:67], v[18:19] op_sel_hi:[1,0,1]
	v_pk_fma_f32 v[212:213], v[212:213], s[66:67], v[20:21] op_sel_hi:[1,0,1]
	v_cvt_pk_bf16_f32 v240, v206, v207
	v_cvt_pk_bf16_f32 v241, v208, v209
	v_cvt_pk_bf16_f32 v242, v210, v211
	v_cvt_pk_bf16_f32 v243, v212, v213
	s_add_u32 s48, s82, 0x90100
	s_addc_u32 s49, s83, 0
	global_store_dwordx4 v170, v[240:243], s[48:49]
	s_waitcnt vmcnt(8)
	v_lshlrev_b32_e32 v206, 16, v244
	v_and_b32_e32 v207, 0xffff0000, v244
	v_lshlrev_b32_e32 v208, 16, v245
	v_and_b32_e32 v209, 0xffff0000, v245
	v_lshlrev_b32_e32 v210, 16, v246
	v_and_b32_e32 v211, 0xffff0000, v246
	v_lshlrev_b32_e32 v212, 16, v247
	v_and_b32_e32 v213, 0xffff0000, v247
	v_sub_f32_e32 v206, v206, v214
	v_sub_f32_e32 v207, v207, v214
	v_sub_f32_e32 v208, v208, v214
	v_sub_f32_e32 v209, v209, v214
	v_sub_f32_e32 v210, v210, v214
	v_sub_f32_e32 v211, v211, v214
	v_sub_f32_e32 v212, v212, v214
	v_sub_f32_e32 v213, v213, v214
	v_pk_mul_f32 v[206:207], v[214:215], v[206:207] op_sel:[1,0]
	v_pk_mul_f32 v[208:209], v[214:215], v[208:209] op_sel:[1,0]
	v_pk_mul_f32 v[210:211], v[214:215], v[210:211] op_sel:[1,0]
	v_pk_mul_f32 v[212:213], v[214:215], v[212:213] op_sel:[1,0]
	v_pk_fma_f32 v[206:207], v[98:99], v[206:207], v[102:103]
	v_pk_fma_f32 v[208:209], v[100:101], v[208:209], v[104:105]
	v_pk_fma_f32 v[210:211], v[90:91], v[210:211], v[94:95]
	v_pk_fma_f32 v[212:213], v[92:93], v[212:213], v[96:97]
	v_pk_fma_f32 v[206:207], v[206:207], s[66:67], v[14:15] op_sel_hi:[1,0,1]
	v_pk_fma_f32 v[208:209], v[208:209], s[66:67], v[16:17] op_sel_hi:[1,0,1]
	v_pk_fma_f32 v[210:211], v[210:211], s[66:67], v[10:11] op_sel_hi:[1,0,1]
	v_pk_fma_f32 v[212:213], v[212:213], s[66:67], v[12:13] op_sel_hi:[1,0,1]
	v_cvt_pk_bf16_f32 v244, v206, v207
	v_cvt_pk_bf16_f32 v245, v208, v209
	v_cvt_pk_bf16_f32 v246, v210, v211
	v_cvt_pk_bf16_f32 v247, v212, v213
	s_add_u32 s48, s82, 0xa0100
	s_addc_u32 s49, s83, 0
	global_store_dwordx4 v170, v[244:247], s[48:49]
	s_waitcnt vmcnt(7)
	v_lshlrev_b32_e32 v206, 16, v248
	v_and_b32_e32 v207, 0xffff0000, v248
	v_lshlrev_b32_e32 v208, 16, v249
	v_and_b32_e32 v209, 0xffff0000, v249
	v_lshlrev_b32_e32 v210, 16, v250
	v_and_b32_e32 v211, 0xffff0000, v250
	v_lshlrev_b32_e32 v212, 16, v251
	v_and_b32_e32 v213, 0xffff0000, v251
	v_sub_f32_e32 v206, v206, v216
	v_sub_f32_e32 v207, v207, v216
	v_sub_f32_e32 v208, v208, v216
	v_sub_f32_e32 v209, v209, v216
	v_sub_f32_e32 v210, v210, v216
	v_sub_f32_e32 v211, v211, v216
	v_sub_f32_e32 v212, v212, v216
	v_sub_f32_e32 v213, v213, v216
	v_pk_mul_f32 v[206:207], v[216:217], v[206:207] op_sel:[1,0]
	v_pk_mul_f32 v[208:209], v[216:217], v[208:209] op_sel:[1,0]
	v_pk_mul_f32 v[210:211], v[216:217], v[210:211] op_sel:[1,0]
	v_pk_mul_f32 v[212:213], v[216:217], v[212:213] op_sel:[1,0]
	v_pk_fma_f32 v[206:207], v[98:99], v[206:207], v[102:103]
	v_pk_fma_f32 v[208:209], v[100:101], v[208:209], v[104:105]
	v_pk_fma_f32 v[210:211], v[90:91], v[210:211], v[94:95]
	v_pk_fma_f32 v[212:213], v[92:93], v[212:213], v[96:97]
	v_pk_fma_f32 v[206:207], v[206:207], s[66:67], v[6:7] op_sel_hi:[1,0,1]
	v_pk_fma_f32 v[208:209], v[208:209], s[66:67], v[8:9] op_sel_hi:[1,0,1]
	v_pk_fma_f32 v[210:211], v[210:211], s[66:67], v[2:3] op_sel_hi:[1,0,1]
	v_pk_fma_f32 v[212:213], v[212:213], s[66:67], v[4:5] op_sel_hi:[1,0,1]
	v_cvt_pk_bf16_f32 v248, v206, v207
	v_cvt_pk_bf16_f32 v249, v208, v209
	v_cvt_pk_bf16_f32 v250, v210, v211
	v_cvt_pk_bf16_f32 v251, v212, v213
	s_add_u32 s48, s82, 0xb0100
	s_addc_u32 s49, s83, 0
	global_store_dwordx4 v170, v[248:251], s[48:49]
	s_and_b64 vcc, exec, s[8:9]
	s_mov_b32 s43, s86
	s_mov_b32 s46, s84
	s_mov_b64 s[68:69], s[90:91]
	s_mov_b64 s[64:65], s[88:89]
	s_cbranch_vccz .LBB0_1249
	s_waitcnt vmcnt(0)
	v_readlane_b32 s86, v254, 39
	s_cmpk_gt_u32 s21, 0xff
	s_mov_b32 s84, 0xf800000
	s_mov_b32 s85, 0x100000
	v_readlane_b32 s87, v254, 40
	s_cbranch_scc1 .LBB0_1260
	s_barrier

.LBB0_1420:
	s_add_u32 s44, s92, 0xfff80080
	s_addc_u32 s45, s93, -1
	s_add_i32 s52, 0, 0x10000
	v_add_u32_e32 v126, s52, v205
	ds_read_b128 v[114:117], v126
	ds_read_b128 v[118:121], v126 offset:1024
	ds_read_b128 v[122:125], v126 offset:2048
	ds_read_b128 v[126:129], v126 offset:3072
	s_cmp_eq_u32 s51, 28
	s_cselect_b32 s95, s6, s45
	s_cselect_b32 s94, s7, s44
	s_cselect_b32 s45, s18, s50
	s_cselect_b32 s44, s19, s49
	v_lshl_add_u64 v[188:189], s[92:93], 0, v[168:169]
	s_add_i32 m0, s37, 0xc000
	ds_read_b128 v[172:175], v206
	ds_read_b128 v[176:179], v206 offset:1024
	ds_read_b128 v[180:183], v206 offset:2048
	ds_read_b128 v[184:187], v206 offset:3072
	ds_read_b128 v[208:211], v206 offset:4096
	ds_read_b128 v[212:215], v206 offset:5120
	ds_read_b128 v[216:219], v206 offset:6144
	ds_read_b128 v[220:223], v206 offset:7168
	global_load_lds_dwordx4 v[188:189], off
	v_lshl_add_u64 v[188:189], s[92:93], 0, v[170:171]
	s_add_i32 m0, s37, 0xe000
	s_nop 0
	global_load_lds_dwordx4 v[188:189], off
	s_waitcnt lgkmcnt(8)
	s_barrier
	s_waitcnt lgkmcnt(0)
	s_setprio 1
	s_waitcnt lgkmcnt(0)
	v_mfma_f32_16x16x32_bf16 v[138:141], v[114:117], v[172:175], v[138:141]
	v_mfma_f32_16x16x32_bf16 v[58:61], v[122:125], v[172:175], v[58:61]
	v_mfma_f32_16x16x32_bf16 v[134:137], v[114:117], v[180:183], v[134:137]
	v_mfma_f32_16x16x32_bf16 v[54:57], v[122:125], v[180:183], v[54:57]
	v_mfma_f32_16x16x32_bf16 v[110:113], v[114:117], v[208:211], v[110:113]
	v_mfma_f32_16x16x32_bf16 v[46:49], v[122:125], v[208:211], v[46:49]
	v_mfma_f32_16x16x32_bf16 v[102:105], v[114:117], v[216:219], v[102:105]
	v_mfma_f32_16x16x32_bf16 v[38:41], v[122:125], v[216:219], v[38:41]
	v_mfma_f32_16x16x32_bf16 v[138:141], v[118:121], v[176:179], v[138:141]
	v_mfma_f32_16x16x32_bf16 v[58:61], v[126:129], v[176:179], v[58:61]
	v_mfma_f32_16x16x32_bf16 v[134:137], v[118:121], v[184:187], v[134:137]
	v_mfma_f32_16x16x32_bf16 v[54:57], v[126:129], v[184:187], v[54:57]
	v_mfma_f32_16x16x32_bf16 v[110:113], v[118:121], v[212:215], v[110:113]
	v_mfma_f32_16x16x32_bf16 v[46:49], v[126:129], v[212:215], v[46:49]
	v_mfma_f32_16x16x32_bf16 v[102:105], v[118:121], v[220:223], v[102:105]
	s_setprio 2
	s_barrier
	v_mfma_f32_16x16x32_bf16 v[38:41], v[126:129], v[220:223], v[38:41]
	s_setprio 0
	s_add_i32 s54, 0, 0x14000
	v_add_u32_e32 v188, s54, v205
	s_add_i32 s52, s52, s23
	ds_read_b128 v[224:227], v188
	ds_read_b128 v[228:231], v188 offset:1024
	ds_read_b128 v[232:235], v188 offset:2048
	ds_read_b128 v[236:239], v188 offset:3072
	v_lshl_add_u64 v[188:189], s[44:45], 0, v[0:1]
	s_mov_b32 m0, s52
	v_lshl_add_u64 v[240:241], s[44:45], 0, v[158:159]
	global_load_lds_dwordx4 v[188:189], off
	s_add_i32 m0, s52, 0x2000
	s_nop 0
	global_load_lds_dwordx4 v[240:241], off
	s_barrier
	s_waitcnt lgkmcnt(0)
	s_setprio 1
	s_waitcnt lgkmcnt(0)
	v_mfma_f32_16x16x32_bf16 v[142:145], v[224:227], v[172:175], v[142:145]
	v_mfma_f32_16x16x32_bf16 v[62:65], v[232:235], v[172:175], v[62:65]
	v_mfma_f32_16x16x32_bf16 v[130:133], v[224:227], v[180:183], v[130:133]
	v_mfma_f32_16x16x32_bf16 v[50:53], v[232:235], v[180:183], v[50:53]
	v_mfma_f32_16x16x32_bf16 v[106:109], v[224:227], v[208:211], v[106:109]
	v_mfma_f32_16x16x32_bf16 v[42:45], v[232:235], v[208:211], v[42:45]
	v_mfma_f32_16x16x32_bf16 v[98:101], v[224:227], v[216:219], v[98:101]
	v_mfma_f32_16x16x32_bf16 v[34:37], v[232:235], v[216:219], v[34:37]
	v_mfma_f32_16x16x32_bf16 v[142:145], v[228:231], v[176:179], v[142:145]
	v_mfma_f32_16x16x32_bf16 v[62:65], v[236:239], v[176:179], v[62:65]
	v_mfma_f32_16x16x32_bf16 v[130:133], v[228:231], v[184:187], v[130:133]
	v_mfma_f32_16x16x32_bf16 v[50:53], v[236:239], v[184:187], v[50:53]
	v_mfma_f32_16x16x32_bf16 v[106:109], v[228:231], v[212:215], v[106:109]
	v_mfma_f32_16x16x32_bf16 v[42:45], v[236:239], v[212:215], v[42:45]
	v_mfma_f32_16x16x32_bf16 v[98:101], v[228:231], v[220:223], v[98:101]
	s_setprio 2
	s_barrier
	v_mfma_f32_16x16x32_bf16 v[34:37], v[236:239], v[220:223], v[34:37]
	s_setprio 0
	s_mov_b32 m0, s37
	v_lshl_add_u64 v[242:243], s[94:95], 0, v[162:163]
	ds_read_b128 v[172:175], v206 offset:16384
	ds_read_b128 v[176:179], v206 offset:17408
	ds_read_b128 v[180:183], v206 offset:18432
	ds_read_b128 v[184:187], v206 offset:19456
	ds_read_b128 v[208:211], v206 offset:20480
	ds_read_b128 v[212:215], v206 offset:21504
	ds_read_b128 v[216:219], v206 offset:22528
	ds_read_b128 v[220:223], v206 offset:23552
	global_load_lds_dwordx4 v[242:243], off
	v_lshl_add_u64 v[244:245], s[94:95], 0, v[160:161]
	s_mov_b32 m0, s40
	s_nop 0
	global_load_lds_dwordx4 v[244:245], off
	s_barrier
	s_waitcnt lgkmcnt(0)
	s_setprio 1
	s_waitcnt lgkmcnt(0)
	v_mfma_f32_16x16x32_bf16 v[94:97], v[114:117], v[172:175], v[94:97]
	v_mfma_f32_16x16x32_bf16 v[30:33], v[122:125], v[172:175], v[30:33]
	v_mfma_f32_16x16x32_bf16 v[86:89], v[114:117], v[180:183], v[86:89]
	v_mfma_f32_16x16x32_bf16 v[22:25], v[122:125], v[180:183], v[22:25]
	v_mfma_f32_16x16x32_bf16 v[78:81], v[114:117], v[208:211], v[78:81]
	v_mfma_f32_16x16x32_bf16 v[14:17], v[122:125], v[208:211], v[14:17]
	v_mfma_f32_16x16x32_bf16 v[70:73], v[114:117], v[216:219], v[70:73]
	v_mfma_f32_16x16x32_bf16 v[6:9], v[122:125], v[216:219], v[6:9]
	v_mfma_f32_16x16x32_bf16 v[94:97], v[118:121], v[176:179], v[94:97]
	v_mfma_f32_16x16x32_bf16 v[30:33], v[126:129], v[176:179], v[30:33]
	v_mfma_f32_16x16x32_bf16 v[86:89], v[118:121], v[184:187], v[86:89]
	v_mfma_f32_16x16x32_bf16 v[22:25], v[126:129], v[184:187], v[22:25]
	v_mfma_f32_16x16x32_bf16 v[78:81], v[118:121], v[212:215], v[78:81]
	v_mfma_f32_16x16x32_bf16 v[14:17], v[126:129], v[212:215], v[14:17]
	v_mfma_f32_16x16x32_bf16 v[70:73], v[118:121], v[220:223], v[70:73]
	s_setprio 2
	s_barrier
	v_mfma_f32_16x16x32_bf16 v[6:9], v[126:129], v[220:223], v[6:9]
	s_setprio 0
	s_add_u32 s52, s44, 0x80000
	s_addc_u32 s53, s45, 0
	s_add_i32 s54, s54, s23
	v_lshl_add_u64 v[114:115], s[52:53], 0, v[0:1]
	s_mov_b32 m0, s54
	s_nop 0
	global_load_lds_dwordx4 v[114:115], off
	v_lshl_add_u64 v[114:115], s[52:53], 0, v[158:159]
	s_add_i32 m0, s54, 0x2000
	s_nop 0
	global_load_lds_dwordx4 v[114:115], off
	s_waitcnt vmcnt(6)
	s_barrier
	s_setprio 1
	v_mfma_f32_16x16x32_bf16 v[90:93], v[224:227], v[172:175], v[90:93]
	v_mfma_f32_16x16x32_bf16 v[26:29], v[232:235], v[172:175], v[26:29]
	v_mfma_f32_16x16x32_bf16 v[82:85], v[224:227], v[180:183], v[82:85]
	v_mfma_f32_16x16x32_bf16 v[18:21], v[232:235], v[180:183], v[18:21]
	v_mfma_f32_16x16x32_bf16 v[74:77], v[224:227], v[208:211], v[74:77]
	v_mfma_f32_16x16x32_bf16 v[10:13], v[232:235], v[208:211], v[10:13]
	v_mfma_f32_16x16x32_bf16 v[66:69], v[224:227], v[216:219], v[66:69]
	v_mfma_f32_16x16x32_bf16 v[2:5], v[232:235], v[216:219], v[2:5]
	v_mfma_f32_16x16x32_bf16 v[90:93], v[228:231], v[176:179], v[90:93]
	v_mfma_f32_16x16x32_bf16 v[26:29], v[236:239], v[176:179], v[26:29]
	v_mfma_f32_16x16x32_bf16 v[82:85], v[228:231], v[184:187], v[82:85]
	v_mfma_f32_16x16x32_bf16 v[18:21], v[236:239], v[184:187], v[18:21]
	v_mfma_f32_16x16x32_bf16 v[74:77], v[228:231], v[212:215], v[74:77]
	v_mfma_f32_16x16x32_bf16 v[10:13], v[236:239], v[212:215], v[10:13]
	v_mfma_f32_16x16x32_bf16 v[66:69], v[228:231], v[220:223], v[66:69]
	s_setprio 2
	s_barrier
	v_mfma_f32_16x16x32_bf16 v[2:5], v[236:239], v[220:223], v[2:5]
	s_setprio 0
	s_add_i32 s54, 0, 0x18000
	v_add_u32_e32 v126, s54, v205
	ds_read_b128 v[114:117], v126
	ds_read_b128 v[118:121], v126 offset:1024
	ds_read_b128 v[122:125], v126 offset:2048
	ds_read_b128 v[126:129], v126 offset:3072
	s_add_u32 s52, s94, 0x80000
	s_addc_u32 s53, s95, 0
	s_mov_b32 m0, s41
	v_lshl_add_u64 v[224:225], s[52:53], 0, v[162:163]
	ds_read_b128 v[172:175], v206 offset:32768
	ds_read_b128 v[176:179], v206 offset:33792
	ds_read_b128 v[180:183], v206 offset:34816
	ds_read_b128 v[184:187], v206 offset:35840
	ds_read_b128 v[208:211], v206 offset:36864
	ds_read_b128 v[212:215], v206 offset:37888
	ds_read_b128 v[216:219], v206 offset:38912
	ds_read_b128 v[220:223], v206 offset:39936
	global_load_lds_dwordx4 v[224:225], off
	v_lshl_add_u64 v[224:225], s[52:53], 0, v[160:161]
	s_mov_b32 m0, s42
	s_nop 0
	global_load_lds_dwordx4 v[224:225], off
	s_waitcnt lgkmcnt(8)
	s_barrier
	s_waitcnt lgkmcnt(0)
	s_setprio 1
	s_waitcnt lgkmcnt(0)
	v_mfma_f32_16x16x32_bf16 v[138:141], v[114:117], v[172:175], v[138:141]
	v_mfma_f32_16x16x32_bf16 v[58:61], v[122:125], v[172:175], v[58:61]
	v_mfma_f32_16x16x32_bf16 v[134:137], v[114:117], v[180:183], v[134:137]
	v_mfma_f32_16x16x32_bf16 v[54:57], v[122:125], v[180:183], v[54:57]
	v_mfma_f32_16x16x32_bf16 v[110:113], v[114:117], v[208:211], v[110:113]
	v_mfma_f32_16x16x32_bf16 v[46:49], v[122:125], v[208:211], v[46:49]
	v_mfma_f32_16x16x32_bf16 v[102:105], v[114:117], v[216:219], v[102:105]
	v_mfma_f32_16x16x32_bf16 v[38:41], v[122:125], v[216:219], v[38:41]
	v_mfma_f32_16x16x32_bf16 v[138:141], v[118:121], v[176:179], v[138:141]
	v_mfma_f32_16x16x32_bf16 v[58:61], v[126:129], v[176:179], v[58:61]
	v_mfma_f32_16x16x32_bf16 v[134:137], v[118:121], v[184:187], v[134:137]
	v_mfma_f32_16x16x32_bf16 v[54:57], v[126:129], v[184:187], v[54:57]
	v_mfma_f32_16x16x32_bf16 v[110:113], v[118:121], v[212:215], v[110:113]
	v_mfma_f32_16x16x32_bf16 v[46:49], v[126:129], v[212:215], v[46:49]
	v_mfma_f32_16x16x32_bf16 v[102:105], v[118:121], v[220:223], v[102:105]
	s_setprio 2
	s_barrier
	v_mfma_f32_16x16x32_bf16 v[38:41], v[126:129], v[220:223], v[38:41]
	s_setprio 0
	s_add_i32 s52, 0, 0x1c000
	s_add_i32 s53, s54, s23
	v_add_u32_e32 v207, s52, v205
	v_lshl_add_u64 v[188:189], v[188:189], 0, s[62:63]
	s_mov_b32 m0, s53
	ds_read_b128 v[224:227], v207
	ds_read_b128 v[228:231], v207 offset:1024
	ds_read_b128 v[232:235], v207 offset:2048
	ds_read_b128 v[236:239], v207 offset:3072
	global_load_lds_dwordx4 v[188:189], off
	v_lshl_add_u64 v[188:189], v[240:241], 0, s[62:63]
	s_add_i32 m0, s53, 0x2000
	s_nop 0
	global_load_lds_dwordx4 v[188:189], off
	s_barrier
	s_waitcnt lgkmcnt(0)
	s_setprio 1
	s_waitcnt lgkmcnt(0)
	v_mfma_f32_16x16x32_bf16 v[142:145], v[224:227], v[172:175], v[142:145]
	v_mfma_f32_16x16x32_bf16 v[62:65], v[232:235], v[172:175], v[62:65]
	v_mfma_f32_16x16x32_bf16 v[130:133], v[224:227], v[180:183], v[130:133]
	v_mfma_f32_16x16x32_bf16 v[50:53], v[232:235], v[180:183], v[50:53]
	v_mfma_f32_16x16x32_bf16 v[106:109], v[224:227], v[208:211], v[106:109]
	v_mfma_f32_16x16x32_bf16 v[42:45], v[232:235], v[208:211], v[42:45]
	v_mfma_f32_16x16x32_bf16 v[98:101], v[224:227], v[216:219], v[98:101]
	v_mfma_f32_16x16x32_bf16 v[34:37], v[232:235], v[216:219], v[34:37]
	v_mfma_f32_16x16x32_bf16 v[142:145], v[228:231], v[176:179], v[142:145]
	v_mfma_f32_16x16x32_bf16 v[62:65], v[236:239], v[176:179], v[62:65]
	v_mfma_f32_16x16x32_bf16 v[130:133], v[228:231], v[184:187], v[130:133]
	v_mfma_f32_16x16x32_bf16 v[50:53], v[236:239], v[184:187], v[50:53]
	v_mfma_f32_16x16x32_bf16 v[106:109], v[228:231], v[212:215], v[106:109]
	v_mfma_f32_16x16x32_bf16 v[42:45], v[236:239], v[212:215], v[42:45]
	v_mfma_f32_16x16x32_bf16 v[98:101], v[228:231], v[220:223], v[98:101]
	s_setprio 2
	s_barrier
	v_mfma_f32_16x16x32_bf16 v[34:37], v[236:239], v[220:223], v[34:37]
	s_setprio 0
	s_mov_b32 m0, s46
	v_lshl_add_u64 v[188:189], v[242:243], 0, s[62:63]
	ds_read_b128 v[172:175], v206 offset:49152
	ds_read_b128 v[176:179], v206 offset:50176
	ds_read_b128 v[180:183], v206 offset:51200
	ds_read_b128 v[184:187], v206 offset:52224
	ds_read_b128 v[208:211], v206 offset:53248
	ds_read_b128 v[212:215], v206 offset:54272
	ds_read_b128 v[216:219], v206 offset:55296
	ds_read_b128 v[220:223], v206 offset:56320
	global_load_lds_dwordx4 v[188:189], off
	v_lshl_add_u64 v[188:189], v[244:245], 0, s[62:63]
	s_mov_b32 m0, s47
	s_nop 0
	global_load_lds_dwordx4 v[188:189], off
	s_barrier
	s_waitcnt lgkmcnt(0)
	s_setprio 1
	s_waitcnt lgkmcnt(0)
	v_mfma_f32_16x16x32_bf16 v[94:97], v[114:117], v[172:175], v[94:97]
	v_mfma_f32_16x16x32_bf16 v[30:33], v[122:125], v[172:175], v[30:33]
	v_mfma_f32_16x16x32_bf16 v[86:89], v[114:117], v[180:183], v[86:89]
	v_mfma_f32_16x16x32_bf16 v[22:25], v[122:125], v[180:183], v[22:25]
	v_mfma_f32_16x16x32_bf16 v[78:81], v[114:117], v[208:211], v[78:81]
	v_mfma_f32_16x16x32_bf16 v[14:17], v[122:125], v[208:211], v[14:17]
	v_mfma_f32_16x16x32_bf16 v[70:73], v[114:117], v[216:219], v[70:73]
	v_mfma_f32_16x16x32_bf16 v[6:9], v[122:125], v[216:219], v[6:9]
	v_mfma_f32_16x16x32_bf16 v[94:97], v[118:121], v[176:179], v[94:97]
	v_mfma_f32_16x16x32_bf16 v[30:33], v[126:129], v[176:179], v[30:33]
	v_mfma_f32_16x16x32_bf16 v[86:89], v[118:121], v[184:187], v[86:89]
	v_mfma_f32_16x16x32_bf16 v[22:25], v[126:129], v[184:187], v[22:25]
	v_mfma_f32_16x16x32_bf16 v[78:81], v[118:121], v[212:215], v[78:81]
	v_mfma_f32_16x16x32_bf16 v[14:17], v[126:129], v[212:215], v[14:17]
	v_mfma_f32_16x16x32_bf16 v[70:73], v[118:121], v[220:223], v[70:73]
	s_setprio 2
	s_barrier
	v_mfma_f32_16x16x32_bf16 v[6:9], v[126:129], v[220:223], v[6:9]
	s_setprio 0
	s_add_u32 s44, s44, 0x80080
	s_addc_u32 s45, s45, 0
	s_add_i32 s52, s52, s23
	v_lshl_add_u64 v[114:115], s[44:45], 0, v[0:1]
	s_mov_b32 m0, s52
	s_nop 0
	global_load_lds_dwordx4 v[114:115], off
	v_lshl_add_u64 v[114:115], s[44:45], 0, v[158:159]
	s_add_i32 m0, s52, 0x2000
	s_nop 0
	global_load_lds_dwordx4 v[114:115], off
	s_waitcnt vmcnt(6)
	s_barrier
	s_setprio 1
	v_mfma_f32_16x16x32_bf16 v[90:93], v[224:227], v[172:175], v[90:93]
	v_mfma_f32_16x16x32_bf16 v[26:29], v[232:235], v[172:175], v[26:29]
	v_mfma_f32_16x16x32_bf16 v[82:85], v[224:227], v[180:183], v[82:85]
	v_mfma_f32_16x16x32_bf16 v[18:21], v[232:235], v[180:183], v[18:21]
	v_mfma_f32_16x16x32_bf16 v[74:77], v[224:227], v[208:211], v[74:77]
	v_mfma_f32_16x16x32_bf16 v[10:13], v[232:235], v[208:211], v[10:13]
	v_mfma_f32_16x16x32_bf16 v[66:69], v[224:227], v[216:219], v[66:69]
	v_mfma_f32_16x16x32_bf16 v[2:5], v[232:235], v[216:219], v[2:5]
	v_mfma_f32_16x16x32_bf16 v[90:93], v[228:231], v[176:179], v[90:93]
	v_mfma_f32_16x16x32_bf16 v[26:29], v[236:239], v[176:179], v[26:29]
	v_mfma_f32_16x16x32_bf16 v[82:85], v[228:231], v[184:187], v[82:85]
	v_mfma_f32_16x16x32_bf16 v[18:21], v[236:239], v[184:187], v[18:21]
	v_mfma_f32_16x16x32_bf16 v[74:77], v[228:231], v[212:215], v[74:77]
	v_mfma_f32_16x16x32_bf16 v[10:13], v[236:239], v[212:215], v[10:13]
	v_mfma_f32_16x16x32_bf16 v[66:69], v[228:231], v[220:223], v[66:69]
	s_setprio 2
	s_barrier
	v_mfma_f32_16x16x32_bf16 v[2:5], v[236:239], v[220:223], v[2:5]
	s_setprio 0
	s_add_i32 s51, s51, 2
	s_add_u32 s92, s92, 0x100
	s_addc_u32 s93, s93, 0
	s_add_u32 s49, s49, 0x100
	s_addc_u32 s50, s50, 0
	s_cmp_gt_u32 s51, 29
	s_cbranch_scc0 .LBB0_1420
	v_lshl_or_b32 v174, s5, 7, v167
	v_ashrrev_i32_e32 v175, 31, v174
	v_lshlrev_b64 v[180:181], 2, v[174:175]
	v_lshl_add_u64 v[176:177], s[76:77], 0, v[180:181]
	v_lshl_add_u64 v[118:119], s[82:83], 0, v[180:181]
	v_lshl_add_u64 v[120:121], s[84:85], 0, v[180:181]
	v_lshl_add_u64 v[178:179], s[80:81], 0, v[180:181]
	global_load_dwordx4 v[114:117], v[176:177], off
	global_load_dwordx4 v[220:223], v[176:177], off offset:16
	global_load_dwordx4 v[122:125], v[118:119], off
	global_load_dwordx4 v[224:227], v[118:119], off offset:16
	global_load_dwordx4 v[228:231], v[120:121], off offset:16
	global_load_dwordx4 v[118:121], v[120:121], off
	s_lshl_b32 s4, s4, 8
	global_load_dwordx4 v[126:129], v[178:179], off
	global_load_dwordx4 v[232:235], v[178:179], off offset:16
	s_and_b32 s4, s4, 0x3f00
	s_add_i32 s4, s4, s43
	v_or_b32_e32 v207, s4, v164
	v_lshl_add_u64 v[172:173], v[174:175], 1, s[78:79]
	v_mov_b32_dpp v186, v138 row_shr:1 row_mask:0xf bank_mask:0xf bound_ctrl:1
	v_mov_b32_dpp v188, v138 row_shr:2 row_mask:0xf bank_mask:0xf bound_ctrl:1
	v_mov_b32_dpp v187, v139 row_shr:1 row_mask:0xf bank_mask:0xf bound_ctrl:1
	v_mov_b32_dpp v189, v139 row_shr:2 row_mask:0xf bank_mask:0xf bound_ctrl:1
	v_mov_b32_dpp v182, v140 row_shr:1 row_mask:0xf bank_mask:0xf bound_ctrl:1
	v_mov_b32_dpp v184, v140 row_shr:2 row_mask:0xf bank_mask:0xf bound_ctrl:1
	v_mov_b32_dpp v183, v141 row_shr:1 row_mask:0xf bank_mask:0xf bound_ctrl:1
	v_mov_b32_dpp v185, v141 row_shr:2 row_mask:0xf bank_mask:0xf bound_ctrl:1
	s_and_saveexec_b64 s[6:7], s[10:11]
	s_xor_b64 s[6:7], exec, s[6:7]
	s_cbranch_execz .LBB0_1423
	s_waitcnt vmcnt(0)
	v_pk_fma_f32 v[188:189], v[114:115], v[188:189], v[126:127]
	v_pk_fma_f32 v[184:185], v[116:117], v[184:185], v[128:129]
	v_pk_fma_f32 v[186:187], v[122:123], v[186:187], v[188:189]
	v_pk_fma_f32 v[182:183], v[124:125], v[182:183], v[184:185]
	v_pk_fma_f32 v[186:187], v[138:139], v[118:119], v[186:187]
	v_pk_fma_f32 v[182:183], v[140:141], v[120:121], v[182:183]
	v_mul_f32_e32 v175, 0xbfb8aa3b, v186
	v_exp_f32_e32 v175, v175
	v_mul_f32_e32 v188, 0xbfb8aa3b, v187
	v_exp_f32_e32 v188, v188
	v_mul_f32_e32 v184, 0xbfb8aa3b, v183
	v_add_f32_e32 v175, 1.0, v175
	v_exp_f32_e32 v185, v184
	v_add_f32_e32 v189, 1.0, v188
	v_rcp_f32_e32 v188, v175
	v_mul_f32_e32 v175, 0xbfb8aa3b, v182
	v_exp_f32_e32 v175, v175
	v_rcp_f32_e32 v189, v189
	v_add_f32_e32 v175, 1.0, v175
	v_rcp_f32_e32 v184, v175
	v_add_f32_e32 v175, 1.0, v185
	v_rcp_f32_e32 v185, v175
	v_pk_mul_f32 v[186:187], v[186:187], v[188:189]
	v_pk_mul_f32 v[182:183], v[182:183], v[184:185]
	v_pk_mul_f32 v[186:187], v[142:143], v[186:187]
	v_pk_mul_f32 v[182:183], v[144:145], v[182:183]
	v_cvt_pk_bf16_f32 v184, v186, v187
	v_cvt_pk_bf16_f32 v185, v182, v183
	v_mad_i64_i32 v[182:183], s[18:19], v207, s39, v[172:173]
	global_store_dwordx2 v[182:183], v[184:185], off

.LBB0_1617:
	s_add_u32 s68, s64, 0x100
	s_addc_u32 s69, s65, 0
	s_add_i32 s48, 0, 0x10000
	v_add_u32_e32 v102, s48, v187
	ds_read_b128 v[90:93], v102
	ds_read_b128 v[94:97], v102 offset:1024
	ds_read_b128 v[98:101], v102 offset:2048
	ds_read_b128 v[102:105], v102 offset:3072
	s_cmpk_eq_i32 s47, 0x54
	s_cselect_b32 s81, s11, s69
	s_cselect_b32 s80, s10, s68
	s_cselect_b32 s45, s13, s5
	s_cselect_b32 s44, s12, s4
	v_lshl_add_u64 v[184:185], s[64:65], 0, v[164:165]
	s_add_i32 m0, s27, 0xc000
	ds_read_b128 v[168:171], v189
	ds_read_b128 v[172:175], v189 offset:1024
	ds_read_b128 v[176:179], v189 offset:2048
	ds_read_b128 v[180:183], v189 offset:3072
	ds_read_b128 v[206:209], v189 offset:4096
	ds_read_b128 v[210:213], v189 offset:5120
	ds_read_b128 v[214:217], v189 offset:6144
	ds_read_b128 v[218:221], v189 offset:7168
	global_load_lds_dwordx4 v[184:185], off
	v_lshl_add_u64 v[184:185], s[64:65], 0, v[166:167]
	s_add_i32 m0, s27, 0xe000
	s_nop 0
	global_load_lds_dwordx4 v[184:185], off
	s_waitcnt lgkmcnt(8)
	s_barrier
	s_waitcnt lgkmcnt(0)
	s_setprio 1
	s_waitcnt lgkmcnt(0)
	v_mfma_f32_16x16x32_bf16 v[142:145], v[90:93], v[168:171], v[142:145]
	v_mfma_f32_16x16x32_bf16 v[138:141], v[98:101], v[168:171], v[138:141]
	v_mfma_f32_16x16x32_bf16 v[134:137], v[90:93], v[176:179], v[134:137]
	v_mfma_f32_16x16x32_bf16 v[130:133], v[98:101], v[176:179], v[130:133]
	v_mfma_f32_16x16x32_bf16 v[126:129], v[90:93], v[206:209], v[126:129]
	v_mfma_f32_16x16x32_bf16 v[122:125], v[98:101], v[206:209], v[122:125]
	v_mfma_f32_16x16x32_bf16 v[118:121], v[90:93], v[214:217], v[118:121]
	v_mfma_f32_16x16x32_bf16 v[114:117], v[98:101], v[214:217], v[114:117]
	v_mfma_f32_16x16x32_bf16 v[142:145], v[94:97], v[172:175], v[142:145]
	v_mfma_f32_16x16x32_bf16 v[138:141], v[102:105], v[172:175], v[138:141]
	v_mfma_f32_16x16x32_bf16 v[134:137], v[94:97], v[180:183], v[134:137]
	v_mfma_f32_16x16x32_bf16 v[130:133], v[102:105], v[180:183], v[130:133]
	v_mfma_f32_16x16x32_bf16 v[126:129], v[94:97], v[210:213], v[126:129]
	v_mfma_f32_16x16x32_bf16 v[122:125], v[102:105], v[210:213], v[122:125]
	v_mfma_f32_16x16x32_bf16 v[118:121], v[94:97], v[218:221], v[118:121]
	s_setprio 2
	s_barrier
	v_mfma_f32_16x16x32_bf16 v[114:117], v[102:105], v[218:221], v[114:117]
	s_setprio 0
	s_add_i32 s50, 0, 0x14000
	v_add_u32_e32 v184, s50, v187
	s_add_i32 s48, s48, s22
	ds_read_b128 v[222:225], v184
	ds_read_b128 v[226:229], v184 offset:1024
	ds_read_b128 v[230:233], v184 offset:2048
	ds_read_b128 v[234:237], v184 offset:3072
	v_lshl_add_u64 v[184:185], s[44:45], 0, v[0:1]
	s_mov_b32 m0, s48
	v_lshl_add_u64 v[238:239], s[44:45], 0, v[158:159]
	global_load_lds_dwordx4 v[184:185], off
	s_add_i32 m0, s48, 0x2000
	s_nop 0
	global_load_lds_dwordx4 v[238:239], off
	s_barrier
	s_waitcnt lgkmcnt(0)
	s_setprio 1
	s_waitcnt lgkmcnt(0)
	v_mfma_f32_16x16x32_bf16 v[62:65], v[222:225], v[168:171], v[62:65]
	v_mfma_f32_16x16x32_bf16 v[58:61], v[230:233], v[168:171], v[58:61]
	v_mfma_f32_16x16x32_bf16 v[54:57], v[222:225], v[176:179], v[54:57]
	v_mfma_f32_16x16x32_bf16 v[50:53], v[230:233], v[176:179], v[50:53]
	v_mfma_f32_16x16x32_bf16 v[46:49], v[222:225], v[206:209], v[46:49]
	v_mfma_f32_16x16x32_bf16 v[42:45], v[230:233], v[206:209], v[42:45]
	v_mfma_f32_16x16x32_bf16 v[38:41], v[222:225], v[214:217], v[38:41]
	v_mfma_f32_16x16x32_bf16 v[34:37], v[230:233], v[214:217], v[34:37]
	v_mfma_f32_16x16x32_bf16 v[62:65], v[226:229], v[172:175], v[62:65]
	v_mfma_f32_16x16x32_bf16 v[58:61], v[234:237], v[172:175], v[58:61]
	v_mfma_f32_16x16x32_bf16 v[54:57], v[226:229], v[180:183], v[54:57]
	v_mfma_f32_16x16x32_bf16 v[50:53], v[234:237], v[180:183], v[50:53]
	v_mfma_f32_16x16x32_bf16 v[46:49], v[226:229], v[210:213], v[46:49]
	v_mfma_f32_16x16x32_bf16 v[42:45], v[234:237], v[210:213], v[42:45]
	v_mfma_f32_16x16x32_bf16 v[38:41], v[226:229], v[218:221], v[38:41]
	s_setprio 2
	s_barrier
	v_mfma_f32_16x16x32_bf16 v[34:37], v[234:237], v[218:221], v[34:37]
	s_setprio 0
	s_mov_b32 m0, s27
	v_lshl_add_u64 v[240:241], s[80:81], 0, v[162:163]
	ds_read_b128 v[168:171], v189 offset:16384
	ds_read_b128 v[172:175], v189 offset:17408
	ds_read_b128 v[176:179], v189 offset:18432
	ds_read_b128 v[180:183], v189 offset:19456
	ds_read_b128 v[206:209], v189 offset:20480
	ds_read_b128 v[210:213], v189 offset:21504
	ds_read_b128 v[214:217], v189 offset:22528
	ds_read_b128 v[218:221], v189 offset:23552
	global_load_lds_dwordx4 v[240:241], off
	v_lshl_add_u64 v[242:243], s[80:81], 0, v[160:161]
	s_mov_b32 m0, s36
	s_nop 0
	global_load_lds_dwordx4 v[242:243], off
	s_barrier
	s_waitcnt lgkmcnt(0)
	s_setprio 1
	s_waitcnt lgkmcnt(0)
	v_mfma_f32_16x16x32_bf16 v[110:113], v[90:93], v[168:171], v[110:113]
	v_mfma_f32_16x16x32_bf16 v[106:109], v[98:101], v[168:171], v[106:109]
	v_mfma_f32_16x16x32_bf16 v[86:89], v[90:93], v[176:179], v[86:89]
	v_mfma_f32_16x16x32_bf16 v[82:85], v[98:101], v[176:179], v[82:85]
	v_mfma_f32_16x16x32_bf16 v[78:81], v[90:93], v[206:209], v[78:81]
	v_mfma_f32_16x16x32_bf16 v[74:77], v[98:101], v[206:209], v[74:77]
	v_mfma_f32_16x16x32_bf16 v[70:73], v[90:93], v[214:217], v[70:73]
	v_mfma_f32_16x16x32_bf16 v[66:69], v[98:101], v[214:217], v[66:69]
	v_mfma_f32_16x16x32_bf16 v[110:113], v[94:97], v[172:175], v[110:113]
	v_mfma_f32_16x16x32_bf16 v[106:109], v[102:105], v[172:175], v[106:109]
	v_mfma_f32_16x16x32_bf16 v[86:89], v[94:97], v[180:183], v[86:89]
	v_mfma_f32_16x16x32_bf16 v[82:85], v[102:105], v[180:183], v[82:85]
	v_mfma_f32_16x16x32_bf16 v[78:81], v[94:97], v[210:213], v[78:81]
	v_mfma_f32_16x16x32_bf16 v[74:77], v[102:105], v[210:213], v[74:77]
	v_mfma_f32_16x16x32_bf16 v[70:73], v[94:97], v[218:221], v[70:73]
	s_setprio 2
	s_barrier
	v_mfma_f32_16x16x32_bf16 v[66:69], v[102:105], v[218:221], v[66:69]
	s_setprio 0
	s_add_u32 s48, s44, 0x160000
	s_addc_u32 s49, s45, 0
	s_add_i32 s50, s50, s22
	v_lshl_add_u64 v[90:91], s[48:49], 0, v[0:1]
	s_mov_b32 m0, s50
	s_nop 0
	global_load_lds_dwordx4 v[90:91], off
	v_lshl_add_u64 v[90:91], s[48:49], 0, v[158:159]
	s_add_i32 m0, s50, 0x2000
	s_nop 0
	global_load_lds_dwordx4 v[90:91], off
	s_waitcnt vmcnt(6)
	s_barrier
	s_setprio 1
	v_mfma_f32_16x16x32_bf16 v[30:33], v[222:225], v[168:171], v[30:33]
	v_mfma_f32_16x16x32_bf16 v[26:29], v[230:233], v[168:171], v[26:29]
	v_mfma_f32_16x16x32_bf16 v[22:25], v[222:225], v[176:179], v[22:25]
	v_mfma_f32_16x16x32_bf16 v[18:21], v[230:233], v[176:179], v[18:21]
	v_mfma_f32_16x16x32_bf16 v[14:17], v[222:225], v[206:209], v[14:17]
	v_mfma_f32_16x16x32_bf16 v[10:13], v[230:233], v[206:209], v[10:13]
	v_mfma_f32_16x16x32_bf16 v[6:9], v[222:225], v[214:217], v[6:9]
	v_mfma_f32_16x16x32_bf16 v[2:5], v[230:233], v[214:217], v[2:5]
	v_mfma_f32_16x16x32_bf16 v[30:33], v[226:229], v[172:175], v[30:33]
	v_mfma_f32_16x16x32_bf16 v[26:29], v[234:237], v[172:175], v[26:29]
	v_mfma_f32_16x16x32_bf16 v[22:25], v[226:229], v[180:183], v[22:25]
	v_mfma_f32_16x16x32_bf16 v[18:21], v[234:237], v[180:183], v[18:21]
	v_mfma_f32_16x16x32_bf16 v[14:17], v[226:229], v[210:213], v[14:17]
	v_mfma_f32_16x16x32_bf16 v[10:13], v[234:237], v[210:213], v[10:13]
	v_mfma_f32_16x16x32_bf16 v[6:9], v[226:229], v[218:221], v[6:9]
	s_setprio 2
	s_barrier
	v_mfma_f32_16x16x32_bf16 v[2:5], v[234:237], v[218:221], v[2:5]
	s_setprio 0
	s_add_i32 s50, 0, 0x18000
	v_add_u32_e32 v102, s50, v187
	ds_read_b128 v[90:93], v102
	ds_read_b128 v[94:97], v102 offset:1024
	ds_read_b128 v[98:101], v102 offset:2048
	ds_read_b128 v[102:105], v102 offset:3072
	s_add_u32 s48, s80, 0x160000
	s_addc_u32 s49, s81, 0
	s_mov_b32 m0, s37
	v_lshl_add_u64 v[222:223], s[48:49], 0, v[162:163]
	ds_read_b128 v[168:171], v189 offset:32768
	ds_read_b128 v[172:175], v189 offset:33792
	ds_read_b128 v[176:179], v189 offset:34816
	ds_read_b128 v[180:183], v189 offset:35840
	ds_read_b128 v[206:209], v189 offset:36864
	ds_read_b128 v[210:213], v189 offset:37888
	ds_read_b128 v[214:217], v189 offset:38912
	ds_read_b128 v[218:221], v189 offset:39936
	global_load_lds_dwordx4 v[222:223], off
	v_lshl_add_u64 v[222:223], s[48:49], 0, v[160:161]
	s_mov_b32 m0, s40
	s_nop 0
	global_load_lds_dwordx4 v[222:223], off
	s_waitcnt lgkmcnt(8)
	s_barrier
	s_waitcnt lgkmcnt(0)
	s_setprio 1
	s_waitcnt lgkmcnt(0)
	v_mfma_f32_16x16x32_bf16 v[142:145], v[90:93], v[168:171], v[142:145]
	v_mfma_f32_16x16x32_bf16 v[138:141], v[98:101], v[168:171], v[138:141]
	v_mfma_f32_16x16x32_bf16 v[134:137], v[90:93], v[176:179], v[134:137]
	v_mfma_f32_16x16x32_bf16 v[130:133], v[98:101], v[176:179], v[130:133]
	v_mfma_f32_16x16x32_bf16 v[126:129], v[90:93], v[206:209], v[126:129]
	v_mfma_f32_16x16x32_bf16 v[122:125], v[98:101], v[206:209], v[122:125]
	v_mfma_f32_16x16x32_bf16 v[118:121], v[90:93], v[214:217], v[118:121]
	v_mfma_f32_16x16x32_bf16 v[114:117], v[98:101], v[214:217], v[114:117]
	v_mfma_f32_16x16x32_bf16 v[142:145], v[94:97], v[172:175], v[142:145]
	v_mfma_f32_16x16x32_bf16 v[138:141], v[102:105], v[172:175], v[138:141]
	v_mfma_f32_16x16x32_bf16 v[134:137], v[94:97], v[180:183], v[134:137]
	v_mfma_f32_16x16x32_bf16 v[130:133], v[102:105], v[180:183], v[130:133]
	v_mfma_f32_16x16x32_bf16 v[126:129], v[94:97], v[210:213], v[126:129]
	v_mfma_f32_16x16x32_bf16 v[122:125], v[102:105], v[210:213], v[122:125]
	v_mfma_f32_16x16x32_bf16 v[118:121], v[94:97], v[218:221], v[118:121]
	s_setprio 2
	s_barrier
	v_mfma_f32_16x16x32_bf16 v[114:117], v[102:105], v[218:221], v[114:117]
	s_setprio 0
	s_add_i32 s48, 0, 0x1c000
	s_add_i32 s49, s50, s22
	v_add_u32_e32 v205, s48, v187
	v_lshl_add_u64 v[184:185], v[184:185], 0, s[62:63]
	s_mov_b32 m0, s49
	ds_read_b128 v[222:225], v205
	ds_read_b128 v[226:229], v205 offset:1024
	ds_read_b128 v[230:233], v205 offset:2048
	ds_read_b128 v[234:237], v205 offset:3072
	global_load_lds_dwordx4 v[184:185], off
	v_lshl_add_u64 v[184:185], v[238:239], 0, s[62:63]
	s_add_i32 m0, s49, 0x2000
	s_nop 0
	global_load_lds_dwordx4 v[184:185], off
	s_barrier
	s_waitcnt lgkmcnt(0)
	s_setprio 1
	s_waitcnt lgkmcnt(0)
	v_mfma_f32_16x16x32_bf16 v[62:65], v[222:225], v[168:171], v[62:65]
	v_mfma_f32_16x16x32_bf16 v[58:61], v[230:233], v[168:171], v[58:61]
	v_mfma_f32_16x16x32_bf16 v[54:57], v[222:225], v[176:179], v[54:57]
	v_mfma_f32_16x16x32_bf16 v[50:53], v[230:233], v[176:179], v[50:53]
	v_mfma_f32_16x16x32_bf16 v[46:49], v[222:225], v[206:209], v[46:49]
	v_mfma_f32_16x16x32_bf16 v[42:45], v[230:233], v[206:209], v[42:45]
	v_mfma_f32_16x16x32_bf16 v[38:41], v[222:225], v[214:217], v[38:41]
	v_mfma_f32_16x16x32_bf16 v[34:37], v[230:233], v[214:217], v[34:37]
	v_mfma_f32_16x16x32_bf16 v[62:65], v[226:229], v[172:175], v[62:65]
	v_mfma_f32_16x16x32_bf16 v[58:61], v[234:237], v[172:175], v[58:61]
	v_mfma_f32_16x16x32_bf16 v[54:57], v[226:229], v[180:183], v[54:57]
	v_mfma_f32_16x16x32_bf16 v[50:53], v[234:237], v[180:183], v[50:53]
	v_mfma_f32_16x16x32_bf16 v[46:49], v[226:229], v[210:213], v[46:49]
	v_mfma_f32_16x16x32_bf16 v[42:45], v[234:237], v[210:213], v[42:45]
	v_mfma_f32_16x16x32_bf16 v[38:41], v[226:229], v[218:221], v[38:41]
	s_setprio 2
	s_barrier
	v_mfma_f32_16x16x32_bf16 v[34:37], v[234:237], v[218:221], v[34:37]
	s_setprio 0
	s_mov_b32 m0, s28
	v_lshl_add_u64 v[184:185], v[240:241], 0, s[62:63]
	ds_read_b128 v[168:171], v189 offset:49152
	ds_read_b128 v[172:175], v189 offset:50176
	ds_read_b128 v[176:179], v189 offset:51200
	ds_read_b128 v[180:183], v189 offset:52224
	ds_read_b128 v[206:209], v189 offset:53248
	ds_read_b128 v[210:213], v189 offset:54272
	ds_read_b128 v[214:217], v189 offset:55296
	ds_read_b128 v[218:221], v189 offset:56320
	global_load_lds_dwordx4 v[184:185], off
	v_lshl_add_u64 v[184:185], v[242:243], 0, s[62:63]
	s_mov_b32 m0, s41
	s_nop 0
	global_load_lds_dwordx4 v[184:185], off
	s_barrier
	s_waitcnt lgkmcnt(0)
	s_setprio 1
	s_waitcnt lgkmcnt(0)
	v_mfma_f32_16x16x32_bf16 v[110:113], v[90:93], v[168:171], v[110:113]
	v_mfma_f32_16x16x32_bf16 v[106:109], v[98:101], v[168:171], v[106:109]
	v_mfma_f32_16x16x32_bf16 v[86:89], v[90:93], v[176:179], v[86:89]
	v_mfma_f32_16x16x32_bf16 v[82:85], v[98:101], v[176:179], v[82:85]
	v_mfma_f32_16x16x32_bf16 v[78:81], v[90:93], v[206:209], v[78:81]
	v_mfma_f32_16x16x32_bf16 v[74:77], v[98:101], v[206:209], v[74:77]
	v_mfma_f32_16x16x32_bf16 v[70:73], v[90:93], v[214:217], v[70:73]
	v_mfma_f32_16x16x32_bf16 v[66:69], v[98:101], v[214:217], v[66:69]
	v_mfma_f32_16x16x32_bf16 v[110:113], v[94:97], v[172:175], v[110:113]
	v_mfma_f32_16x16x32_bf16 v[106:109], v[102:105], v[172:175], v[106:109]
	v_mfma_f32_16x16x32_bf16 v[86:89], v[94:97], v[180:183], v[86:89]
	v_mfma_f32_16x16x32_bf16 v[82:85], v[102:105], v[180:183], v[82:85]
	v_mfma_f32_16x16x32_bf16 v[78:81], v[94:97], v[210:213], v[78:81]
	v_mfma_f32_16x16x32_bf16 v[74:77], v[102:105], v[210:213], v[74:77]
	v_mfma_f32_16x16x32_bf16 v[70:73], v[94:97], v[218:221], v[70:73]
	s_setprio 2
	s_barrier
	v_mfma_f32_16x16x32_bf16 v[66:69], v[102:105], v[218:221], v[66:69]
	s_setprio 0
	s_add_u32 s44, s44, 0x160080
	s_addc_u32 s45, s45, 0
	s_add_i32 s48, s48, s22
	v_lshl_add_u64 v[90:91], s[44:45], 0, v[0:1]
	s_mov_b32 m0, s48
	s_nop 0
	global_load_lds_dwordx4 v[90:91], off
	v_lshl_add_u64 v[90:91], s[44:45], 0, v[158:159]
	s_add_i32 m0, s48, 0x2000
	s_nop 0
	global_load_lds_dwordx4 v[90:91], off
	s_waitcnt vmcnt(6)
	s_barrier
	s_setprio 1
	v_mfma_f32_16x16x32_bf16 v[30:33], v[222:225], v[168:171], v[30:33]
	v_mfma_f32_16x16x32_bf16 v[26:29], v[230:233], v[168:171], v[26:29]
	v_mfma_f32_16x16x32_bf16 v[22:25], v[222:225], v[176:179], v[22:25]
	v_mfma_f32_16x16x32_bf16 v[18:21], v[230:233], v[176:179], v[18:21]
	v_mfma_f32_16x16x32_bf16 v[14:17], v[222:225], v[206:209], v[14:17]
	v_mfma_f32_16x16x32_bf16 v[10:13], v[230:233], v[206:209], v[10:13]
	v_mfma_f32_16x16x32_bf16 v[6:9], v[222:225], v[214:217], v[6:9]
	v_mfma_f32_16x16x32_bf16 v[2:5], v[230:233], v[214:217], v[2:5]
	v_mfma_f32_16x16x32_bf16 v[30:33], v[226:229], v[172:175], v[30:33]
	v_mfma_f32_16x16x32_bf16 v[26:29], v[234:237], v[172:175], v[26:29]
	v_mfma_f32_16x16x32_bf16 v[22:25], v[226:229], v[180:183], v[22:25]
	v_mfma_f32_16x16x32_bf16 v[18:21], v[234:237], v[180:183], v[18:21]
	v_mfma_f32_16x16x32_bf16 v[14:17], v[226:229], v[210:213], v[14:17]
	v_mfma_f32_16x16x32_bf16 v[10:13], v[234:237], v[210:213], v[10:13]
	v_mfma_f32_16x16x32_bf16 v[6:9], v[226:229], v[218:221], v[6:9]
	s_setprio 2
	s_barrier
	v_mfma_f32_16x16x32_bf16 v[2:5], v[234:237], v[218:221], v[2:5]
	s_setprio 0
	s_add_i32 s47, s47, 2
	s_add_u32 s4, s4, 0x100
	s_addc_u32 s5, s5, 0
	s_cmpk_gt_u32 s47, 0x55
	s_mov_b64 s[64:65], s[68:69]
	s_cbranch_scc0 .LBB0_1617
	s_lshl_b32 s4, s46, 8
	s_and_b32 s4, s4, 0x3f00
	v_add_u32_e32 v178, s4, v186
	s_ashr_i32 s4, s43, 31
	s_lshr_b32 s4, s4, 29
	s_add_i32 s4, s43, s4
	s_and_b32 s4, s4, 0xfffff8
	s_sub_i32 s4, s43, s4
	v_lshl_or_b32 v172, s4, 8, v188
	v_ashrrev_i32_e32 v173, 31, v172
	v_ashrrev_i32_e32 v179, 31, v178
	v_lshlrev_b32_e32 v170, 12, v178
	v_lshl_add_u32 v170, v172, 1, v170
	v_lshlrev_b32_e32 v171, 3, v178
	v_lshlrev_b32_e32 v174, 2, v172
	global_load_dwordx4 v[98:101], v174, s[74:75]
	global_load_dwordx4 v[90:93], v174, s[74:75] offset:16
	global_load_dwordx4 v[102:105], v174, s[76:77]
	global_load_dwordx4 v[94:97], v174, s[76:77] offset:16
	s_add_u32 s48, s72, 0x0
	s_addc_u32 s49, s73, 0
	global_load_dwordx4 v[220:223], v170, s[48:49]
	s_add_u32 s50, s14, 0x0
	s_addc_u32 s51, s15, 0
	global_load_dwordx2 v[176:177], v171, s[50:51]
	s_add_u32 s48, s72, 0x10000
	s_addc_u32 s49, s73, 0
	global_load_dwordx4 v[224:227], v170, s[48:49]
	s_add_u32 s50, s14, 0x80
	s_addc_u32 s51, s15, 0
	global_load_dwordx2 v[180:181], v171, s[50:51]
	s_add_u32 s48, s72, 0x20000
	s_addc_u32 s49, s73, 0
	global_load_dwordx4 v[228:231], v170, s[48:49]
	s_add_u32 s50, s14, 0x100
	s_addc_u32 s51, s15, 0
	global_load_dwordx2 v[182:183], v171, s[50:51]
	s_add_u32 s48, s72, 0x30000
	s_addc_u32 s49, s73, 0
	global_load_dwordx4 v[232:235], v170, s[48:49]
	s_add_u32 s50, s14, 0x180
	s_addc_u32 s51, s15, 0
	global_load_dwordx2 v[184:185], v171, s[50:51]
	s_add_u32 s48, s72, 0x80000
	s_addc_u32 s49, s73, 0
	global_load_dwordx4 v[236:239], v170, s[48:49]
	s_add_u32 s50, s14, 0x400
	s_addc_u32 s51, s15, 0
	global_load_dwordx2 v[168:169], v171, s[50:51]
	s_add_u32 s48, s72, 0x90000
	s_addc_u32 s49, s73, 0
	global_load_dwordx4 v[240:243], v170, s[48:49]
	s_add_u32 s50, s14, 0x480
	s_addc_u32 s51, s15, 0
	global_load_dwordx2 v[252:253], v171, s[50:51]
	s_add_u32 s48, s72, 0xa0000
	s_addc_u32 s49, s73, 0
	global_load_dwordx4 v[244:247], v170, s[48:49]
	s_add_u32 s50, s14, 0x500
	s_addc_u32 s51, s15, 0
	global_load_dwordx2 v[214:215], v171, s[50:51]
	s_add_u32 s48, s72, 0xb0000
	s_addc_u32 s49, s73, 0
	global_load_dwordx4 v[248:251], v170, s[48:49]
	s_add_u32 s50, s14, 0x580
	s_addc_u32 s51, s15, 0
	global_load_dwordx2 v[216:217], v171, s[50:51]
	s_waitcnt vmcnt(14)
	v_lshlrev_b32_e32 v206, 16, v220
	v_and_b32_e32 v207, 0xffff0000, v220
	v_lshlrev_b32_e32 v208, 16, v221
	v_and_b32_e32 v209, 0xffff0000, v221
	v_lshlrev_b32_e32 v210, 16, v222
	v_and_b32_e32 v211, 0xffff0000, v222
	v_lshlrev_b32_e32 v212, 16, v223
	v_and_b32_e32 v213, 0xffff0000, v223
	v_sub_f32_e32 v206, v206, v176
	v_sub_f32_e32 v207, v207, v176
	v_sub_f32_e32 v208, v208, v176
	v_sub_f32_e32 v209, v209, v176
	v_sub_f32_e32 v210, v210, v176
	v_sub_f32_e32 v211, v211, v176
	v_sub_f32_e32 v212, v212, v176
	v_sub_f32_e32 v213, v213, v176
	v_pk_mul_f32 v[206:207], v[176:177], v[206:207] op_sel:[1,0]
	v_pk_mul_f32 v[208:209], v[176:177], v[208:209] op_sel:[1,0]
	v_pk_mul_f32 v[210:211], v[176:177], v[210:211] op_sel:[1,0]
	v_pk_mul_f32 v[212:213], v[176:177], v[212:213] op_sel:[1,0]
	v_pk_fma_f32 v[206:207], v[98:99], v[206:207], v[102:103]
	v_pk_fma_f32 v[208:209], v[100:101], v[208:209], v[104:105]
	v_pk_fma_f32 v[210:211], v[90:91], v[210:211], v[94:95]
	v_pk_fma_f32 v[212:213], v[92:93], v[212:213], v[96:97]
	v_pk_fma_f32 v[206:207], v[206:207], s[66:67], v[142:143] op_sel_hi:[1,0,1]
	v_pk_fma_f32 v[208:209], v[208:209], s[66:67], v[144:145] op_sel_hi:[1,0,1]
	v_pk_fma_f32 v[210:211], v[210:211], s[66:67], v[138:139] op_sel_hi:[1,0,1]
	v_pk_fma_f32 v[212:213], v[212:213], s[66:67], v[140:141] op_sel_hi:[1,0,1]
	v_cvt_pk_bf16_f32 v220, v206, v207
	v_cvt_pk_bf16_f32 v221, v208, v209
	v_cvt_pk_bf16_f32 v222, v210, v211
	v_cvt_pk_bf16_f32 v223, v212, v213
	s_add_u32 s48, s72, 0x0
	s_addc_u32 s49, s73, 0
	global_store_dwordx4 v170, v[220:223], s[48:49]
	s_waitcnt vmcnt(13)
	v_lshlrev_b32_e32 v206, 16, v224
	v_and_b32_e32 v207, 0xffff0000, v224
	v_lshlrev_b32_e32 v208, 16, v225
	v_and_b32_e32 v209, 0xffff0000, v225
	v_lshlrev_b32_e32 v210, 16, v226
	v_and_b32_e32 v211, 0xffff0000, v226
	v_lshlrev_b32_e32 v212, 16, v227
	v_and_b32_e32 v213, 0xffff0000, v227
	v_sub_f32_e32 v206, v206, v180
	v_sub_f32_e32 v207, v207, v180
	v_sub_f32_e32 v208, v208, v180
	v_sub_f32_e32 v209, v209, v180
	v_sub_f32_e32 v210, v210, v180
	v_sub_f32_e32 v211, v211, v180
	v_sub_f32_e32 v212, v212, v180
	v_sub_f32_e32 v213, v213, v180
	v_pk_mul_f32 v[206:207], v[180:181], v[206:207] op_sel:[1,0]
	v_pk_mul_f32 v[208:209], v[180:181], v[208:209] op_sel:[1,0]
	v_pk_mul_f32 v[210:211], v[180:181], v[210:211] op_sel:[1,0]
	v_pk_mul_f32 v[212:213], v[180:181], v[212:213] op_sel:[1,0]
	v_pk_fma_f32 v[206:207], v[98:99], v[206:207], v[102:103]
	v_pk_fma_f32 v[208:209], v[100:101], v[208:209], v[104:105]
	v_pk_fma_f32 v[210:211], v[90:91], v[210:211], v[94:95]
	v_pk_fma_f32 v[212:213], v[92:93], v[212:213], v[96:97]
	v_pk_fma_f32 v[206:207], v[206:207], s[66:67], v[134:135] op_sel_hi:[1,0,1]
	v_pk_fma_f32 v[208:209], v[208:209], s[66:67], v[136:137] op_sel_hi:[1,0,1]
	v_pk_fma_f32 v[210:211], v[210:211], s[66:67], v[130:131] op_sel_hi:[1,0,1]
	v_pk_fma_f32 v[212:213], v[212:213], s[66:67], v[132:133] op_sel_hi:[1,0,1]
	v_cvt_pk_bf16_f32 v224, v206, v207
	v_cvt_pk_bf16_f32 v225, v208, v209
	v_cvt_pk_bf16_f32 v226, v210, v211
	v_cvt_pk_bf16_f32 v227, v212, v213
	s_add_u32 s48, s72, 0x10000
	s_addc_u32 s49, s73, 0
	global_store_dwordx4 v170, v[224:227], s[48:49]
	s_waitcnt vmcnt(12)
	v_lshlrev_b32_e32 v206, 16, v228
	v_and_b32_e32 v207, 0xffff0000, v228
	v_lshlrev_b32_e32 v208, 16, v229
	v_and_b32_e32 v209, 0xffff0000, v229
	v_lshlrev_b32_e32 v210, 16, v230
	v_and_b32_e32 v211, 0xffff0000, v230
	v_lshlrev_b32_e32 v212, 16, v231
	v_and_b32_e32 v213, 0xffff0000, v231
	v_sub_f32_e32 v206, v206, v182
	v_sub_f32_e32 v207, v207, v182
	v_sub_f32_e32 v208, v208, v182
	v_sub_f32_e32 v209, v209, v182
	v_sub_f32_e32 v210, v210, v182
	v_sub_f32_e32 v211, v211, v182
	v_sub_f32_e32 v212, v212, v182
	v_sub_f32_e32 v213, v213, v182
	v_pk_mul_f32 v[206:207], v[182:183], v[206:207] op_sel:[1,0]
	v_pk_mul_f32 v[208:209], v[182:183], v[208:209] op_sel:[1,0]
	v_pk_mul_f32 v[210:211], v[182:183], v[210:211] op_sel:[1,0]
	v_pk_mul_f32 v[212:213], v[182:183], v[212:213] op_sel:[1,0]
	v_pk_fma_f32 v[206:207], v[98:99], v[206:207], v[102:103]
	v_pk_fma_f32 v[208:209], v[100:101], v[208:209], v[104:105]
	v_pk_fma_f32 v[210:211], v[90:91], v[210:211], v[94:95]
	v_pk_fma_f32 v[212:213], v[92:93], v[212:213], v[96:97]
	v_pk_fma_f32 v[206:207], v[206:207], s[66:67], v[126:127] op_sel_hi:[1,0,1]
	v_pk_fma_f32 v[208:209], v[208:209], s[66:67], v[128:129] op_sel_hi:[1,0,1]
	v_pk_fma_f32 v[210:211], v[210:211], s[66:67], v[122:123] op_sel_hi:[1,0,1]
	v_pk_fma_f32 v[212:213], v[212:213], s[66:67], v[124:125] op_sel_hi:[1,0,1]
	v_cvt_pk_bf16_f32 v228, v206, v207
	v_cvt_pk_bf16_f32 v229, v208, v209
	v_cvt_pk_bf16_f32 v230, v210, v211
	v_cvt_pk_bf16_f32 v231, v212, v213
	s_add_u32 s48, s72, 0x20000
	s_addc_u32 s49, s73, 0
	global_store_dwordx4 v170, v[228:231], s[48:49]
	s_waitcnt vmcnt(11)
	v_lshlrev_b32_e32 v206, 16, v232
	v_and_b32_e32 v207, 0xffff0000, v232
	v_lshlrev_b32_e32 v208, 16, v233
	v_and_b32_e32 v209, 0xffff0000, v233
	v_lshlrev_b32_e32 v210, 16, v234
	v_and_b32_e32 v211, 0xffff0000, v234
	v_lshlrev_b32_e32 v212, 16, v235
	v_and_b32_e32 v213, 0xffff0000, v235
	v_sub_f32_e32 v206, v206, v184
	v_sub_f32_e32 v207, v207, v184
	v_sub_f32_e32 v208, v208, v184
	v_sub_f32_e32 v209, v209, v184
	v_sub_f32_e32 v210, v210, v184
	v_sub_f32_e32 v211, v211, v184
	v_sub_f32_e32 v212, v212, v184
	v_sub_f32_e32 v213, v213, v184
	v_pk_mul_f32 v[206:207], v[184:185], v[206:207] op_sel:[1,0]
	v_pk_mul_f32 v[208:209], v[184:185], v[208:209] op_sel:[1,0]
	v_pk_mul_f32 v[210:211], v[184:185], v[210:211] op_sel:[1,0]
	v_pk_mul_f32 v[212:213], v[184:185], v[212:213] op_sel:[1,0]
	v_pk_fma_f32 v[206:207], v[98:99], v[206:207], v[102:103]
	v_pk_fma_f32 v[208:209], v[100:101], v[208:209], v[104:105]
	v_pk_fma_f32 v[210:211], v[90:91], v[210:211], v[94:95]
	v_pk_fma_f32 v[212:213], v[92:93], v[212:213], v[96:97]
	v_pk_fma_f32 v[206:207], v[206:207], s[66:67], v[118:119] op_sel_hi:[1,0,1]
	v_pk_fma_f32 v[208:209], v[208:209], s[66:67], v[120:121] op_sel_hi:[1,0,1]
	v_pk_fma_f32 v[210:211], v[210:211], s[66:67], v[114:115] op_sel_hi:[1,0,1]
	v_pk_fma_f32 v[212:213], v[212:213], s[66:67], v[116:117] op_sel_hi:[1,0,1]
	v_cvt_pk_bf16_f32 v232, v206, v207
	v_cvt_pk_bf16_f32 v233, v208, v209
	v_cvt_pk_bf16_f32 v234, v210, v211
	v_cvt_pk_bf16_f32 v235, v212, v213
	s_add_u32 s48, s72, 0x30000
	s_addc_u32 s49, s73, 0
	global_store_dwordx4 v170, v[232:235], s[48:49]
	s_waitcnt vmcnt(10)
	v_lshlrev_b32_e32 v206, 16, v236
	v_and_b32_e32 v207, 0xffff0000, v236
	v_lshlrev_b32_e32 v208, 16, v237
	v_and_b32_e32 v209, 0xffff0000, v237
	v_lshlrev_b32_e32 v210, 16, v238
	v_and_b32_e32 v211, 0xffff0000, v238
	v_lshlrev_b32_e32 v212, 16, v239
	v_and_b32_e32 v213, 0xffff0000, v239
	v_sub_f32_e32 v206, v206, v168
	v_sub_f32_e32 v207, v207, v168
	v_sub_f32_e32 v208, v208, v168
	v_sub_f32_e32 v209, v209, v168
	v_sub_f32_e32 v210, v210, v168
	v_sub_f32_e32 v211, v211, v168
	v_sub_f32_e32 v212, v212, v168
	v_sub_f32_e32 v213, v213, v168
	v_pk_mul_f32 v[206:207], v[168:169], v[206:207] op_sel:[1,0]
	v_pk_mul_f32 v[208:209], v[168:169], v[208:209] op_sel:[1,0]
	v_pk_mul_f32 v[210:211], v[168:169], v[210:211] op_sel:[1,0]
	v_pk_mul_f32 v[212:213], v[168:169], v[212:213] op_sel:[1,0]
	v_pk_fma_f32 v[206:207], v[98:99], v[206:207], v[102:103]
	v_pk_fma_f32 v[208:209], v[100:101], v[208:209], v[104:105]
	v_pk_fma_f32 v[210:211], v[90:91], v[210:211], v[94:95]
	v_pk_fma_f32 v[212:213], v[92:93], v[212:213], v[96:97]
	v_pk_fma_f32 v[206:207], v[206:207], s[66:67], v[110:111] op_sel_hi:[1,0,1]
	v_pk_fma_f32 v[208:209], v[208:209], s[66:67], v[112:113] op_sel_hi:[1,0,1]
	v_pk_fma_f32 v[210:211], v[210:211], s[66:67], v[106:107] op_sel_hi:[1,0,1]
	v_pk_fma_f32 v[212:213], v[212:213], s[66:67], v[108:109] op_sel_hi:[1,0,1]
	v_cvt_pk_bf16_f32 v236, v206, v207
	v_cvt_pk_bf16_f32 v237, v208, v209
	v_cvt_pk_bf16_f32 v238, v210, v211
	v_cvt_pk_bf16_f32 v239, v212, v213
	s_add_u32 s48, s72, 0x80000
	s_addc_u32 s49, s73, 0
	global_store_dwordx4 v170, v[236:239], s[48:49]
	s_waitcnt vmcnt(9)
	v_lshlrev_b32_e32 v206, 16, v240
	v_and_b32_e32 v207, 0xffff0000, v240
	v_lshlrev_b32_e32 v208, 16, v241
	v_and_b32_e32 v209, 0xffff0000, v241
	v_lshlrev_b32_e32 v210, 16, v242
	v_and_b32_e32 v211, 0xffff0000, v242
	v_lshlrev_b32_e32 v212, 16, v243
	v_and_b32_e32 v213, 0xffff0000, v243
	v_sub_f32_e32 v206, v206, v252
	v_sub_f32_e32 v207, v207, v252
	v_sub_f32_e32 v208, v208, v252
	v_sub_f32_e32 v209, v209, v252
	v_sub_f32_e32 v210, v210, v252
	v_sub_f32_e32 v211, v211, v252
	v_sub_f32_e32 v212, v212, v252
	v_sub_f32_e32 v213, v213, v252
	v_pk_mul_f32 v[206:207], v[252:253], v[206:207] op_sel:[1,0]
	v_pk_mul_f32 v[208:209], v[252:253], v[208:209] op_sel:[1,0]
	v_pk_mul_f32 v[210:211], v[252:253], v[210:211] op_sel:[1,0]
	v_pk_mul_f32 v[212:213], v[252:253], v[212:213] op_sel:[1,0]
	v_pk_fma_f32 v[206:207], v[98:99], v[206:207], v[102:103]
	v_pk_fma_f32 v[208:209], v[100:101], v[208:209], v[104:105]
	v_pk_fma_f32 v[210:211], v[90:91], v[210:211], v[94:95]
	v_pk_fma_f32 v[212:213], v[92:93], v[212:213], v[96:97]
	v_pk_fma_f32 v[206:207], v[206:207], s[66:67], v[86:87] op_sel_hi:[1,0,1]
	v_pk_fma_f32 v[208:209], v[208:209], s[66:67], v[88:89] op_sel_hi:[1,0,1]
	v_pk_fma_f32 v[210:211], v[210:211], s[66:67], v[82:83] op_sel_hi:[1,0,1]
	v_pk_fma_f32 v[212:213], v[212:213], s[66:67], v[84:85] op_sel_hi:[1,0,1]
	v_cvt_pk_bf16_f32 v240, v206, v207
	v_cvt_pk_bf16_f32 v241, v208, v209
	v_cvt_pk_bf16_f32 v242, v210, v211
	v_cvt_pk_bf16_f32 v243, v212, v213
	s_add_u32 s48, s72, 0x90000
	s_addc_u32 s49, s73, 0
	global_store_dwordx4 v170, v[240:243], s[48:49]
	s_waitcnt vmcnt(8)
	v_lshlrev_b32_e32 v206, 16, v244
	v_and_b32_e32 v207, 0xffff0000, v244
	v_lshlrev_b32_e32 v208, 16, v245
	v_and_b32_e32 v209, 0xffff0000, v245
	v_lshlrev_b32_e32 v210, 16, v246
	v_and_b32_e32 v211, 0xffff0000, v246
	v_lshlrev_b32_e32 v212, 16, v247
	v_and_b32_e32 v213, 0xffff0000, v247
	v_sub_f32_e32 v206, v206, v214
	v_sub_f32_e32 v207, v207, v214
	v_sub_f32_e32 v208, v208, v214
	v_sub_f32_e32 v209, v209, v214
	v_sub_f32_e32 v210, v210, v214
	v_sub_f32_e32 v211, v211, v214
	v_sub_f32_e32 v212, v212, v214
	v_sub_f32_e32 v213, v213, v214
	v_pk_mul_f32 v[206:207], v[214:215], v[206:207] op_sel:[1,0]
	v_pk_mul_f32 v[208:209], v[214:215], v[208:209] op_sel:[1,0]
	v_pk_mul_f32 v[210:211], v[214:215], v[210:211] op_sel:[1,0]
	v_pk_mul_f32 v[212:213], v[214:215], v[212:213] op_sel:[1,0]
	v_pk_fma_f32 v[206:207], v[98:99], v[206:207], v[102:103]
	v_pk_fma_f32 v[208:209], v[100:101], v[208:209], v[104:105]
	v_pk_fma_f32 v[210:211], v[90:91], v[210:211], v[94:95]
	v_pk_fma_f32 v[212:213], v[92:93], v[212:213], v[96:97]
	v_pk_fma_f32 v[206:207], v[206:207], s[66:67], v[78:79] op_sel_hi:[1,0,1]
	v_pk_fma_f32 v[208:209], v[208:209], s[66:67], v[80:81] op_sel_hi:[1,0,1]
	v_pk_fma_f32 v[210:211], v[210:211], s[66:67], v[74:75] op_sel_hi:[1,0,1]
	v_pk_fma_f32 v[212:213], v[212:213], s[66:67], v[76:77] op_sel_hi:[1,0,1]
	v_cvt_pk_bf16_f32 v244, v206, v207
	v_cvt_pk_bf16_f32 v245, v208, v209
	v_cvt_pk_bf16_f32 v246, v210, v211
	v_cvt_pk_bf16_f32 v247, v212, v213
	s_add_u32 s48, s72, 0xa0000
	s_addc_u32 s49, s73, 0
	global_store_dwordx4 v170, v[244:247], s[48:49]
	s_waitcnt vmcnt(7)
	v_lshlrev_b32_e32 v206, 16, v248
	v_and_b32_e32 v207, 0xffff0000, v248
	v_lshlrev_b32_e32 v208, 16, v249
	v_and_b32_e32 v209, 0xffff0000, v249
	v_lshlrev_b32_e32 v210, 16, v250
	v_and_b32_e32 v211, 0xffff0000, v250
	v_lshlrev_b32_e32 v212, 16, v251
	v_and_b32_e32 v213, 0xffff0000, v251
	v_sub_f32_e32 v206, v206, v216
	v_sub_f32_e32 v207, v207, v216
	v_sub_f32_e32 v208, v208, v216
	v_sub_f32_e32 v209, v209, v216
	v_sub_f32_e32 v210, v210, v216
	v_sub_f32_e32 v211, v211, v216
	v_sub_f32_e32 v212, v212, v216
	v_sub_f32_e32 v213, v213, v216
	v_pk_mul_f32 v[206:207], v[216:217], v[206:207] op_sel:[1,0]
	v_pk_mul_f32 v[208:209], v[216:217], v[208:209] op_sel:[1,0]
	v_pk_mul_f32 v[210:211], v[216:217], v[210:211] op_sel:[1,0]
	v_pk_mul_f32 v[212:213], v[216:217], v[212:213] op_sel:[1,0]
	v_pk_fma_f32 v[206:207], v[98:99], v[206:207], v[102:103]
	v_pk_fma_f32 v[208:209], v[100:101], v[208:209], v[104:105]
	v_pk_fma_f32 v[210:211], v[90:91], v[210:211], v[94:95]
	v_pk_fma_f32 v[212:213], v[92:93], v[212:213], v[96:97]
	v_pk_fma_f32 v[206:207], v[206:207], s[66:67], v[70:71] op_sel_hi:[1,0,1]
	v_pk_fma_f32 v[208:209], v[208:209], s[66:67], v[72:73] op_sel_hi:[1,0,1]
	v_pk_fma_f32 v[210:211], v[210:211], s[66:67], v[66:67] op_sel_hi:[1,0,1]
	v_pk_fma_f32 v[212:213], v[212:213], s[66:67], v[68:69] op_sel_hi:[1,0,1]
	v_cvt_pk_bf16_f32 v248, v206, v207
	v_cvt_pk_bf16_f32 v249, v208, v209
	v_cvt_pk_bf16_f32 v250, v210, v211
	v_cvt_pk_bf16_f32 v251, v212, v213
	s_add_u32 s48, s72, 0xb0000
	s_addc_u32 s49, s73, 0
	global_store_dwordx4 v170, v[248:251], s[48:49]
	global_load_dwordx4 v[98:101], v174, s[74:75] offset:512
	global_load_dwordx4 v[90:93], v174, s[74:75] offset:528
	global_load_dwordx4 v[102:105], v174, s[76:77] offset:512
	global_load_dwordx4 v[94:97], v174, s[76:77] offset:528
	s_add_u32 s48, s72, 0x100
	s_addc_u32 s49, s73, 0
	global_load_dwordx4 v[220:223], v170, s[48:49]
	s_add_u32 s50, s14, 0x0
	s_addc_u32 s51, s15, 0
	global_load_dwordx2 v[176:177], v171, s[50:51]
	s_add_u32 s48, s72, 0x10100
	s_addc_u32 s49, s73, 0
	global_load_dwordx4 v[224:227], v170, s[48:49]
	s_add_u32 s50, s14, 0x80
	s_addc_u32 s51, s15, 0
	global_load_dwordx2 v[180:181], v171, s[50:51]
	s_add_u32 s48, s72, 0x20100
	s_addc_u32 s49, s73, 0
	global_load_dwordx4 v[228:231], v170, s[48:49]
	s_add_u32 s50, s14, 0x100
	s_addc_u32 s51, s15, 0
	global_load_dwordx2 v[182:183], v171, s[50:51]
	s_add_u32 s48, s72, 0x30100
	s_addc_u32 s49, s73, 0
	global_load_dwordx4 v[232:235], v170, s[48:49]
	s_add_u32 s50, s14, 0x180
	s_addc_u32 s51, s15, 0
	global_load_dwordx2 v[184:185], v171, s[50:51]
	s_add_u32 s48, s72, 0x80100
	s_addc_u32 s49, s73, 0
	global_load_dwordx4 v[236:239], v170, s[48:49]
	s_add_u32 s50, s14, 0x400
	s_addc_u32 s51, s15, 0
	global_load_dwordx2 v[168:169], v171, s[50:51]
	s_add_u32 s48, s72, 0x90100
	s_addc_u32 s49, s73, 0
	global_load_dwordx4 v[240:243], v170, s[48:49]
	s_add_u32 s50, s14, 0x480
	s_addc_u32 s51, s15, 0
	global_load_dwordx2 v[252:253], v171, s[50:51]
	s_add_u32 s48, s72, 0xa0100
	s_addc_u32 s49, s73, 0
	global_load_dwordx4 v[244:247], v170, s[48:49]
	s_add_u32 s50, s14, 0x500
	s_addc_u32 s51, s15, 0
	global_load_dwordx2 v[214:215], v171, s[50:51]
	s_add_u32 s48, s72, 0xb0100
	s_addc_u32 s49, s73, 0
	global_load_dwordx4 v[248:251], v170, s[48:49]
	s_add_u32 s50, s14, 0x580
	s_addc_u32 s51, s15, 0
	global_load_dwordx2 v[216:217], v171, s[50:51]
	s_waitcnt vmcnt(14)
	v_lshlrev_b32_e32 v206, 16, v220
	v_and_b32_e32 v207, 0xffff0000, v220
	v_lshlrev_b32_e32 v208, 16, v221
	v_and_b32_e32 v209, 0xffff0000, v221
	v_lshlrev_b32_e32 v210, 16, v222
	v_and_b32_e32 v211, 0xffff0000, v222
	v_lshlrev_b32_e32 v212, 16, v223
	v_and_b32_e32 v213, 0xffff0000, v223
	v_sub_f32_e32 v206, v206, v176
	v_sub_f32_e32 v207, v207, v176
	v_sub_f32_e32 v208, v208, v176
	v_sub_f32_e32 v209, v209, v176
	v_sub_f32_e32 v210, v210, v176
	v_sub_f32_e32 v211, v211, v176
	v_sub_f32_e32 v212, v212, v176
	v_sub_f32_e32 v213, v213, v176
	v_pk_mul_f32 v[206:207], v[176:177], v[206:207] op_sel:[1,0]
	v_pk_mul_f32 v[208:209], v[176:177], v[208:209] op_sel:[1,0]
	v_pk_mul_f32 v[210:211], v[176:177], v[210:211] op_sel:[1,0]
	v_pk_mul_f32 v[212:213], v[176:177], v[212:213] op_sel:[1,0]
	v_pk_fma_f32 v[206:207], v[98:99], v[206:207], v[102:103]
	v_pk_fma_f32 v[208:209], v[100:101], v[208:209], v[104:105]
	v_pk_fma_f32 v[210:211], v[90:91], v[210:211], v[94:95]
	v_pk_fma_f32 v[212:213], v[92:93], v[212:213], v[96:97]
	v_pk_fma_f32 v[206:207], v[206:207], s[66:67], v[62:63] op_sel_hi:[1,0,1]
	v_pk_fma_f32 v[208:209], v[208:209], s[66:67], v[64:65] op_sel_hi:[1,0,1]
	v_pk_fma_f32 v[210:211], v[210:211], s[66:67], v[58:59] op_sel_hi:[1,0,1]
	v_pk_fma_f32 v[212:213], v[212:213], s[66:67], v[60:61] op_sel_hi:[1,0,1]
	v_cvt_pk_bf16_f32 v220, v206, v207
	v_cvt_pk_bf16_f32 v221, v208, v209
	v_cvt_pk_bf16_f32 v222, v210, v211
	v_cvt_pk_bf16_f32 v223, v212, v213
	s_add_u32 s48, s72, 0x100
	s_addc_u32 s49, s73, 0
	global_store_dwordx4 v170, v[220:223], s[48:49]
	s_waitcnt vmcnt(13)
	v_lshlrev_b32_e32 v206, 16, v224
	v_and_b32_e32 v207, 0xffff0000, v224
	v_lshlrev_b32_e32 v208, 16, v225
	v_and_b32_e32 v209, 0xffff0000, v225
	v_lshlrev_b32_e32 v210, 16, v226
	v_and_b32_e32 v211, 0xffff0000, v226
	v_lshlrev_b32_e32 v212, 16, v227
	v_and_b32_e32 v213, 0xffff0000, v227
	v_sub_f32_e32 v206, v206, v180
	v_sub_f32_e32 v207, v207, v180
	v_sub_f32_e32 v208, v208, v180
	v_sub_f32_e32 v209, v209, v180
	v_sub_f32_e32 v210, v210, v180
	v_sub_f32_e32 v211, v211, v180
	v_sub_f32_e32 v212, v212, v180
	v_sub_f32_e32 v213, v213, v180
	v_pk_mul_f32 v[206:207], v[180:181], v[206:207] op_sel:[1,0]
	v_pk_mul_f32 v[208:209], v[180:181], v[208:209] op_sel:[1,0]
	v_pk_mul_f32 v[210:211], v[180:181], v[210:211] op_sel:[1,0]
	v_pk_mul_f32 v[212:213], v[180:181], v[212:213] op_sel:[1,0]
	v_pk_fma_f32 v[206:207], v[98:99], v[206:207], v[102:103]
	v_pk_fma_f32 v[208:209], v[100:101], v[208:209], v[104:105]
	v_pk_fma_f32 v[210:211], v[90:91], v[210:211], v[94:95]
	v_pk_fma_f32 v[212:213], v[92:93], v[212:213], v[96:97]
	v_pk_fma_f32 v[206:207], v[206:207], s[66:67], v[54:55] op_sel_hi:[1,0,1]
	v_pk_fma_f32 v[208:209], v[208:209], s[66:67], v[56:57] op_sel_hi:[1,0,1]
	v_pk_fma_f32 v[210:211], v[210:211], s[66:67], v[50:51] op_sel_hi:[1,0,1]
	v_pk_fma_f32 v[212:213], v[212:213], s[66:67], v[52:53] op_sel_hi:[1,0,1]
	v_cvt_pk_bf16_f32 v224, v206, v207
	v_cvt_pk_bf16_f32 v225, v208, v209
	v_cvt_pk_bf16_f32 v226, v210, v211
	v_cvt_pk_bf16_f32 v227, v212, v213
	s_add_u32 s48, s72, 0x10100
	s_addc_u32 s49, s73, 0
	global_store_dwordx4 v170, v[224:227], s[48:49]
	s_waitcnt vmcnt(12)
	v_lshlrev_b32_e32 v206, 16, v228
	v_and_b32_e32 v207, 0xffff0000, v228
	v_lshlrev_b32_e32 v208, 16, v229
	v_and_b32_e32 v209, 0xffff0000, v229
	v_lshlrev_b32_e32 v210, 16, v230
	v_and_b32_e32 v211, 0xffff0000, v230
	v_lshlrev_b32_e32 v212, 16, v231
	v_and_b32_e32 v213, 0xffff0000, v231
	v_sub_f32_e32 v206, v206, v182
	v_sub_f32_e32 v207, v207, v182
	v_sub_f32_e32 v208, v208, v182
	v_sub_f32_e32 v209, v209, v182
	v_sub_f32_e32 v210, v210, v182
	v_sub_f32_e32 v211, v211, v182
	v_sub_f32_e32 v212, v212, v182
	v_sub_f32_e32 v213, v213, v182
	v_pk_mul_f32 v[206:207], v[182:183], v[206:207] op_sel:[1,0]
	v_pk_mul_f32 v[208:209], v[182:183], v[208:209] op_sel:[1,0]
	v_pk_mul_f32 v[210:211], v[182:183], v[210:211] op_sel:[1,0]
	v_pk_mul_f32 v[212:213], v[182:183], v[212:213] op_sel:[1,0]
	v_pk_fma_f32 v[206:207], v[98:99], v[206:207], v[102:103]
	v_pk_fma_f32 v[208:209], v[100:101], v[208:209], v[104:105]
	v_pk_fma_f32 v[210:211], v[90:91], v[210:211], v[94:95]
	v_pk_fma_f32 v[212:213], v[92:93], v[212:213], v[96:97]
	v_pk_fma_f32 v[206:207], v[206:207], s[66:67], v[46:47] op_sel_hi:[1,0,1]
	v_pk_fma_f32 v[208:209], v[208:209], s[66:67], v[48:49] op_sel_hi:[1,0,1]
	v_pk_fma_f32 v[210:211], v[210:211], s[66:67], v[42:43] op_sel_hi:[1,0,1]
	v_pk_fma_f32 v[212:213], v[212:213], s[66:67], v[44:45] op_sel_hi:[1,0,1]
	v_cvt_pk_bf16_f32 v228, v206, v207
	v_cvt_pk_bf16_f32 v229, v208, v209
	v_cvt_pk_bf16_f32 v230, v210, v211
	v_cvt_pk_bf16_f32 v231, v212, v213
	s_add_u32 s48, s72, 0x20100
	s_addc_u32 s49, s73, 0
	global_store_dwordx4 v170, v[228:231], s[48:49]
	s_waitcnt vmcnt(11)
	v_lshlrev_b32_e32 v206, 16, v232
	v_and_b32_e32 v207, 0xffff0000, v232
	v_lshlrev_b32_e32 v208, 16, v233
	v_and_b32_e32 v209, 0xffff0000, v233
	v_lshlrev_b32_e32 v210, 16, v234
	v_and_b32_e32 v211, 0xffff0000, v234
	v_lshlrev_b32_e32 v212, 16, v235
	v_and_b32_e32 v213, 0xffff0000, v235
	v_sub_f32_e32 v206, v206, v184
	v_sub_f32_e32 v207, v207, v184
	v_sub_f32_e32 v208, v208, v184
	v_sub_f32_e32 v209, v209, v184
	v_sub_f32_e32 v210, v210, v184
	v_sub_f32_e32 v211, v211, v184
	v_sub_f32_e32 v212, v212, v184
	v_sub_f32_e32 v213, v213, v184
	v_pk_mul_f32 v[206:207], v[184:185], v[206:207] op_sel:[1,0]
	v_pk_mul_f32 v[208:209], v[184:185], v[208:209] op_sel:[1,0]
	v_pk_mul_f32 v[210:211], v[184:185], v[210:211] op_sel:[1,0]
	v_pk_mul_f32 v[212:213], v[184:185], v[212:213] op_sel:[1,0]
	v_pk_fma_f32 v[206:207], v[98:99], v[206:207], v[102:103]
	v_pk_fma_f32 v[208:209], v[100:101], v[208:209], v[104:105]
	v_pk_fma_f32 v[210:211], v[90:91], v[210:211], v[94:95]
	v_pk_fma_f32 v[212:213], v[92:93], v[212:213], v[96:97]
	v_pk_fma_f32 v[206:207], v[206:207], s[66:67], v[38:39] op_sel_hi:[1,0,1]
	v_pk_fma_f32 v[208:209], v[208:209], s[66:67], v[40:41] op_sel_hi:[1,0,1]
	v_pk_fma_f32 v[210:211], v[210:211], s[66:67], v[34:35] op_sel_hi:[1,0,1]
	v_pk_fma_f32 v[212:213], v[212:213], s[66:67], v[36:37] op_sel_hi:[1,0,1]
	v_cvt_pk_bf16_f32 v232, v206, v207
	v_cvt_pk_bf16_f32 v233, v208, v209
	v_cvt_pk_bf16_f32 v234, v210, v211
	v_cvt_pk_bf16_f32 v235, v212, v213
	s_add_u32 s48, s72, 0x30100
	s_addc_u32 s49, s73, 0
	global_store_dwordx4 v170, v[232:235], s[48:49]
	s_waitcnt vmcnt(10)
	v_lshlrev_b32_e32 v206, 16, v236
	v_and_b32_e32 v207, 0xffff0000, v236
	v_lshlrev_b32_e32 v208, 16, v237
	v_and_b32_e32 v209, 0xffff0000, v237
	v_lshlrev_b32_e32 v210, 16, v238
	v_and_b32_e32 v211, 0xffff0000, v238
	v_lshlrev_b32_e32 v212, 16, v239
	v_and_b32_e32 v213, 0xffff0000, v239
	v_sub_f32_e32 v206, v206, v168
	v_sub_f32_e32 v207, v207, v168
	v_sub_f32_e32 v208, v208, v168
	v_sub_f32_e32 v209, v209, v168
	v_sub_f32_e32 v210, v210, v168
	v_sub_f32_e32 v211, v211, v168
	v_sub_f32_e32 v212, v212, v168
	v_sub_f32_e32 v213, v213, v168
	v_pk_mul_f32 v[206:207], v[168:169], v[206:207] op_sel:[1,0]
	v_pk_mul_f32 v[208:209], v[168:169], v[208:209] op_sel:[1,0]
	v_pk_mul_f32 v[210:211], v[168:169], v[210:211] op_sel:[1,0]
	v_pk_mul_f32 v[212:213], v[168:169], v[212:213] op_sel:[1,0]
	v_pk_fma_f32 v[206:207], v[98:99], v[206:207], v[102:103]
	v_pk_fma_f32 v[208:209], v[100:101], v[208:209], v[104:105]
	v_pk_fma_f32 v[210:211], v[90:91], v[210:211], v[94:95]
	v_pk_fma_f32 v[212:213], v[92:93], v[212:213], v[96:97]
	v_pk_fma_f32 v[206:207], v[206:207], s[66:67], v[30:31] op_sel_hi:[1,0,1]
	v_pk_fma_f32 v[208:209], v[208:209], s[66:67], v[32:33] op_sel_hi:[1,0,1]
	v_pk_fma_f32 v[210:211], v[210:211], s[66:67], v[26:27] op_sel_hi:[1,0,1]
	v_pk_fma_f32 v[212:213], v[212:213], s[66:67], v[28:29] op_sel_hi:[1,0,1]
	v_cvt_pk_bf16_f32 v236, v206, v207
	v_cvt_pk_bf16_f32 v237, v208, v209
	v_cvt_pk_bf16_f32 v238, v210, v211
	v_cvt_pk_bf16_f32 v239, v212, v213
	s_add_u32 s48, s72, 0x80100
	s_addc_u32 s49, s73, 0
	global_store_dwordx4 v170, v[236:239], s[48:49]
	s_waitcnt vmcnt(9)
	v_lshlrev_b32_e32 v206, 16, v240
	v_and_b32_e32 v207, 0xffff0000, v240
	v_lshlrev_b32_e32 v208, 16, v241
	v_and_b32_e32 v209, 0xffff0000, v241
	v_lshlrev_b32_e32 v210, 16, v242
	v_and_b32_e32 v211, 0xffff0000, v242
	v_lshlrev_b32_e32 v212, 16, v243
	v_and_b32_e32 v213, 0xffff0000, v243
	v_sub_f32_e32 v206, v206, v252
	v_sub_f32_e32 v207, v207, v252
	v_sub_f32_e32 v208, v208, v252
	v_sub_f32_e32 v209, v209, v252
	v_sub_f32_e32 v210, v210, v252
	v_sub_f32_e32 v211, v211, v252
	v_sub_f32_e32 v212, v212, v252
	v_sub_f32_e32 v213, v213, v252
	v_pk_mul_f32 v[206:207], v[252:253], v[206:207] op_sel:[1,0]
	v_pk_mul_f32 v[208:209], v[252:253], v[208:209] op_sel:[1,0]
	v_pk_mul_f32 v[210:211], v[252:253], v[210:211] op_sel:[1,0]
	v_pk_mul_f32 v[212:213], v[252:253], v[212:213] op_sel:[1,0]
	v_pk_fma_f32 v[206:207], v[98:99], v[206:207], v[102:103]
	v_pk_fma_f32 v[208:209], v[100:101], v[208:209], v[104:105]
	v_pk_fma_f32 v[210:211], v[90:91], v[210:211], v[94:95]
	v_pk_fma_f32 v[212:213], v[92:93], v[212:213], v[96:97]
	v_pk_fma_f32 v[206:207], v[206:207], s[66:67], v[22:23] op_sel_hi:[1,0,1]
	v_pk_fma_f32 v[208:209], v[208:209], s[66:67], v[24:25] op_sel_hi:[1,0,1]
	v_pk_fma_f32 v[210:211], v[210:211], s[66:67], v[18:19] op_sel_hi:[1,0,1]
	v_pk_fma_f32 v[212:213], v[212:213], s[66:67], v[20:21] op_sel_hi:[1,0,1]
	v_cvt_pk_bf16_f32 v240, v206, v207
	v_cvt_pk_bf16_f32 v241, v208, v209
	v_cvt_pk_bf16_f32 v242, v210, v211
	v_cvt_pk_bf16_f32 v243, v212, v213
	s_add_u32 s48, s72, 0x90100
	s_addc_u32 s49, s73, 0
	global_store_dwordx4 v170, v[240:243], s[48:49]
	s_waitcnt vmcnt(8)
	v_lshlrev_b32_e32 v206, 16, v244
	v_and_b32_e32 v207, 0xffff0000, v244
	v_lshlrev_b32_e32 v208, 16, v245
	v_and_b32_e32 v209, 0xffff0000, v245
	v_lshlrev_b32_e32 v210, 16, v246
	v_and_b32_e32 v211, 0xffff0000, v246
	v_lshlrev_b32_e32 v212, 16, v247
	v_and_b32_e32 v213, 0xffff0000, v247
	v_sub_f32_e32 v206, v206, v214
	v_sub_f32_e32 v207, v207, v214
	v_sub_f32_e32 v208, v208, v214
	v_sub_f32_e32 v209, v209, v214
	v_sub_f32_e32 v210, v210, v214
	v_sub_f32_e32 v211, v211, v214
	v_sub_f32_e32 v212, v212, v214
	v_sub_f32_e32 v213, v213, v214
	v_pk_mul_f32 v[206:207], v[214:215], v[206:207] op_sel:[1,0]
	v_pk_mul_f32 v[208:209], v[214:215], v[208:209] op_sel:[1,0]
	v_pk_mul_f32 v[210:211], v[214:215], v[210:211] op_sel:[1,0]
	v_pk_mul_f32 v[212:213], v[214:215], v[212:213] op_sel:[1,0]
	v_pk_fma_f32 v[206:207], v[98:99], v[206:207], v[102:103]
	v_pk_fma_f32 v[208:209], v[100:101], v[208:209], v[104:105]
	v_pk_fma_f32 v[210:211], v[90:91], v[210:211], v[94:95]
	v_pk_fma_f32 v[212:213], v[92:93], v[212:213], v[96:97]
	v_pk_fma_f32 v[206:207], v[206:207], s[66:67], v[14:15] op_sel_hi:[1,0,1]
	v_pk_fma_f32 v[208:209], v[208:209], s[66:67], v[16:17] op_sel_hi:[1,0,1]
	v_pk_fma_f32 v[210:211], v[210:211], s[66:67], v[10:11] op_sel_hi:[1,0,1]
	v_pk_fma_f32 v[212:213], v[212:213], s[66:67], v[12:13] op_sel_hi:[1,0,1]
	v_cvt_pk_bf16_f32 v244, v206, v207
	v_cvt_pk_bf16_f32 v245, v208, v209
	v_cvt_pk_bf16_f32 v246, v210, v211
	v_cvt_pk_bf16_f32 v247, v212, v213
	s_add_u32 s48, s72, 0xa0100
	s_addc_u32 s49, s73, 0
	global_store_dwordx4 v170, v[244:247], s[48:49]
	s_waitcnt vmcnt(7)
	v_lshlrev_b32_e32 v206, 16, v248
	v_and_b32_e32 v207, 0xffff0000, v248
	v_lshlrev_b32_e32 v208, 16, v249
	v_and_b32_e32 v209, 0xffff0000, v249
	v_lshlrev_b32_e32 v210, 16, v250
	v_and_b32_e32 v211, 0xffff0000, v250
	v_lshlrev_b32_e32 v212, 16, v251
	v_and_b32_e32 v213, 0xffff0000, v251
	v_sub_f32_e32 v206, v206, v216
	v_sub_f32_e32 v207, v207, v216
	v_sub_f32_e32 v208, v208, v216
	v_sub_f32_e32 v209, v209, v216
	v_sub_f32_e32 v210, v210, v216
	v_sub_f32_e32 v211, v211, v216
	v_sub_f32_e32 v212, v212, v216
	v_sub_f32_e32 v213, v213, v216
	v_pk_mul_f32 v[206:207], v[216:217], v[206:207] op_sel:[1,0]
	v_pk_mul_f32 v[208:209], v[216:217], v[208:209] op_sel:[1,0]
	v_pk_mul_f32 v[210:211], v[216:217], v[210:211] op_sel:[1,0]
	v_pk_mul_f32 v[212:213], v[216:217], v[212:213] op_sel:[1,0]
	v_pk_fma_f32 v[206:207], v[98:99], v[206:207], v[102:103]
	v_pk_fma_f32 v[208:209], v[100:101], v[208:209], v[104:105]
	v_pk_fma_f32 v[210:211], v[90:91], v[210:211], v[94:95]
	v_pk_fma_f32 v[212:213], v[92:93], v[212:213], v[96:97]
	v_pk_fma_f32 v[206:207], v[206:207], s[66:67], v[6:7] op_sel_hi:[1,0,1]
	v_pk_fma_f32 v[208:209], v[208:209], s[66:67], v[8:9] op_sel_hi:[1,0,1]
	v_pk_fma_f32 v[210:211], v[210:211], s[66:67], v[2:3] op_sel_hi:[1,0,1]
	v_pk_fma_f32 v[212:213], v[212:213], s[66:67], v[4:5] op_sel_hi:[1,0,1]
	v_cvt_pk_bf16_f32 v248, v206, v207
	v_cvt_pk_bf16_f32 v249, v208, v209
	v_cvt_pk_bf16_f32 v250, v210, v211
	v_cvt_pk_bf16_f32 v251, v212, v213
	s_add_u32 s48, s72, 0xb0100
	s_addc_u32 s49, s73, 0
	global_store_dwordx4 v170, v[248:251], s[48:49]
	s_and_b64 vcc, exec, s[8:9]
	s_mov_b32 s43, s6
	s_mov_b32 s46, s7
	s_mov_b64 s[68:69], s[12:13]
	s_mov_b64 s[64:65], s[10:11]
	s_cbranch_vccz .LBB0_1606
	s_waitcnt vmcnt(0)
	s_cmpk_gt_u32 s19, 0xff
	s_cbranch_scc1 .LBB0_1621
	s_barrier
